# up phase: next tile's first k-slab LDS-DMA issued under the epilogue (slabs moved to the k-odd staging halves, end-of-tile barrier dropped, tail stores batched, conv weights loaded at tile start)
# speedup vs baseline: 1.0356x; 1.0027x over previous
; DI int bid() { int b; asm volatile("s_mov_b32 %0, %1" : "=s"(b) : "s"((int)blockIdx.x)); return b; }
; DI void phase_up(const Params& p, int l, char* smem) {
;   const int rows = (l == 3) ? NLAT : NROWS;
;   const int MT = (rows + 253) / 254;
;   const int MTP = (MT + 7) & ~7;
;   const u16* W = (const u16*)(p.ws + OFF_WUP) + (size_t)l * 5632 * 1024;
;   const u16* H = (const u16*)(p.ws + OFF_H);
;   for (int tile = bid(); tile < MTP * 22; tile += gridDim.x) {
;     int mt, nt;
;     if (!tile_map(tile, 22, MT, mt, nt)) continue;
;     EpiUp e;
;     e.act = (u16*)(p.ws + OFF_ACT); e.cw = p.conv_w + (size_t)l * 3 * 5632; e.cb = p.conv_b + (size_t)l * 5632;
;     e.row0 = mt * 254 - 1; e.Mrows = rows; e.nt = nt; e.edge = (float*)(smem + 131072); e.ostage = (u16*)smem;
;     gemm_tile<4>(H, 1024, mt * 254 - 1, rows, W + (size_t)nt * 256 * 1024, 1024, 1024, smem, e, tile);
.LBB0_768:
	s_or_b64 exec, exec, s[2:3]
	s_or_b32 s0, s26, 0xfc
	s_lshr_b32 s0, s0, 1
	s_mul_i32 s0, s0, 0x8103
	s_lshr_b32 s8, s0, 22
	s_add_i32 s0, s8, 7
	s_and_b32 s10, s0, 0x1f8
	s_mul_i32 s10, s10, 22
	s_waitcnt lgkmcnt(0)
	s_barrier
	v_readlane_b32 s0, v234, 22
	s_mov_b32 s9, s0
	s_cmp_ge_i32 s9, s10
	s_cbranch_scc1 .LBB0_798
	s_mul_i32 s2, s40, 0xb00000
	v_readlane_b32 s3, v235, 56
	s_mul_hi_u32 s0, s40, 0xb00000
	s_add_u32 s11, s3, s2
	v_readlane_b32 s2, v235, 57
	s_addc_u32 s12, s2, s0
	s_mul_hi_u32 s0, s40, 0x10800
	s_mul_i32 s2, s40, 0x10800
	s_mul_hi_u32 s3, s40, 0x5800
	s_mul_i32 s14, s40, 0x5800
	v_readlane_b32 s40, v236, 0
	s_add_i32 s13, s26, -1
	v_readlane_b32 s42, v236, 2
	v_readlane_b32 s41, v236, 1
	v_readlane_b32 s43, v236, 3
	s_add_u32 s40, s42, s2
	v_readlane_b32 s44, v236, 4
	s_addc_u32 s41, s43, s0
	v_readlane_b32 s45, v236, 5
	s_add_u32 s42, s44, s14
	s_addc_u32 s43, s45, s3
	s_add_u32 s44, s40, 0x5800
	v_readlane_b32 s46, v236, 6
	s_addc_u32 s45, s41, 0
	v_readlane_b32 s47, v236, 7
	s_add_u32 s46, s40, 0xb000
	s_addc_u32 s47, s41, 0
	s_movk_i32 s52, 0xff
	s_movk_i32 s53, 0x2000
	s_mov_b64 s[38:39], -1
	s_branch .LBB0_772

; DI int crow(int i, int h) { return (i & 3) + 8 * (i >> 2) + 4 * h; }
; template <int MB, class Epi>
; DI void gemm_tile(const u16* __restrict__ A, int lda, int row0, int Mrows, const u16* __restrict__ Bt, int ldb, int K, char* smem, Epi& epi, int rot) {
;     ...
;   const int t = tid(), lane = t & 63, w = __builtin_amdgcn_readfirstlane(t >> 6), wm = w >> 2, wn = w & 3, r = lane & 31, h = lane >> 5;
;   constexpr int NAJ = MB;
;   const int lr = t >> 3;
;   const int lch = (t & 7) ^ ((lr >> 1) & 7);
;   unsigned aoff[NAJ];
; #pragma unroll
;   for (int j = 0; j < NAJ; ++j) {
;     int gr = row0 + lr + 64 * j;
;     gr = gr < 0 ? 0 : (gr > Mrows - 1 ? Mrows - 1 : gr);
;     aoff[j] = (unsigned)gr * (unsigned)lda + lch * 8;
;   }
;   const u16* bp = Bt + (size_t)lr * ldb + lch * 8;
;   f32x16 acc[2][MB];
; #pragma unroll
;   for (int nb = 0; nb < 2; ++nb)
; #pragma unroll
;     for (int mb = 0; mb < MB; ++mb)
; #pragma unroll
;       for (int i = 0; i < 16; ++i) acc[nb][mb][i] = 0.f;
;   const int KT = K >> 6;
;   int kcur = rot % KT;
;     ...
;   GEMM_STAGE(0)
;   asm volatile("s_waitcnt vmcnt(0)" ::: "memory");
;   __syncthreads();
;   const int sw = (r >> 1) & 7;
;   int foff[4];
; #pragma unroll
;   for (int ks = 0; ks < 4; ++ks) foff[ks] = r * 128 + (((2 * ks + h) ^ sw) << 4);
;   bf8 af[2][MB], bfr[2][2];
;   {
;     const char* as0 = As + wm * (32 * MB) * 128;
;     const char* bs0 = Bs + wn * 64 * 128;
; #pragma unroll
;     for (int mb = 0; mb < MB; ++mb) af[0][mb] = *(const bf8*)(as0 + mb * 32 * 128 + foff[0]);
; #pragma unroll
;     for (int nb = 0; nb < 2; ++nb) bfr[0][nb] = *(const bf8*)(bs0 + nb * 32 * 128 + foff[0]);
;   }
;   const int kbase = rot % KT;
;   if (KT > 1) {
;     const int k1_ = (kbase + 1 >= KT) ? kbase + 1 - KT : kbase + 1;
;     const int ko_ = k1_ * 64;
; #pragma unroll
;     for (int pc = 0; pc < 3; ++pc) GEMM_PIECE(1, pc)
;   DI void operator()(f32x16 (&acc)[2][4], int wm, int wn, int r, int h) {
;     ...
;             const int ff = nt * 128 + wn * 32 + crow(i0, h) + nb * DFF;
;             const f32x2n a0 = *(const f32x2n*)(cw + ff), a1 = *(const f32x2n*)(cw + 2 * DFF + ff), a2 = *(const f32x2n*)(cw + 4 * DFF + ff),
;                          a3 = *(const f32x2n*)(cb + ff);
;             w0[0] = a0.x; w0[1] = a0.y; w1[0] = a1.x; w1[1] = a1.y; w2[0] = a2.x; w2[1] = a2.y; bz[0] = a3.x; bz[1] = a3.y;
.Lup_nomap:
	s_ashr_i32 s0, s100, 3
	s_mul_hi_i32 s2, s0, 0x2e8ba2e9
	s_lshr_b32 s14, s2, 31
	s_ashr_i32 s2, s2, 2
	s_add_i32 s2, s2, s14
	s_and_b32 s3, s100, 7
	s_lshl_b32 s14, s2, 3
	s_or_b32 s3, s14, s3
	s_cmp_ge_i32 s3, s8
	s_cbranch_scc1 .LBB0_771
	s_mul_i32 s14, s3, 0xfe
	s_add_i32 s14, s14, -1
	v_mov_b32 v165, v163
	s_movk_i32 s15, 0xffbf
	v_ashrrev_i32_e32 v2, 3, v165
	v_add_u32_e32 v3, s14, v2
	v_min_u32_e32 v4, s13, v3
	v_add_u32_e32 v6, 64, v3
	v_lshrrev_b32_e32 v0, 4, v165
	v_lshlrev_b32_e32 v4, 10, v4
	v_cmp_lt_i32_e32 vcc, -1, v3
	v_min_u32_e32 v6, s13, v6
	v_add_u32_e32 v7, 0x80, v3
	v_xor_b32_e32 v0, v0, v165
	v_cndmask_b32_e32 v4, 0, v4, vcc
	v_lshlrev_b32_e32 v6, 10, v6
	v_cmp_lt_i32_e32 vcc, s15, v3
	v_min_u32_e32 v7, s13, v7
	s_movk_i32 s15, 0xff7f
	v_lshlrev_b32_e32 v0, 3, v0
	v_cndmask_b32_e32 v6, 0, v6, vcc
	v_lshlrev_b32_e32 v7, 10, v7
	v_cmp_lt_i32_e32 vcc, s15, v3
	v_and_b32_e32 v0, 56, v0
	s_mul_i32 s2, s2, 22
	v_cndmask_b32_e32 v7, 0, v7, vcc
	v_or_b32_e32 v8, v7, v0
	v_add_u32_e32 v7, 0xc0, v3
	s_sub_i32 s48, s0, s2
	v_min_u32_e32 v7, s13, v7
	s_movk_i32 s15, 0xff3f
	s_ashr_i32 s49, s48, 31
	v_lshlrev_b32_e32 v7, 10, v7
	v_cmp_lt_i32_e32 vcc, s15, v3
	s_lshl_b64 s[2:3], s[48:49], 19
	s_add_u32 s2, s11, s2
	v_cndmask_b32_e32 v3, 0, v7, vcc
	v_or_b32_e32 v7, v3, v0
	v_ashrrev_i32_e32 v3, 31, v2
	s_addc_u32 s3, s12, s3
	v_lshlrev_b64 v[2:3], 11, v[2:3]
	v_lshl_add_u64 v[2:3], s[2:3], 0, v[2:3]
	s_ashr_i32 s2, s9, 31
	s_lshr_b32 s2, s2, 28
	s_add_i32 s2, s9, s2
	s_and_b32 s2, s2, -16
	v_readfirstlane_b32 s0, v165
	s_sub_i32 s19, s9, s2
	s_lshl_b32 s28, s19, 6
	s_lshl_b32 s2, s0, 4
	v_or_b32_e32 v4, v4, v0
	v_or_b32_e32 v6, v6, v0
	v_lshlrev_b32_e32 v0, 1, v0
	s_ashr_i32 s29, s28, 31
	s_and_b32 s3, s2, 0xfffffc00
	s_bfe_u32 s16, s0, 0x20006
	s_ashr_i32 s15, s0, 8
	v_lshl_add_u64 v[154:155], v[2:3], 0, v[0:1]
	s_lshl_b64 s[36:37], s[28:29], 1
	s_add_i32 s22, s3, 0x10000
	v_lshl_add_u64 v[2:3], v[154:155], 0, s[36:37]
	s_add_u32 s36, s84, s36
	s_addc_u32 s37, s85, s37
	v_lshlrev_b32_e32 v0, 1, v4
	v_lshl_add_u64 v[10:11], s[36:37], 0, v[0:1]
	s_mov_b64 vcc, s[38:39]
	s_cbranch_vccz .Lupd_0
	s_mov_b32 m0, s3
	s_nop 0
	global_load_lds_dwordx4 v[10:11], off
.Lupd_0:
	v_lshlrev_b32_e32 v10, 1, v6
	v_mov_b32_e32 v11, v1
	v_lshl_add_u64 v[12:13], s[36:37], 0, v[10:11]
	s_add_i32 s2, s3, 0x2000
	s_cbranch_vccz .Lupd_1
	s_mov_b32 m0, s2
	s_nop 0
	global_load_lds_dwordx4 v[12:13], off
.Lupd_1:
	v_lshlrev_b32_e32 v12, 1, v8
	v_mov_b32_e32 v13, v1
	v_lshl_add_u64 v[14:15], s[36:37], 0, v[12:13]
	s_add_i32 s2, s3, 0x4000
	s_cbranch_vccz .Lupd_2
	s_mov_b32 m0, s2
	s_nop 0
	global_load_lds_dwordx4 v[14:15], off
.Lupd_2:
	v_lshlrev_b32_e32 v14, 1, v7
	v_mov_b32_e32 v15, v1
	v_lshl_add_u64 v[16:17], s[36:37], 0, v[14:15]
	s_add_i32 s23, s3, 0x6000
	s_cbranch_vccz .Lupd_3
	s_mov_b32 m0, s23
	s_nop 0
	global_load_lds_dwordx4 v[16:17], off
.Lupd_3:
	s_cbranch_vccz .Lupd_4
	s_mov_b32 m0, s22
	s_nop 0
	global_load_lds_dwordx4 v[2:3], off
.Lupd_4:
	s_add_i32 s2, s3, 0x12000
	v_lshl_add_u64 v[16:17], v[2:3], 0, s[4:5]
	s_cbranch_vccz .Lupd_5
	s_mov_b32 m0, s2
	s_nop 0
	global_load_lds_dwordx4 v[16:17], off
.Lupd_5:
	s_add_i32 s2, s3, 0x14000
	v_lshl_add_u64 v[16:17], v[2:3], 0, s[6:7]
	s_cbranch_vccz .Lupd_6
	s_mov_b32 m0, s2
	s_nop 0
	global_load_lds_dwordx4 v[16:17], off
.Lupd_6:
	s_add_i32 s2, s3, 0x16000
	v_lshl_add_u64 v[2:3], v[2:3], 0, s[34:35]
	s_cbranch_vccz .Lupd_7
	s_mov_b32 m0, s2
	s_nop 0
	global_load_lds_dwordx4 v[2:3], off
.Lupd_7:
	s_lshl_b32 s2, s16, 13
	s_lshl_b32 s17, s15, 14
	s_bitset1_b32 s2, 16
	s_add_i32 s25, s28, 64
	v_lshrrev_b32_e32 v5, 5, v165
	v_and_b32_e32 v167, 31, v165
	v_bfe_u32 v2, v165, 1, 3
	s_cmp_lt_i32 s19, 15
	v_lshlrev_b32_e32 v3, 7, v167
	v_bitop3_b32 v5, v5, v2, 1 bitop3:0x6c
	s_cselect_b32 s28, s25, 0
	v_lshl_or_b32 v5, v5, 4, v3
	s_ashr_i32 s29, s28, 31
	v_bfe_u32 v169, v165, 5, 1
	v_or_b32_e32 v164, s17, v5
	s_lshl_b64 s[28:29], s[28:29], 1
	s_waitcnt vmcnt(0)
	s_barrier
	v_bitop3_b32 v7, v169, v2, 2 bitop3:0x36
	ds_read_b128 v[146:149], v164
	ds_read_b128 v[142:145], v164 offset:4096
	ds_read_b128 v[134:137], v164 offset:8192
	s_waitcnt vmcnt(0)
	ds_read_b128 v[130:133], v164 offset:12288
	s_add_u32 s28, s84, s28
	v_lshl_or_b32 v171, v7, 4, v3
	v_bitop3_b32 v7, v169, v2, 4 bitop3:0x36
	v_bitop3_b32 v2, v169, v2, 6 bitop3:0x36
	v_or_b32_e32 v166, s2, v5
	s_addc_u32 s29, s85, s29
	v_lshl_or_b32 v170, v7, 4, v3
	v_lshl_or_b32 v168, v2, 4, v3
	ds_read_b128 v[150:153], v166
	ds_read_b128 v[138:141], v166 offset:4096
	s_lshl_b32 s100, s48, 9
	s_lshl_b32 s101, s16, 7
	s_add_i32 s100, s100, s101
	v_lshlrev_b32_e32 v248, 2, v167
	v_add_u32_e32 v248, s100, v248
	v_add_u32_e32 v249, 0x2c00, v248
	global_load_dword v241, v248, s[40:41]
	global_load_dword v240, v248, s[44:45]
	global_load_dword v243, v248, s[46:47]
	global_load_dword v242, v248, s[42:43]
	global_load_dword v245, v249, s[40:41]
	global_load_dword v244, v249, s[44:45]
	global_load_dword v247, v249, s[46:47]
	global_load_dword v246, v249, s[42:43]
	s_add_i32 s25, s3, 0x8000
	v_lshl_add_u64 v[2:3], s[28:29], 0, v[0:1]
	s_mov_b32 m0, s25
	s_nop 0
	global_load_lds_dwordx4 v[2:3], off
	v_lshl_add_u64 v[2:3], s[28:29], 0, v[10:11]
	s_add_i32 s25, s3, 0xa000
	s_mov_b32 m0, s25
	s_nop 0
	global_load_lds_dwordx4 v[2:3], off
	v_lshl_add_u64 v[2:3], s[28:29], 0, v[12:13]
	s_add_i32 s25, s3, 0xc000
	s_mov_b32 m0, s25
	s_nop 0
	global_load_lds_dwordx4 v[2:3], off
	v_mov_b32_e32 v2, 0
	s_mov_b32 s18, 0
	v_lshl_add_u64 v[156:157], s[84:85], 0, v[14:15]
	v_lshlrev_b32_e32 v0, 1, v4
	v_lshlrev_b32_e32 v158, 1, v6
	v_lshlrev_b32_e32 v160, 1, v8
	s_mov_b32 s25, s19
; DI f32x16 mfma32(bf8 a, bf8 b, f32x16 c) { return __builtin_amdgcn_mfma_f32_32x32x16_bf16(a, b, c, 0, 0, 0); }
; template <int MB, class Epi>
; DI void gemm_tile(const u16* __restrict__ A, int lda, int row0, int Mrows, const u16* __restrict__ Bt, int ldb, int K, char* smem, Epi& epi, int rot) {
;     ...
;   f32x16 acc[2][MB];
; #pragma unroll
;   for (int nb = 0; nb < 2; ++nb)
; #pragma unroll
;     for (int mb = 0; mb < MB; ++mb)
; #pragma unroll
;       for (int i = 0; i < 16; ++i) acc[nb][mb][i] = 0.f;
;     ...
;   for (int kt = 0; kt < KT; ++kt) {
;     const bool more = (kt + 1 < KT);
;     const bool more2 = (kt + 2 < KT);
;     const int nstg = (kt + 1) & 1;
;     const char* as = As + (kt & 1) * 32768 + wm * (32 * MB) * 128;
;     const char* bs = Bs + (kt & 1) * 32768 + wn * 64 * 128;
;     int k1_ = kbase + kt + 1; if (k1_ >= KT) k1_ -= KT;
;     int k2_ = kbase + kt + 2; if (k2_ >= KT) k2_ -= KT; if (k2_ >= KT) k2_ -= KT;
; #pragma unroll
;     for (int ks = 0; ks < 3; ++ks) {
; #pragma unroll
;       for (int idx = 0; idx < 2 * MB; ++idx) {
;         const int nb = idx / MB, mb = idx % MB;
;         acc[nb][mb] = mfma32(bfr[ks & 1][nb], af[ks & 1][mb], acc[nb][mb]);
;         if (idx < MB) af[(ks + 1) & 1][idx] = *(const bf8*)(as + idx * 32 * 128 + foff[ks + 1]);
;         else if (idx < MB + 2) bfr[(ks + 1) & 1][idx - MB] = *(const bf8*)(bs + (idx - MB) * 32 * 128 + foff[ks + 1]);
;         if (more && ks < 2 && idx < 3) {
;           const int ko_ = k1_ * 64;
;           GEMM_PIECE(nstg, 3 + ks * 3 + idx)
;         }
;         __builtin_amdgcn_sched_barrier(0);
;       }
;     }
;     if (more) {
;       asm volatile("s_waitcnt vmcnt(0)" ::: "memory");
;       __syncthreads();
;       if (more2) {
;         const int ko_ = k2_ * 64;
; #pragma unroll
;         for (int pc = 0; pc < 3; ++pc) GEMM_PIECE(kt & 1, pc)
;       }
;       __builtin_amdgcn_sched_barrier(0);
;       const char* asn = As + nstg * 32768 + wm * (32 * MB) * 128;
;       const char* bsn = Bs + nstg * 32768 + wn * 64 * 128;
; #pragma unroll
;       for (int mb = 0; mb < MB; ++mb) af[0][mb] = *(const bf8*)(asn + mb * 32 * 128 + foff[0]);
; #pragma unroll
;       for (int nb = 0; nb < 2; ++nb) bfr[0][nb] = *(const bf8*)(bsn + nb * 32 * 128 + foff[0]);
;     }
	v_mov_b32_e32 v3, v2
	v_mov_b32_e32 v4, v2
	v_mov_b32_e32 v5, v2
	v_mov_b32_e32 v6, v2
	v_mov_b32_e32 v7, v2
	v_mov_b32_e32 v8, v2
	v_mov_b32_e32 v9, v2
	v_mov_b32_e32 v10, v2
	v_mov_b32_e32 v11, v2
	v_mov_b32_e32 v12, v2
	v_mov_b32_e32 v13, v2
	v_mov_b32_e32 v14, v2
	v_mov_b32_e32 v15, v2
	v_mov_b32_e32 v16, v2
	v_mov_b32_e32 v17, v2
	v_mov_b32_e32 v18, v2
	v_mov_b32_e32 v19, v2
	v_mov_b32_e32 v20, v2
	v_mov_b32_e32 v21, v2
	v_mov_b32_e32 v22, v2
	v_mov_b32_e32 v23, v2
	v_mov_b32_e32 v24, v2
	v_mov_b32_e32 v25, v2
	v_mov_b32_e32 v26, v2
	v_mov_b32_e32 v27, v2
	v_mov_b32_e32 v28, v2
	v_mov_b32_e32 v29, v2
	v_mov_b32_e32 v30, v2
	v_mov_b32_e32 v31, v2
	v_mov_b32_e32 v32, v2
	v_mov_b32_e32 v33, v2
	v_mov_b32_e32 v50, v2
	v_mov_b32_e32 v51, v2
	v_mov_b32_e32 v52, v2
	v_mov_b32_e32 v53, v2
	v_mov_b32_e32 v54, v2
	v_mov_b32_e32 v55, v2
	v_mov_b32_e32 v56, v2
	v_mov_b32_e32 v57, v2
	v_mov_b32_e32 v58, v2
	v_mov_b32_e32 v59, v2
	v_mov_b32_e32 v60, v2
	v_mov_b32_e32 v61, v2
	v_mov_b32_e32 v62, v2
	v_mov_b32_e32 v63, v2
	v_mov_b32_e32 v64, v2
	v_mov_b32_e32 v65, v2
	v_mov_b32_e32 v98, v2
	v_mov_b32_e32 v99, v2
	v_mov_b32_e32 v100, v2
	v_mov_b32_e32 v101, v2
	v_mov_b32_e32 v102, v2
	v_mov_b32_e32 v103, v2
	v_mov_b32_e32 v104, v2
	v_mov_b32_e32 v105, v2
	v_mov_b32_e32 v106, v2
	v_mov_b32_e32 v107, v2
	v_mov_b32_e32 v108, v2
	v_mov_b32_e32 v109, v2
	v_mov_b32_e32 v110, v2
	v_mov_b32_e32 v111, v2
	v_mov_b32_e32 v112, v2
	v_mov_b32_e32 v113, v2
	v_mov_b32_e32 v114, v2
	v_mov_b32_e32 v115, v2
	v_mov_b32_e32 v116, v2
	v_mov_b32_e32 v117, v2
	v_mov_b32_e32 v118, v2
	v_mov_b32_e32 v119, v2
	v_mov_b32_e32 v120, v2
	v_mov_b32_e32 v121, v2
	v_mov_b32_e32 v122, v2
	v_mov_b32_e32 v123, v2
	v_mov_b32_e32 v124, v2
	v_mov_b32_e32 v125, v2
	v_mov_b32_e32 v126, v2
	v_mov_b32_e32 v127, v2
	v_mov_b32_e32 v128, v2
	v_mov_b32_e32 v129, v2
	v_mov_b32_e32 v82, v2
	v_mov_b32_e32 v83, v2
	v_mov_b32_e32 v84, v2
	v_mov_b32_e32 v85, v2
	v_mov_b32_e32 v86, v2
	v_mov_b32_e32 v87, v2
	v_mov_b32_e32 v88, v2
	v_mov_b32_e32 v89, v2
	v_mov_b32_e32 v90, v2
	v_mov_b32_e32 v91, v2
	v_mov_b32_e32 v92, v2
	v_mov_b32_e32 v93, v2
	v_mov_b32_e32 v94, v2
	v_mov_b32_e32 v95, v2
	v_mov_b32_e32 v96, v2
	v_mov_b32_e32 v97, v2
	v_mov_b32_e32 v66, v2
	v_mov_b32_e32 v67, v2
	v_mov_b32_e32 v68, v2
	v_mov_b32_e32 v69, v2
	v_mov_b32_e32 v70, v2
	v_mov_b32_e32 v71, v2
	v_mov_b32_e32 v72, v2
	v_mov_b32_e32 v73, v2
	v_mov_b32_e32 v74, v2
	v_mov_b32_e32 v75, v2
	v_mov_b32_e32 v76, v2
	v_mov_b32_e32 v77, v2
	v_mov_b32_e32 v78, v2
	v_mov_b32_e32 v79, v2
	v_mov_b32_e32 v80, v2
	v_mov_b32_e32 v81, v2
	v_mov_b32_e32 v34, v2
	v_mov_b32_e32 v35, v2
	v_mov_b32_e32 v36, v2
	v_mov_b32_e32 v37, v2
	v_mov_b32_e32 v38, v2
	v_mov_b32_e32 v39, v2
	v_mov_b32_e32 v40, v2
	v_mov_b32_e32 v41, v2
	v_mov_b32_e32 v42, v2
	v_mov_b32_e32 v43, v2
	v_mov_b32_e32 v44, v2
	v_mov_b32_e32 v45, v2
	v_mov_b32_e32 v46, v2
	v_mov_b32_e32 v47, v2
	v_mov_b32_e32 v48, v2
	v_mov_b32_e32 v49, v2
.LBB0_774:
	s_and_b32 s28, s18, 0x8000
	s_add_i32 s31, s17, s28
	s_add_i32 s29, s2, s28
	s_cmp_gt_i32 s25, 14
	s_cselect_b32 s27, -15, 1
	s_waitcnt lgkmcnt(1)
	v_mfma_f32_32x32x16_bf16 v[98:113], v[146:149], v[150:153], v[98:113]
	s_add_i32 s27, s27, s25
	s_lshl_b32 s36, s27, 6
	s_ashr_i32 s37, s36, 31
	s_add_i32 s18, s18, 0x8000
	v_add_u32_e32 v159, s31, v171
	s_lshl_b64 s[36:37], s[36:37], 1
	s_and_b32 s27, s18, 0x8000
	ds_read_b128 v[172:175], v159
	s_add_i32 s39, s27, s23
	v_lshl_add_u64 v[176:177], v[156:157], 0, s[36:37]
	s_mov_b32 m0, s39
	s_nop 0
	global_load_lds_dwordx4 v[176:177], off
	v_lshl_add_u64 v[184:185], v[154:155], 0, s[36:37]
	s_add_i32 s38, s27, s22
	v_mfma_f32_32x32x16_bf16 v[50:65], v[142:145], v[150:153], v[50:65]
	ds_read_b128 v[176:179], v159 offset:4096
	s_mov_b32 m0, s38
	s_nop 0
	global_load_lds_dwordx4 v[184:185], off
	v_mfma_f32_32x32x16_bf16 v[18:33], v[134:137], v[150:153], v[18:33]
	ds_read_b128 v[180:183], v159 offset:8192
	s_add_i32 s36, s38, 0x2000
	v_lshl_add_u64 v[186:187], v[184:185], 0, s[4:5]
	s_mov_b32 m0, s36
	s_nop 0
	global_load_lds_dwordx4 v[186:187], off
	v_mfma_f32_32x32x16_bf16 v[2:17], v[130:133], v[150:153], v[2:17]
	ds_read_b128 v[150:153], v159 offset:12288
	s_waitcnt lgkmcnt(4)
	v_mfma_f32_32x32x16_bf16 v[114:129], v[146:149], v[138:141], v[114:129]
	v_add_u32_e32 v159, s29, v171
	ds_read_b128 v[146:149], v159
	v_mfma_f32_32x32x16_bf16 v[82:97], v[142:145], v[138:141], v[82:97]
	ds_read_b128 v[142:145], v159 offset:4096
	v_mfma_f32_32x32x16_bf16 v[66:81], v[134:137], v[138:141], v[66:81]
	v_mfma_f32_32x32x16_bf16 v[34:49], v[130:133], v[138:141], v[34:49]
	s_waitcnt lgkmcnt(1)
	v_mfma_f32_32x32x16_bf16 v[98:113], v[172:175], v[146:149], v[98:113]
	v_add_u32_e32 v159, s31, v170
	ds_read_b128 v[130:133], v159
	s_add_i32 s36, s38, 0x4000
	v_lshl_add_u64 v[134:135], v[184:185], 0, s[6:7]
	s_mov_b32 m0, s36
	s_nop 0
	global_load_lds_dwordx4 v[134:135], off
	v_mfma_f32_32x32x16_bf16 v[50:65], v[176:179], v[146:149], v[50:65]
	ds_read_b128 v[134:137], v159 offset:4096
	s_addk_i32 s38, 0x6000
	v_lshl_add_u64 v[138:139], v[184:185], 0, s[34:35]
	s_mov_b32 m0, s38
	s_nop 0
	global_load_lds_dwordx4 v[138:139], off
	v_mfma_f32_32x32x16_bf16 v[18:33], v[180:183], v[146:149], v[18:33]
	ds_read_b128 v[138:141], v159 offset:8192
	v_mfma_f32_32x32x16_bf16 v[2:17], v[150:153], v[146:149], v[2:17]
	ds_read_b128 v[146:149], v159 offset:12288
	s_waitcnt lgkmcnt(4)
	v_mfma_f32_32x32x16_bf16 v[114:129], v[172:175], v[142:145], v[114:129]
	v_add_u32_e32 v159, s29, v170
	ds_read_b128 v[172:175], v159
	v_mfma_f32_32x32x16_bf16 v[82:97], v[176:179], v[142:145], v[82:97]
	ds_read_b128 v[176:179], v159 offset:4096
	v_mfma_f32_32x32x16_bf16 v[66:81], v[180:183], v[142:145], v[66:81]
	v_mfma_f32_32x32x16_bf16 v[34:49], v[150:153], v[142:145], v[34:49]
	s_waitcnt lgkmcnt(1)
	v_mfma_f32_32x32x16_bf16 v[98:113], v[130:133], v[172:175], v[98:113]
	v_add_u32_e32 v142, s31, v168
	ds_read_b128 v[150:153], v142
	v_mfma_f32_32x32x16_bf16 v[50:65], v[134:137], v[172:175], v[50:65]
	ds_read_b128 v[180:183], v142 offset:4096
	v_mfma_f32_32x32x16_bf16 v[18:33], v[138:141], v[172:175], v[18:33]
	ds_read_b128 v[184:187], v142 offset:8192
	v_mfma_f32_32x32x16_bf16 v[2:17], v[146:149], v[172:175], v[2:17]
	ds_read_b128 v[172:175], v142 offset:12288
	s_waitcnt lgkmcnt(4)
	v_mfma_f32_32x32x16_bf16 v[114:129], v[130:133], v[176:179], v[114:129]
	v_add_u32_e32 v142, s29, v168
	ds_read_b128 v[130:133], v142
	v_mfma_f32_32x32x16_bf16 v[82:97], v[134:137], v[176:179], v[82:97]
	ds_read_b128 v[188:191], v142 offset:4096
	v_mfma_f32_32x32x16_bf16 v[66:81], v[138:141], v[176:179], v[66:81]
	v_mfma_f32_32x32x16_bf16 v[34:49], v[146:149], v[176:179], v[34:49]
	s_cmp_gt_i32 s25, 13
	s_cselect_b32 s29, -14, 2
	s_add_i32 s29, s29, s25
	s_lshl_b32 s31, s29, 6
	s_add_i32 s36, s31, 0xfffffc00
	s_cmp_gt_i32 s29, 15
	s_cselect_b32 s36, s36, s31
	s_ashr_i32 s37, s36, 31
	s_lshl_b64 s[36:37], s[36:37], 1
	s_add_u32 s36, s84, s36
	s_addc_u32 s37, s85, s37
	s_waitcnt vmcnt(0)
	s_waitcnt lgkmcnt(0)
	s_barrier
; template <int MB, class Epi>
; DI void gemm_tile(const u16* __restrict__ A, int lda, int row0, int Mrows, const u16* __restrict__ Bt, int ldb, int K, char* smem, Epi& epi, int rot) {
;     ...
;   for (int kt = 0; kt < KT; ++kt) {
;     const bool more = (kt + 1 < KT);
;     const bool more2 = (kt + 2 < KT);
;     const int nstg = (kt + 1) & 1;
;     const char* as = As + (kt & 1) * 32768 + wm * (32 * MB) * 128;
;     const char* bs = Bs + (kt & 1) * 32768 + wn * 64 * 128;
;     int k1_ = kbase + kt + 1; if (k1_ >= KT) k1_ -= KT;
;     int k2_ = kbase + kt + 2; if (k2_ >= KT) k2_ -= KT; if (k2_ >= KT) k2_ -= KT;
; #pragma unroll
;     for (int ks = 0; ks < 3; ++ks) {
; #pragma unroll
;       for (int idx = 0; idx < 2 * MB; ++idx) {
;         const int nb = idx / MB, mb = idx % MB;
;         acc[nb][mb] = mfma32(bfr[ks & 1][nb], af[ks & 1][mb], acc[nb][mb]);
;         if (idx < MB) af[(ks + 1) & 1][idx] = *(const bf8*)(as + idx * 32 * 128 + foff[ks + 1]);
;         else if (idx < MB + 2) bfr[(ks + 1) & 1][idx - MB] = *(const bf8*)(bs + (idx - MB) * 32 * 128 + foff[ks + 1]);
;         if (more && ks < 2 && idx < 3) {
;           const int ko_ = k1_ * 64;
;           GEMM_PIECE(nstg, 3 + ks * 3 + idx)
;         }
;         __builtin_amdgcn_sched_barrier(0);
;       }
;     }
;     if (more) {
;       asm volatile("s_waitcnt vmcnt(0)" ::: "memory");
;       __syncthreads();
;       if (more2) {
;         const int ko_ = k2_ * 64;
; #pragma unroll
;         for (int pc = 0; pc < 3; ++pc) GEMM_PIECE(kt & 1, pc)
;       }
;       __builtin_amdgcn_sched_barrier(0);
;       const char* asn = As + nstg * 32768 + wm * (32 * MB) * 128;
;       const char* bsn = Bs + nstg * 32768 + wn * 64 * 128;
; #pragma unroll
;       for (int mb = 0; mb < MB; ++mb) af[0][mb] = *(const bf8*)(asn + mb * 32 * 128 + foff[0]);
; #pragma unroll
;       for (int nb = 0; nb < 2; ++nb) bfr[0][nb] = *(const bf8*)(bsn + nb * 32 * 128 + foff[0]);
;     }
; #pragma unroll
;     for (int nb = 0; nb < 2; ++nb)
; #pragma unroll
;       for (int mb = 0; mb < MB; ++mb) acc[nb][mb] = mfma32(bfr[1][nb], af[1][mb], acc[nb][mb]);
; #pragma unroll
;     for (int gk = 0; gk < 2 * MB; ++gk) {
;       __builtin_amdgcn_sched_group_barrier(0x008, 1, 0);
;       __builtin_amdgcn_sched_group_barrier(0x100, 1, 0);
;     }
;     __builtin_amdgcn_sched_barrier(0);
;   }
	s_add_i32 s28, s28, s3
	v_lshl_add_u64 v[134:135], s[36:37], 0, v[0:1]
	s_mov_b32 m0, s28
	s_nop 0
	global_load_lds_dwordx4 v[134:135], off
	v_mov_b32_e32 v159, v1
	v_lshl_add_u64 v[134:135], s[36:37], 0, v[158:159]
	s_add_i32 s29, s28, 0x2000
	s_mov_b32 m0, s29
	s_nop 0
	global_load_lds_dwordx4 v[134:135], off
	v_mov_b32_e32 v161, v1
	v_lshl_add_u64 v[134:135], s[36:37], 0, v[160:161]
	s_addk_i32 s28, 0x4000
	s_mov_b32 m0, s28
	s_nop 0
	global_load_lds_dwordx4 v[134:135], off
	v_add_u32_e32 v138, s27, v164
	v_mfma_f32_32x32x16_bf16 v[98:113], v[150:153], v[130:133], v[98:113]
	ds_read_b128 v[146:149], v138
	v_mfma_f32_32x32x16_bf16 v[50:65], v[180:183], v[130:133], v[50:65]
	ds_read_b128 v[142:145], v138 offset:4096
	v_mfma_f32_32x32x16_bf16 v[18:33], v[184:187], v[130:133], v[18:33]
	ds_read_b128 v[134:137], v138 offset:8192
	v_mfma_f32_32x32x16_bf16 v[2:17], v[172:175], v[130:133], v[2:17]
	ds_read_b128 v[130:133], v138 offset:12288
	v_add_u32_e32 v138, s27, v166
	v_mfma_f32_32x32x16_bf16 v[114:129], v[150:153], v[188:191], v[114:129]
	ds_read_b128 v[150:153], v138
	v_mfma_f32_32x32x16_bf16 v[82:97], v[180:183], v[188:191], v[82:97]
	ds_read_b128 v[138:141], v138 offset:4096
	v_mfma_f32_32x32x16_bf16 v[66:81], v[184:187], v[188:191], v[66:81]
	v_mfma_f32_32x32x16_bf16 v[34:49], v[172:175], v[188:191], v[34:49]
	s_add_i32 s25, s25, 1
	s_cmp_eq_u32 s18, 0x70000
	s_cbranch_scc0 .LBB0_774
	s_cmp_lt_i32 s19, 1
	s_cselect_b32 s18, 1, -15
	s_add_i32 s19, s19, s18
	s_waitcnt lgkmcnt(1)
	v_mfma_f32_32x32x16_bf16 v[98:113], v[146:149], v[150:153], v[98:113]
	s_lshl_b32 s18, s19, 6
	s_addk_i32 s18, 0x380
	s_ashr_i32 s19, s18, 31
	v_add_u32_e32 v0, s17, v171
	s_lshl_b64 s[18:19], s[18:19], 1
	ds_read_b128 v[158:161], v0
	v_lshl_add_u64 v[176:177], v[154:155], 0, s[18:19]
	s_add_i32 s23, s3, 0xe000
	v_lshl_add_u64 v[154:155], v[156:157], 0, s[18:19]
	s_mov_b32 m0, s23
	s_nop 0
	global_load_lds_dwordx4 v[154:155], off
	s_add_i32 s22, s3, 0x18000
	v_mfma_f32_32x32x16_bf16 v[50:65], v[142:145], v[150:153], v[50:65]
	ds_read_b128 v[154:157], v0 offset:4096
	s_mov_b32 m0, s22
	s_nop 0
	global_load_lds_dwordx4 v[176:177], off
	v_mfma_f32_32x32x16_bf16 v[18:33], v[134:137], v[150:153], v[18:33]
	ds_read_b128 v[172:175], v0 offset:8192
	s_add_i32 s18, s3, 0x1a000
	v_lshl_add_u64 v[178:179], v[176:177], 0, s[4:5]
	s_mov_b32 m0, s18
	s_nop 0
	global_load_lds_dwordx4 v[178:179], off
	v_mfma_f32_32x32x16_bf16 v[2:17], v[130:133], v[150:153], v[2:17]
	ds_read_b128 v[150:153], v0 offset:12288
	s_waitcnt lgkmcnt(4)
	v_mfma_f32_32x32x16_bf16 v[114:129], v[146:149], v[138:141], v[114:129]
	v_add_u32_e32 v178, s2, v171
	ds_read_b128 v[146:149], v178
	v_mfma_f32_32x32x16_bf16 v[82:97], v[142:145], v[138:141], v[82:97]
	ds_read_b128 v[142:145], v178 offset:4096
	v_mfma_f32_32x32x16_bf16 v[66:81], v[134:137], v[138:141], v[66:81]
	v_mfma_f32_32x32x16_bf16 v[34:49], v[130:133], v[138:141], v[34:49]
	s_waitcnt lgkmcnt(1)
	v_mfma_f32_32x32x16_bf16 v[98:113], v[158:161], v[146:149], v[98:113]
	v_add_u32_e32 v179, s17, v170
	ds_read_b128 v[130:133], v179
	s_add_i32 s18, s3, 0x1c000
	v_lshl_add_u64 v[134:135], v[176:177], 0, s[6:7]
	s_mov_b32 m0, s18
	s_nop 0
	global_load_lds_dwordx4 v[134:135], off
	v_mfma_f32_32x32x16_bf16 v[50:65], v[154:157], v[146:149], v[50:65]
	ds_read_b128 v[134:137], v179 offset:4096
	s_add_i32 s3, s3, 0x1e000
	v_lshl_add_u64 v[138:139], v[176:177], 0, s[34:35]
	s_mov_b32 m0, s3
	s_nop 0
	global_load_lds_dwordx4 v[138:139], off
	v_mfma_f32_32x32x16_bf16 v[18:33], v[172:175], v[146:149], v[18:33]
	ds_read_b128 v[138:141], v179 offset:8192
	v_mfma_f32_32x32x16_bf16 v[2:17], v[150:153], v[146:149], v[2:17]
	ds_read_b128 v[146:149], v179 offset:12288
	s_waitcnt lgkmcnt(4)
	v_mfma_f32_32x32x16_bf16 v[114:129], v[158:161], v[142:145], v[114:129]
	v_add_u32_e32 v176, s2, v170
	ds_read_b128 v[158:161], v176
	v_mfma_f32_32x32x16_bf16 v[82:97], v[154:157], v[142:145], v[82:97]
	ds_read_b128 v[154:157], v176 offset:4096
	v_mfma_f32_32x32x16_bf16 v[66:81], v[172:175], v[142:145], v[66:81]
	v_mfma_f32_32x32x16_bf16 v[34:49], v[150:153], v[142:145], v[34:49]
	s_waitcnt lgkmcnt(1)
	v_mfma_f32_32x32x16_bf16 v[98:113], v[130:133], v[158:161], v[98:113]
	v_add_u32_e32 v174, s17, v168
	ds_read_b128 v[142:145], v174
	v_mfma_f32_32x32x16_bf16 v[50:65], v[134:137], v[158:161], v[50:65]
	ds_read_b128 v[150:153], v174 offset:4096
	v_mfma_f32_32x32x16_bf16 v[18:33], v[138:141], v[158:161], v[18:33]
	ds_read_b128 v[170:173], v174 offset:8192
	v_mfma_f32_32x32x16_bf16 v[2:17], v[146:149], v[158:161], v[2:17]
	ds_read_b128 v[158:161], v174 offset:12288
	s_waitcnt lgkmcnt(4)
	v_mfma_f32_32x32x16_bf16 v[114:129], v[130:133], v[154:157], v[114:129]
	v_add_u32_e32 v168, s2, v168
	ds_read_b128 v[130:133], v168
	v_mfma_f32_32x32x16_bf16 v[82:97], v[134:137], v[154:157], v[82:97]
	ds_read_b128 v[134:137], v168 offset:4096
	v_mfma_f32_32x32x16_bf16 v[66:81], v[138:141], v[154:157], v[66:81]
	v_mfma_f32_32x32x16_bf16 v[34:49], v[146:149], v[154:157], v[34:49]
	s_waitcnt vmcnt(0)
	s_waitcnt lgkmcnt(0)
	s_barrier
; DI int crow(int i, int h) { return (i & 3) + 8 * (i >> 2) + 4 * h; }
; DI f32x16 mfma32(bf8 a, bf8 b, f32x16 c) { return __builtin_amdgcn_mfma_f32_32x32x16_bf16(a, b, c, 0, 0, 0); }
; template <int MB, class Epi>
; DI void gemm_tile(const u16* __restrict__ A, int lda, int row0, int Mrows, const u16* __restrict__ Bt, int ldb, int K, char* smem, Epi& epi, int rot) {
;     ...
; #pragma unroll
;     for (int nb = 0; nb < 2; ++nb)
; #pragma unroll
;       for (int mb = 0; mb < MB; ++mb) acc[nb][mb] = mfma32(bfr[1][nb], af[1][mb], acc[nb][mb]);
; #pragma unroll
;     for (int gk = 0; gk < 2 * MB; ++gk) {
;       __builtin_amdgcn_sched_group_barrier(0x008, 1, 0);
;       __builtin_amdgcn_sched_group_barrier(0x100, 1, 0);
;     }
;     __builtin_amdgcn_sched_barrier(0);
;   }
;   DI void operator()(f32x16 (&acc)[2][4], int wm, int wn, int r, int h) {
;     float* eb = edge + ((wm * 4 + wn) * 2) * 64;
;     if (r == 0) {
; #pragma unroll
;       for (int nb = 0; nb < 2; ++nb)
; #pragma unroll
;         for (int i = 0; i < 16; ++i) eb[nb * 32 + crow(i, h)] = acc[nb][0][i];
;     }
;     if (r == 31) {
; #pragma unroll
;       for (int nb = 0; nb < 2; ++nb)
; #pragma unroll
;         for (int i = 0; i < 16; ++i) eb[64 + nb * 32 + crow(i, h)] = acc[nb][3][i];
;     }
;     __syncthreads();
;     const float* ob = edge + (((wm ^ 1) * 4 + wn) * 2) * 64 + (wm == 0 ? 0 : 64);
;     const int sp = (h << 5) | ((r - 1) & 31), sn = (h << 5) | ((r + 1) & 31);
;     const int Rb = row0 + wm * 128 + r;
;     u16* ost = ostage + (wm * 4 + wn) * (128 * 40);
;     float pm[4], nm[4];
; #pragma unroll
;     for (int mb = 0; mb < 4; ++mb) {
;       const int R = Rb + mb * 32;
;       const bool lat = R < NLAT;
;       const int tt = lat ? (R & 2047) : ((R - NLAT) & 255);
;       pm[mb] = (tt == 0) ? 0.f : 1.f;
;       nm[mb] = (tt == (lat ? 2047 : 255)) ? 0.f : 1.f;
;     }
	v_mfma_f32_32x32x16_bf16 v[98:113], v[142:145], v[130:133], v[98:113]
	ds_read_b128 v[138:141], v164 offset:32768
	v_mfma_f32_32x32x16_bf16 v[50:65], v[150:153], v[130:133], v[50:65]
	ds_read_b128 v[146:149], v164 offset:36864
	v_mfma_f32_32x32x16_bf16 v[18:33], v[170:173], v[130:133], v[18:33]
	ds_read_b128 v[154:157], v164 offset:40960
	v_mfma_f32_32x32x16_bf16 v[2:17], v[158:161], v[130:133], v[2:17]
	ds_read_b128 v[130:133], v164 offset:45056
	v_mfma_f32_32x32x16_bf16 v[114:129], v[142:145], v[134:137], v[114:129]
	ds_read_b128 v[142:145], v166 offset:32768
	v_mfma_f32_32x32x16_bf16 v[82:97], v[150:153], v[134:137], v[82:97]
	ds_read_b128 v[150:153], v166 offset:36864
	v_mfma_f32_32x32x16_bf16 v[66:81], v[170:173], v[134:137], v[66:81]
	v_mfma_f32_32x32x16_bf16 v[34:49], v[158:161], v[134:137], v[34:49]
	s_waitcnt lgkmcnt(1)
	v_mfma_f32_32x32x16_bf16 v[98:113], v[138:141], v[142:145], v[98:113]
	ds_read_b128 v[134:137], v0 offset:32768
	v_mfma_f32_32x32x16_bf16 v[50:65], v[146:149], v[142:145], v[50:65]
	ds_read_b128 v[158:161], v0 offset:36864
	v_mfma_f32_32x32x16_bf16 v[18:33], v[154:157], v[142:145], v[18:33]
	ds_read_b128 v[170:173], v0 offset:40960
	v_mfma_f32_32x32x16_bf16 v[2:17], v[130:133], v[142:145], v[2:17]
	ds_read_b128 v[142:145], v0 offset:45056
	s_waitcnt lgkmcnt(4)
	v_mfma_f32_32x32x16_bf16 v[114:129], v[138:141], v[150:153], v[114:129]
	ds_read_b128 v[138:141], v178 offset:32768
	v_mfma_f32_32x32x16_bf16 v[82:97], v[146:149], v[150:153], v[82:97]
	ds_read_b128 v[146:149], v178 offset:36864
	v_mfma_f32_32x32x16_bf16 v[66:81], v[154:157], v[150:153], v[66:81]
	v_mfma_f32_32x32x16_bf16 v[34:49], v[130:133], v[150:153], v[34:49]
	s_waitcnt lgkmcnt(1)
	v_mfma_f32_32x32x16_bf16 v[98:113], v[134:137], v[138:141], v[98:113]
	ds_read_b128 v[130:133], v179 offset:32768
	v_mfma_f32_32x32x16_bf16 v[50:65], v[158:161], v[138:141], v[50:65]
	ds_read_b128 v[150:153], v179 offset:36864
	v_mfma_f32_32x32x16_bf16 v[18:33], v[170:173], v[138:141], v[18:33]
	ds_read_b128 v[154:157], v179 offset:40960
	v_mfma_f32_32x32x16_bf16 v[2:17], v[142:145], v[138:141], v[2:17]
	ds_read_b128 v[138:141], v179 offset:45056
	s_waitcnt lgkmcnt(4)
	v_mfma_f32_32x32x16_bf16 v[114:129], v[134:137], v[146:149], v[114:129]
	ds_read_b128 v[134:137], v176 offset:32768
	v_mfma_f32_32x32x16_bf16 v[82:97], v[158:161], v[146:149], v[82:97]
	ds_read_b128 v[158:161], v176 offset:36864
	v_mfma_f32_32x32x16_bf16 v[66:81], v[170:173], v[146:149], v[66:81]
	v_mfma_f32_32x32x16_bf16 v[34:49], v[142:145], v[146:149], v[34:49]
	s_waitcnt lgkmcnt(1)
	v_mfma_f32_32x32x16_bf16 v[98:113], v[130:133], v[134:137], v[98:113]
	ds_read_b128 v[142:145], v174 offset:32768
	v_mfma_f32_32x32x16_bf16 v[50:65], v[150:153], v[134:137], v[50:65]
	ds_read_b128 v[146:149], v174 offset:36864
	v_mfma_f32_32x32x16_bf16 v[18:33], v[154:157], v[134:137], v[18:33]
	ds_read_b128 v[170:173], v174 offset:40960
	v_mfma_f32_32x32x16_bf16 v[2:17], v[138:141], v[134:137], v[2:17]
	ds_read_b128 v[134:137], v174 offset:45056
	s_waitcnt lgkmcnt(4)
	v_mfma_f32_32x32x16_bf16 v[114:129], v[130:133], v[158:161], v[114:129]
	ds_read_b128 v[130:133], v168 offset:32768
	v_mfma_f32_32x32x16_bf16 v[82:97], v[150:153], v[158:161], v[82:97]
	ds_read_b128 v[150:153], v168 offset:36864
	v_mfma_f32_32x32x16_bf16 v[66:81], v[154:157], v[158:161], v[66:81]
	v_mfma_f32_32x32x16_bf16 v[34:49], v[138:141], v[158:161], v[34:49]
	s_waitcnt lgkmcnt(1)
	v_mfma_f32_32x32x16_bf16 v[98:113], v[142:145], v[130:133], v[98:113]
	v_mfma_f32_32x32x16_bf16 v[50:65], v[146:149], v[130:133], v[50:65]
	v_mfma_f32_32x32x16_bf16 v[18:33], v[170:173], v[130:133], v[18:33]
	v_mfma_f32_32x32x16_bf16 v[2:17], v[134:137], v[130:133], v[2:17]
	s_waitcnt lgkmcnt(0)
	v_mfma_f32_32x32x16_bf16 v[114:129], v[142:145], v[150:153], v[114:129]
	v_mfma_f32_32x32x16_bf16 v[82:97], v[146:149], v[150:153], v[82:97]
	v_mfma_f32_32x32x16_bf16 v[66:81], v[170:173], v[150:153], v[66:81]
	v_mfma_f32_32x32x16_bf16 v[34:49], v[134:137], v[150:153], v[34:49]
	s_nop 7
	s_nop 7
	s_lshl_b32 s2, s15, 2
	s_or_b32 s17, s2, s16
	v_lshlrev_b32_e32 v225, 2, v167
	s_lshl_b32 s2, s48, 9
	s_lshl_b32 s3, s16, 7
	s_add_i32 s2, s2, s3
	v_add_u32_e32 v227, s2, v225
	v_add_u32_e32 v217, 0x2c00, v227
	s_lshl_b32 s3, s17, 9
	s_xor_b32 s2, s3, 0x800
	s_add_i32 s3, s3, 0x20000
	s_add_i32 s2, s2, 0x20000
	v_add_u32_e32 v226, s2, v225
	v_add_u32_e32 v225, s3, v225
	s_mov_b32 exec_hi, 0
	ds_write_b32 v225, v98
	ds_write_b32 v225, v114 offset:128
	s_mov_b64 exec, -1
	s_mov_b32 exec_lo, 0
	ds_write_b32 v225, v17 offset:256
	ds_write_b32 v225, v49 offset:384
	s_mov_b64 exec, -1
	s_and_b32 s0, s17, 3
	s_lshl_b32 s0, s0, 13
	s_lshr_b32 s2, s17, 2
	s_lshl_b32 s2, s2, 16
	s_add_i32 s0, s0, s2
	s_add_i32 s0, s0, 0x8000
	v_lshlrev_b32_e32 v224, 1, v167
	v_add_u32_e32 v224, s0, v224
	v_mul_u32_u24_e32 v237, 0xc0, v169
	v_add_u32_e32 v237, v237, v224
	v_mul_u32_u24_e32 v238, 0x140, v169
	v_add_u32_e32 v224, v238, v224
	v_mov_b32_e32 v178, 0xbdd2d3e8
	v_mov_b32_e32 v180, 0xc0135761
	v_mov_b32_e32 v182, 1.0
	s_lshl_b32 s2, s15, 7
	s_add_i32 s2, s2, s14
	s_add_i32 s3, s2, 0x7f
	s_and_b32 s3, s3, 0xffffff00
	s_sub_i32 s37, s3, s2
	s_mov_b32 s36, -1
	s_cmp_lt_i32 s37, 1
	s_cbranch_scc1 .Lupe_nb
	s_cmp_ge_i32 s3, 0x8000
	s_cbranch_scc1 .Lupe_yes
	s_and_b32 s100, s3, 0x7ff
	s_cmp_lg_u32 s100, 0
	s_cbranch_scc1 .Lupe_nb

; template <int MB, class Epi>
; DI void gemm_tile(const u16* __restrict__ A, int lda, int row0, int Mrows, const u16* __restrict__ Bt, int ldb, int K, char* smem, Epi& epi, int rot) {
;     ...
;   GEMM_STAGE(0)
;   DI void operator()(f32x16 (&acc)[2][4], int wm, int wn, int r, int h) {
;     ...
; #pragma unroll
;     for (int ig = 0; ig < 4; ++ig)
; #pragma unroll
;       for (int qp = 0; qp < 2; ++qp) {
;         const int i0 = ig * 4 + qp * 2;
;         float u[2][4][2];
; #pragma unroll
;         for (int nb = 0; nb < 2; ++nb) {
;           int xp[4];
; #pragma unroll
;           for (int mb = 0; mb < 4; ++mb) xp[mb] = (int)pack2(acc[nb][mb][i0], acc[nb][mb][i0 + 1]);
;           const float eo0 = ob[nb * 32 + crow(i0, h)], eo1 = ob[nb * 32 + crow(i0 + 1, h)];
;           float w0[2], w1[2], w2[2], bz[2];
;           {
;             const int ff = nt * 128 + wn * 32 + crow(i0, h) + nb * DFF;
;             const f32x2n a0 = *(const f32x2n*)(cw + ff), a1 = *(const f32x2n*)(cw + 2 * DFF + ff), a2 = *(const f32x2n*)(cw + 4 * DFF + ff),
;                          a3 = *(const f32x2n*)(cb + ff);
;             w0[0] = a0.x; w0[1] = a0.y; w1[0] = a1.x; w1[1] = a1.y; w2[0] = a2.x; w2[1] = a2.y; bz[0] = a3.x; bz[1] = a3.y;
;           }
;           int spm = 0;
; #pragma unroll
;           for (int mb = 0; mb < 4; ++mb) {
;             const int spc = __builtin_amdgcn_ds_bpermute(sp << 2, xp[mb]);
;             const int snc = __builtin_amdgcn_ds_bpermute(sn << 2, xp[mb]);
;             const int snn = (mb < 3) ? __builtin_amdgcn_ds_bpermute(sn << 2, xp[mb < 3 ? mb + 1 : 3]) : 0;
;             const int pv = (mb > 0) ? ((r == 0) ? spm : spc) : spc;
;             const int nv = (mb < 3) ? ((r == 31) ? snn : snc) : snc;
;             float prev0 = __int_as_float(pv << 16), prev1 = __int_as_float(pv & 0xffff0000);
;             float next0 = __int_as_float(nv << 16), next1 = __int_as_float(nv & 0xffff0000);
;             if (mb == 0 && r == 0) { prev0 = eo0; prev1 = eo1; }
;             if (mb == 3 && r == 31) { next0 = eo0; next1 = eo1; }
;             spm = spc;
;             prev0 *= pm[mb]; prev1 *= pm[mb];
;             next0 *= nm[mb]; next1 *= nm[mb];
;             u[nb][mb][0] = w0[0] * prev0 + w1[0] * acc[nb][mb][i0] + w2[0] * next0 + bz[0];
;             u[nb][mb][1] = w0[1] * prev1 + w1[1] * acc[nb][mb][i0 + 1] + w2[1] * next1 + bz[1];
;           }
;         }
.Lupe_nb:
	s_cmp_lt_i32 s36, 0
	s_cbranch_scc0 .Lupe_slow
	v_mov_b32_e32 v184, v50
	v_mov_b32_e32 v185, v82
	v_pk_fma_f32 v[130:131], v[98:99], v[240:241], v[242:243] op_sel_hi:[1,0,0]
	v_pk_fma_f32 v[132:133], v[100:101], v[240:241], v[242:243] op_sel_hi:[1,0,0]
	v_pk_fma_f32 v[134:135], v[102:103], v[240:241], v[242:243] op_sel_hi:[1,0,0]
	v_pk_fma_f32 v[136:137], v[104:105], v[240:241], v[242:243] op_sel_hi:[1,0,0]
	v_pk_fma_f32 v[138:139], v[106:107], v[240:241], v[242:243] op_sel_hi:[1,0,0]
	v_pk_fma_f32 v[140:141], v[108:109], v[240:241], v[242:243] op_sel_hi:[1,0,0]
	v_pk_fma_f32 v[142:143], v[110:111], v[240:241], v[242:243] op_sel_hi:[1,0,0]
	v_pk_fma_f32 v[144:145], v[112:113], v[240:241], v[242:243] op_sel_hi:[1,0,0]
	v_pk_fma_f32 v[146:147], v[114:115], v[244:245], v[246:247] op_sel_hi:[1,0,0]
	v_pk_fma_f32 v[148:149], v[116:117], v[244:245], v[246:247] op_sel_hi:[1,0,0]
	v_pk_fma_f32 v[150:151], v[118:119], v[244:245], v[246:247] op_sel_hi:[1,0,0]
	v_pk_fma_f32 v[152:153], v[120:121], v[244:245], v[246:247] op_sel_hi:[1,0,0]
	v_pk_fma_f32 v[154:155], v[122:123], v[244:245], v[246:247] op_sel_hi:[1,0,0]
	v_pk_fma_f32 v[156:157], v[124:125], v[244:245], v[246:247] op_sel_hi:[1,0,0]
	v_pk_fma_f32 v[158:159], v[126:127], v[244:245], v[246:247] op_sel_hi:[1,0,0]
	v_pk_fma_f32 v[160:161], v[128:129], v[244:245], v[246:247] op_sel_hi:[1,0,0]
	v_fmac_f32_e32 v131, v241, v98
	v_fmac_f32_e32 v130, v243, v99
	v_fmac_f32_e32 v147, v245, v114
	v_fmac_f32_e32 v146, v247, v115
	v_fmac_f32_e32 v133, v241, v100
	v_fmac_f32_e32 v132, v243, v101
	v_fmac_f32_e32 v149, v245, v116
	v_fmac_f32_e32 v148, v247, v117
	v_fmac_f32_e32 v135, v241, v102
	v_fmac_f32_e32 v134, v243, v103
	v_fmac_f32_e32 v151, v245, v118
	v_fmac_f32_e32 v150, v247, v119
	v_fmac_f32_e32 v137, v241, v104
	v_fmac_f32_e32 v136, v243, v105
	v_fmac_f32_e32 v153, v245, v120
	v_fmac_f32_e32 v152, v247, v121
	v_fmac_f32_e32 v139, v241, v106
	v_fmac_f32_e32 v138, v243, v107
	v_fmac_f32_e32 v155, v245, v122
	v_fmac_f32_e32 v154, v247, v123
	v_fmac_f32_e32 v141, v241, v108
	v_fmac_f32_e32 v140, v243, v109
	v_fmac_f32_e32 v157, v245, v124
	v_fmac_f32_e32 v156, v247, v125
	v_fmac_f32_e32 v143, v241, v110
	v_fmac_f32_e32 v142, v243, v111
	v_fmac_f32_e32 v159, v245, v126
	v_fmac_f32_e32 v158, v247, v127
	v_fmac_f32_e32 v145, v241, v112
	v_fmac_f32_e32 v144, v243, v113
	v_fmac_f32_e32 v161, v245, v128
	v_fmac_f32_e32 v160, v247, v129
	v_permlane32_swap_b32_e32 v98, v101
	v_permlane32_swap_b32_e32 v102, v105
	v_permlane32_swap_b32_e32 v106, v109
	v_permlane32_swap_b32_e32 v110, v113
	v_permlane32_swap_b32_e32 v114, v117
	v_permlane32_swap_b32_e32 v118, v121
	v_permlane32_swap_b32_e32 v122, v125
	v_permlane32_swap_b32_e32 v126, v129
	v_permlane32_swap_b32_e32 v101, v102
	v_permlane32_swap_b32_e32 v105, v106
	v_permlane32_swap_b32_e32 v109, v110
	v_permlane32_swap_b32_e32 v117, v118
	v_permlane32_swap_b32_e32 v121, v122
	v_permlane32_swap_b32_e32 v125, v126
	v_permlane32_swap_b32_e32 v113, v184
	v_permlane32_swap_b32_e32 v129, v185
	s_waitcnt lgkmcnt(0)
	s_barrier
	s_mov_b32 s101, 0
	s_mov_b32 s2, s9
.Lupf_advf:
	s_add_i32 s2, s2, s90
	s_cmp_lt_i32 s2, s10
	s_cbranch_scc0 .Lupf_nonef
	s_mov_b32 s3, s2
	s_cmp_lg_u32 s8, 0x92
	s_cbranch_scc1 .Lupf_mapf
	s_cmp_ge_u32 s2, 0xd00
	s_cbranch_scc1 .Lupf_advf
	s_cmp_lt_u32 s2, 0xcfc
	s_cbranch_scc1 .Lupf_mapf
	s_cmp_ge_u32 s2, 0xcfe
	s_cselect_b32 s3, 10, 4
	s_add_i32 s3, s2, s3
.Lupf_mapf:
	s_ashr_i32 s22, s3, 3
	s_mul_hi_i32 s37, s22, 0x2e8ba2e9
	s_lshr_b32 s100, s37, 31
	s_ashr_i32 s37, s37, 2
	s_add_i32 s37, s37, s100
	s_and_b32 s3, s3, 7
	s_lshl_b32 s100, s37, 3
	s_or_b32 s3, s100, s3
	s_cmp_ge_i32 s3, s8
	s_cbranch_scc1 .Lupf_advf
	s_mul_i32 s37, s37, 22
	s_sub_i32 s22, s22, s37
	s_mul_i32 s3, s3, 0xfe
	s_add_i32 s3, s3, -1
	s_and_b32 s37, s2, 15
	s_lshl_b32 s37, s37, 7
	v_ashrrev_i32_e32 v188, 3, v163
	v_lshrrev_b32_e32 v189, 4, v163
	v_xor_b32_e32 v189, v189, v163
	v_lshlrev_b32_e32 v189, 4, v189
	v_and_b32_e32 v189, 0x70, v189
	v_add_u32_e32 v189, s37, v189
	v_mov_b32_e32 v191, 0
	v_readfirstlane_b32 s100, v163
	s_lshl_b32 s100, s100, 4
	v_add_u32_e32 v190, s3, v188
	v_max_i32_e32 v190, 0, v190
	v_min_u32_e32 v190, s13, v190
	v_lshl_add_u32 v190, v190, 11, v189
	v_lshl_add_u64 v[192:193], s[84:85], 0, v[190:191]
	s_mov_b32 m0, s100
	s_nop 0
	global_load_lds_dwordx4 v[192:193], off
	s_add_i32 s3, s3, 64
	v_add_u32_e32 v190, s3, v188
	v_max_i32_e32 v190, 0, v190
	v_min_u32_e32 v190, s13, v190
	v_lshl_add_u32 v190, v190, 11, v189
	v_lshl_add_u64 v[192:193], s[84:85], 0, v[190:191]
	s_add_i32 s2, s100, 0x2000
	s_mov_b32 m0, s2
	s_nop 0
	global_load_lds_dwordx4 v[192:193], off
	s_add_i32 s3, s3, 64
	v_add_u32_e32 v190, s3, v188
	v_max_i32_e32 v190, 0, v190
	v_min_u32_e32 v190, s13, v190
	v_lshl_add_u32 v190, v190, 11, v189
	v_lshl_add_u64 v[192:193], s[84:85], 0, v[190:191]
	s_add_i32 s2, s100, 0x4000
	s_mov_b32 m0, s2
	s_nop 0
	global_load_lds_dwordx4 v[192:193], off
	s_add_i32 s3, s3, 64
	v_add_u32_e32 v190, s3, v188
	v_max_i32_e32 v190, 0, v190
	v_min_u32_e32 v190, s13, v190
	v_lshl_add_u32 v190, v190, 11, v189
	v_lshl_add_u64 v[192:193], s[84:85], 0, v[190:191]
	s_add_i32 s2, s100, 0x6000
	s_mov_b32 m0, s2
	s_nop 0
	global_load_lds_dwordx4 v[192:193], off
	s_lshl_b32 s2, s22, 19
	s_add_u32 s2, s11, s2
	s_addc_u32 s3, s12, 0
	v_lshl_add_u32 v190, v188, 11, v189
	v_lshl_add_u64 v[192:193], s[2:3], 0, v[190:191]
	s_add_i32 s2, s100, 0x10000
	s_mov_b32 m0, s2
	s_nop 0
	global_load_lds_dwordx4 v[192:193], off
	v_lshl_add_u64 v[194:195], v[192:193], 0, s[4:5]
	s_add_i32 s2, s100, 0x12000
	s_mov_b32 m0, s2
	s_nop 0
	global_load_lds_dwordx4 v[194:195], off
	v_lshl_add_u64 v[194:195], v[192:193], 0, s[6:7]
	s_add_i32 s2, s100, 0x14000
	s_mov_b32 m0, s2
	s_nop 0
	global_load_lds_dwordx4 v[194:195], off
	v_lshl_add_u64 v[194:195], v[192:193], 0, s[34:35]
	s_add_i32 s2, s100, 0x16000
	s_mov_b32 m0, s2
	s_nop 0
	global_load_lds_dwordx4 v[194:195], off
	s_mov_b32 s101, 1
; DI unsigned pack2(float a, float b) { f2 v = {a, b}; bf2 r = __builtin_convertvector(v, bf2); return __builtin_bit_cast(unsigned, r); }
;   DI void operator()(f32x16 (&acc)[2][4], int wm, int wn, int r, int h) {
;     ...
;           for (int mb = 0; mb < 4; ++mb) {
;             const int spc = __builtin_amdgcn_ds_bpermute(sp << 2, xp[mb]);
;             const int snc = __builtin_amdgcn_ds_bpermute(sn << 2, xp[mb]);
;             const int snn = (mb < 3) ? __builtin_amdgcn_ds_bpermute(sn << 2, xp[mb < 3 ? mb + 1 : 3]) : 0;
;             const int pv = (mb > 0) ? ((r == 0) ? spm : spc) : spc;
;             const int nv = (mb < 3) ? ((r == 31) ? snn : snc) : snc;
;             float prev0 = __int_as_float(pv << 16), prev1 = __int_as_float(pv & 0xffff0000);
;             float next0 = __int_as_float(nv << 16), next1 = __int_as_float(nv & 0xffff0000);
;             if (mb == 0 && r == 0) { prev0 = eo0; prev1 = eo1; }
;             if (mb == 3 && r == 31) { next0 = eo0; next1 = eo1; }
;             spm = spc;
;             prev0 *= pm[mb]; prev1 *= pm[mb];
;             next0 *= nm[mb]; next1 *= nm[mb];
;             u[nb][mb][0] = w0[0] * prev0 + w1[0] * acc[nb][mb][i0] + w2[0] * next0 + bz[0];
;             u[nb][mb][1] = w0[1] * prev1 + w1[1] * acc[nb][mb][i0 + 1] + w2[1] * next1 + bz[1];
;           }
;         }
; #pragma unroll
;         for (int mb = 0; mb < 4; ++mb)
;           *(unsigned*)(ost + (mb * 32 + r) * 40 + ig * 8 + h * 4 + qp * 2) =
;               pack2(gelu_tanh(u[1][mb][0]) * u[0][mb][0], gelu_tanh(u[1][mb][1]) * u[0][mb][1]);
.Lupf_nonef:
	s_mov_b32 exec_hi, 0
	ds_read_b32 v98, v226 offset:256
	ds_read_b32 v114, v226 offset:384
	s_mov_b64 exec, -1
	v_fmac_f32_e32 v131, v243, v100
	v_fmac_f32_e32 v132, v241, v99
	v_fmac_f32_e32 v135, v243, v104
	v_fmac_f32_e32 v136, v241, v103
	v_fmac_f32_e32 v139, v243, v108
	v_fmac_f32_e32 v140, v241, v107
	v_fmac_f32_e32 v143, v243, v112
	v_fmac_f32_e32 v144, v241, v111
	v_fmac_f32_e32 v147, v247, v116
	v_fmac_f32_e32 v148, v245, v115
	v_fmac_f32_e32 v151, v247, v120
	v_fmac_f32_e32 v152, v245, v119
	v_fmac_f32_e32 v155, v247, v124
	v_fmac_f32_e32 v156, v245, v123
	v_fmac_f32_e32 v159, v247, v128
	v_fmac_f32_e32 v160, v245, v127
	s_waitcnt lgkmcnt(0)
	v_fmac_f32_e32 v130, v241, v98
	v_fmac_f32_e32 v133, v243, v101
	v_fmac_f32_e32 v134, v241, v102
	v_fmac_f32_e32 v137, v243, v105
	v_fmac_f32_e32 v138, v241, v106
	v_fmac_f32_e32 v141, v243, v109
	v_fmac_f32_e32 v142, v241, v110
	v_fmac_f32_e32 v145, v243, v113
	v_fmac_f32_e32 v146, v245, v114
	v_fmac_f32_e32 v149, v247, v117
	v_fmac_f32_e32 v150, v245, v118
	v_fmac_f32_e32 v153, v247, v121
	v_fmac_f32_e32 v154, v245, v122
	v_fmac_f32_e32 v157, v247, v125
	v_fmac_f32_e32 v158, v245, v126
	v_fmac_f32_e32 v161, v247, v129
	v_pk_mul_f32 v[188:189], v[146:147], v[146:147]
	v_pk_mul_f32 v[190:191], v[148:149], v[148:149]
	v_pk_mul_f32 v[192:193], v[150:151], v[150:151]
	v_pk_mul_f32 v[194:195], v[152:153], v[152:153]
	v_pk_mul_f32 v[196:197], v[154:155], v[154:155]
	v_pk_mul_f32 v[218:219], v[156:157], v[156:157]
	v_pk_mul_f32 v[220:221], v[158:159], v[158:159]
	v_pk_mul_f32 v[222:223], v[160:161], v[160:161]
	v_pk_fma_f32 v[188:189], v[188:189], v[178:179], v[180:181] op_sel_hi:[1,0,0]
	v_pk_fma_f32 v[190:191], v[190:191], v[178:179], v[180:181] op_sel_hi:[1,0,0]
	v_pk_fma_f32 v[192:193], v[192:193], v[178:179], v[180:181] op_sel_hi:[1,0,0]
	v_pk_fma_f32 v[194:195], v[194:195], v[178:179], v[180:181] op_sel_hi:[1,0,0]
	v_pk_fma_f32 v[196:197], v[196:197], v[178:179], v[180:181] op_sel_hi:[1,0,0]
	v_pk_fma_f32 v[218:219], v[218:219], v[178:179], v[180:181] op_sel_hi:[1,0,0]
	v_pk_fma_f32 v[220:221], v[220:221], v[178:179], v[180:181] op_sel_hi:[1,0,0]
	v_pk_fma_f32 v[222:223], v[222:223], v[178:179], v[180:181] op_sel_hi:[1,0,0]
	v_pk_mul_f32 v[188:189], v[146:147], v[188:189]
	v_pk_mul_f32 v[190:191], v[148:149], v[190:191]
	v_pk_mul_f32 v[192:193], v[150:151], v[192:193]
	v_pk_mul_f32 v[194:195], v[152:153], v[194:195]
	v_pk_mul_f32 v[196:197], v[154:155], v[196:197]
	v_pk_mul_f32 v[218:219], v[156:157], v[218:219]
	v_pk_mul_f32 v[220:221], v[158:159], v[220:221]
	v_pk_mul_f32 v[222:223], v[160:161], v[222:223]
	v_exp_f32_e32 v188, v188
	v_exp_f32_e32 v189, v189
	v_exp_f32_e32 v190, v190
	v_exp_f32_e32 v191, v191
	v_exp_f32_e32 v192, v192
	v_exp_f32_e32 v193, v193
	v_exp_f32_e32 v194, v194
	v_exp_f32_e32 v195, v195
	v_exp_f32_e32 v196, v196
	v_exp_f32_e32 v197, v197
	v_exp_f32_e32 v218, v218
	v_exp_f32_e32 v219, v219
	v_exp_f32_e32 v220, v220
	v_exp_f32_e32 v221, v221
	v_exp_f32_e32 v222, v222
	v_exp_f32_e32 v223, v223
	v_pk_add_f32 v[188:189], v[188:189], v[182:183] op_sel_hi:[1,0]
	v_pk_add_f32 v[190:191], v[190:191], v[182:183] op_sel_hi:[1,0]
	v_pk_add_f32 v[192:193], v[192:193], v[182:183] op_sel_hi:[1,0]
	v_pk_add_f32 v[194:195], v[194:195], v[182:183] op_sel_hi:[1,0]
	v_pk_add_f32 v[196:197], v[196:197], v[182:183] op_sel_hi:[1,0]
	v_pk_add_f32 v[218:219], v[218:219], v[182:183] op_sel_hi:[1,0]
	v_pk_add_f32 v[220:221], v[220:221], v[182:183] op_sel_hi:[1,0]
	v_pk_add_f32 v[222:223], v[222:223], v[182:183] op_sel_hi:[1,0]
	v_rcp_f32_e32 v188, v188
	v_rcp_f32_e32 v189, v189
	v_rcp_f32_e32 v190, v190
	v_rcp_f32_e32 v191, v191
	v_rcp_f32_e32 v192, v192
	v_rcp_f32_e32 v193, v193
	v_rcp_f32_e32 v194, v194
	v_rcp_f32_e32 v195, v195
	v_rcp_f32_e32 v196, v196
	v_rcp_f32_e32 v197, v197
	v_rcp_f32_e32 v218, v218
	v_rcp_f32_e32 v219, v219
	v_rcp_f32_e32 v220, v220
	v_rcp_f32_e32 v221, v221
	v_rcp_f32_e32 v222, v222
	v_rcp_f32_e32 v223, v223
	v_pk_mul_f32 v[188:189], v[146:147], v[188:189]
	v_pk_mul_f32 v[190:191], v[148:149], v[190:191]
	v_pk_mul_f32 v[192:193], v[150:151], v[192:193]
	v_pk_mul_f32 v[194:195], v[152:153], v[194:195]
	v_pk_mul_f32 v[196:197], v[154:155], v[196:197]
	v_pk_mul_f32 v[218:219], v[156:157], v[218:219]
	v_pk_mul_f32 v[220:221], v[158:159], v[220:221]
	v_pk_mul_f32 v[222:223], v[160:161], v[222:223]
	v_pk_mul_f32 v[188:189], v[188:189], v[130:131]
	v_pk_mul_f32 v[190:191], v[190:191], v[132:133]
	v_pk_mul_f32 v[192:193], v[192:193], v[134:135]
	v_pk_mul_f32 v[194:195], v[194:195], v[136:137]
	v_pk_mul_f32 v[196:197], v[196:197], v[138:139]
	v_pk_mul_f32 v[218:219], v[218:219], v[140:141]
	v_pk_mul_f32 v[220:221], v[220:221], v[142:143]
	v_pk_mul_f32 v[222:223], v[222:223], v[144:145]
	v_cvt_pk_bf16_f32 v188, v188, v189
	v_cvt_pk_bf16_f32 v190, v190, v191
	v_cvt_pk_bf16_f32 v192, v192, v193
	v_cvt_pk_bf16_f32 v194, v194, v195
	v_cvt_pk_bf16_f32 v196, v196, v197
	v_cvt_pk_bf16_f32 v218, v218, v219
	v_cvt_pk_bf16_f32 v220, v220, v221
	v_cvt_pk_bf16_f32 v222, v222, v223
	ds_write_b16 v224, v188 offset:0
	ds_write_b16_d16_hi v237, v188 offset:64
	ds_write_b16 v224, v190 offset:128
	ds_write_b16_d16_hi v237, v190 offset:192
	ds_write_b16 v224, v192 offset:512
	ds_write_b16_d16_hi v237, v192 offset:576
	ds_write_b16 v224, v194 offset:640
	ds_write_b16_d16_hi v237, v194 offset:704
	ds_write_b16 v224, v196 offset:1024
	ds_write_b16_d16_hi v237, v196 offset:1088
	ds_write_b16 v224, v218 offset:1152
	ds_write_b16_d16_hi v237, v218 offset:1216
	ds_write_b16 v224, v220 offset:1536
	ds_write_b16_d16_hi v237, v220 offset:1600
	ds_write_b16 v224, v222 offset:1664
; DI int crow(int i, int h) { return (i & 3) + 8 * (i >> 2) + 4 * h; }
;   DI void operator()(f32x16 (&acc)[2][4], int wm, int wn, int r, int h) {
;     ...
; #pragma unroll
;     for (int ig = 0; ig < 4; ++ig)
; #pragma unroll
;       for (int qp = 0; qp < 2; ++qp) {
;         const int i0 = ig * 4 + qp * 2;
;         float u[2][4][2];
; #pragma unroll
;         for (int nb = 0; nb < 2; ++nb) {
;           int xp[4];
; #pragma unroll
;           for (int mb = 0; mb < 4; ++mb) xp[mb] = (int)pack2(acc[nb][mb][i0], acc[nb][mb][i0 + 1]);
;           const float eo0 = ob[nb * 32 + crow(i0, h)], eo1 = ob[nb * 32 + crow(i0 + 1, h)];
;           float w0[2], w1[2], w2[2], bz[2];
;           {
;             const int ff = nt * 128 + wn * 32 + crow(i0, h) + nb * DFF;
;             const f32x2n a0 = *(const f32x2n*)(cw + ff), a1 = *(const f32x2n*)(cw + 2 * DFF + ff), a2 = *(const f32x2n*)(cw + 4 * DFF + ff),
;                          a3 = *(const f32x2n*)(cb + ff);
;             w0[0] = a0.x; w0[1] = a0.y; w1[0] = a1.x; w1[1] = a1.y; w2[0] = a2.x; w2[1] = a2.y; bz[0] = a3.x; bz[1] = a3.y;
;           }
;           int spm = 0;
; #pragma unroll
;           for (int mb = 0; mb < 4; ++mb) {
;             const int spc = __builtin_amdgcn_ds_bpermute(sp << 2, xp[mb]);
;             const int snc = __builtin_amdgcn_ds_bpermute(sn << 2, xp[mb]);
;             const int snn = (mb < 3) ? __builtin_amdgcn_ds_bpermute(sn << 2, xp[mb < 3 ? mb + 1 : 3]) : 0;
;             const int pv = (mb > 0) ? ((r == 0) ? spm : spc) : spc;
;             const int nv = (mb < 3) ? ((r == 31) ? snn : snc) : snc;
;             float prev0 = __int_as_float(pv << 16), prev1 = __int_as_float(pv & 0xffff0000);
;             float next0 = __int_as_float(nv << 16), next1 = __int_as_float(nv & 0xffff0000);
;             if (mb == 0 && r == 0) { prev0 = eo0; prev1 = eo1; }
;             if (mb == 3 && r == 31) { next0 = eo0; next1 = eo1; }
;             spm = spc;
;             prev0 *= pm[mb]; prev1 *= pm[mb];
;             next0 *= nm[mb]; next1 *= nm[mb];
;             u[nb][mb][0] = w0[0] * prev0 + w1[0] * acc[nb][mb][i0] + w2[0] * next0 + bz[0];
;             u[nb][mb][1] = w0[1] * prev1 + w1[1] * acc[nb][mb][i0 + 1] + w2[1] * next1 + bz[1];
;           }
;         }
; #pragma unroll
;         for (int mb = 0; mb < 4; ++mb)
;           *(unsigned*)(ost + (mb * 32 + r) * 40 + ig * 8 + h * 4 + qp * 2) =
	ds_write_b16_d16_hi v237, v222 offset:1728
	v_mov_b32_e32 v186, v18
	v_mov_b32_e32 v187, v66
	v_pk_fma_f32 v[130:131], v[50:51], v[240:241], v[242:243] op_sel_hi:[1,0,0]
	v_pk_fma_f32 v[132:133], v[52:53], v[240:241], v[242:243] op_sel_hi:[1,0,0]
	v_pk_fma_f32 v[134:135], v[54:55], v[240:241], v[242:243] op_sel_hi:[1,0,0]
	v_pk_fma_f32 v[136:137], v[56:57], v[240:241], v[242:243] op_sel_hi:[1,0,0]
	v_pk_fma_f32 v[138:139], v[58:59], v[240:241], v[242:243] op_sel_hi:[1,0,0]
	v_pk_fma_f32 v[140:141], v[60:61], v[240:241], v[242:243] op_sel_hi:[1,0,0]
	v_pk_fma_f32 v[142:143], v[62:63], v[240:241], v[242:243] op_sel_hi:[1,0,0]
	v_pk_fma_f32 v[144:145], v[64:65], v[240:241], v[242:243] op_sel_hi:[1,0,0]
	v_pk_fma_f32 v[146:147], v[82:83], v[244:245], v[246:247] op_sel_hi:[1,0,0]
	v_pk_fma_f32 v[148:149], v[84:85], v[244:245], v[246:247] op_sel_hi:[1,0,0]
	v_pk_fma_f32 v[150:151], v[86:87], v[244:245], v[246:247] op_sel_hi:[1,0,0]
	v_pk_fma_f32 v[152:153], v[88:89], v[244:245], v[246:247] op_sel_hi:[1,0,0]
	v_pk_fma_f32 v[154:155], v[90:91], v[244:245], v[246:247] op_sel_hi:[1,0,0]
	v_pk_fma_f32 v[156:157], v[92:93], v[244:245], v[246:247] op_sel_hi:[1,0,0]
	v_pk_fma_f32 v[158:159], v[94:95], v[244:245], v[246:247] op_sel_hi:[1,0,0]
	v_pk_fma_f32 v[160:161], v[96:97], v[244:245], v[246:247] op_sel_hi:[1,0,0]
	v_fmac_f32_e32 v131, v241, v50
	v_fmac_f32_e32 v130, v243, v51
	v_fmac_f32_e32 v147, v245, v82
	v_fmac_f32_e32 v146, v247, v83
	v_fmac_f32_e32 v133, v241, v52
	v_fmac_f32_e32 v132, v243, v53
	v_fmac_f32_e32 v149, v245, v84
	v_fmac_f32_e32 v148, v247, v85
	v_fmac_f32_e32 v135, v241, v54
	v_fmac_f32_e32 v134, v243, v55
	v_fmac_f32_e32 v151, v245, v86
	v_fmac_f32_e32 v150, v247, v87
	v_fmac_f32_e32 v137, v241, v56
	v_fmac_f32_e32 v136, v243, v57
	v_fmac_f32_e32 v153, v245, v88
	v_fmac_f32_e32 v152, v247, v89
	v_fmac_f32_e32 v139, v241, v58
	v_fmac_f32_e32 v138, v243, v59
	v_fmac_f32_e32 v155, v245, v90
	v_fmac_f32_e32 v154, v247, v91
	v_fmac_f32_e32 v141, v241, v60
	v_fmac_f32_e32 v140, v243, v61
	v_fmac_f32_e32 v157, v245, v92
	v_fmac_f32_e32 v156, v247, v93
	v_fmac_f32_e32 v143, v241, v62
	v_fmac_f32_e32 v142, v243, v63
	v_fmac_f32_e32 v159, v245, v94
	v_fmac_f32_e32 v158, v247, v95
	v_fmac_f32_e32 v145, v241, v64
	v_fmac_f32_e32 v144, v243, v65
	v_fmac_f32_e32 v161, v245, v96
	v_fmac_f32_e32 v160, v247, v97
	v_permlane32_swap_b32_e32 v50, v53
	v_permlane32_swap_b32_e32 v54, v57
	v_permlane32_swap_b32_e32 v58, v61
	v_permlane32_swap_b32_e32 v62, v65
	v_permlane32_swap_b32_e32 v82, v85
	v_permlane32_swap_b32_e32 v86, v89
	v_permlane32_swap_b32_e32 v90, v93
	v_permlane32_swap_b32_e32 v94, v97
	v_permlane32_swap_b32_e32 v53, v54
	v_permlane32_swap_b32_e32 v57, v58
	v_permlane32_swap_b32_e32 v61, v62
	v_permlane32_swap_b32_e32 v85, v86
	v_permlane32_swap_b32_e32 v89, v90
	v_permlane32_swap_b32_e32 v93, v94
	v_permlane32_swap_b32_e32 v65, v186
	v_permlane32_swap_b32_e32 v97, v187
	s_mov_b32 exec_hi, 0
	v_mov_b32_e32 v50, v184
	v_mov_b32_e32 v82, v185
	s_mov_b64 exec, -1
	v_fmac_f32_e32 v131, v243, v52
	v_fmac_f32_e32 v132, v241, v51
	v_fmac_f32_e32 v135, v243, v56
	v_fmac_f32_e32 v136, v241, v55
	v_fmac_f32_e32 v139, v243, v60
	v_fmac_f32_e32 v140, v241, v59
	v_fmac_f32_e32 v143, v243, v64
	v_fmac_f32_e32 v144, v241, v63
	v_fmac_f32_e32 v147, v247, v84
	v_fmac_f32_e32 v148, v245, v83
	v_fmac_f32_e32 v151, v247, v88
	v_fmac_f32_e32 v152, v245, v87
	v_fmac_f32_e32 v155, v247, v92
	v_fmac_f32_e32 v156, v245, v91
	v_fmac_f32_e32 v159, v247, v96
	v_fmac_f32_e32 v160, v245, v95
	v_fmac_f32_e32 v130, v241, v50
	v_fmac_f32_e32 v133, v243, v53
	v_fmac_f32_e32 v134, v241, v54
	v_fmac_f32_e32 v137, v243, v57
	v_fmac_f32_e32 v138, v241, v58
	v_fmac_f32_e32 v141, v243, v61
	v_fmac_f32_e32 v142, v241, v62
	v_fmac_f32_e32 v145, v243, v65
	v_fmac_f32_e32 v146, v245, v82
	v_fmac_f32_e32 v149, v247, v85
	v_fmac_f32_e32 v150, v245, v86
	v_fmac_f32_e32 v153, v247, v89
	v_fmac_f32_e32 v154, v245, v90
	v_fmac_f32_e32 v157, v247, v93
	v_fmac_f32_e32 v158, v245, v94
	v_fmac_f32_e32 v161, v247, v97
	v_pk_mul_f32 v[188:189], v[146:147], v[146:147]
	v_pk_mul_f32 v[190:191], v[148:149], v[148:149]
	v_pk_mul_f32 v[192:193], v[150:151], v[150:151]
	v_pk_mul_f32 v[194:195], v[152:153], v[152:153]
	v_pk_mul_f32 v[196:197], v[154:155], v[154:155]
	v_pk_mul_f32 v[218:219], v[156:157], v[156:157]
	v_pk_mul_f32 v[220:221], v[158:159], v[158:159]
	v_pk_mul_f32 v[222:223], v[160:161], v[160:161]
	v_pk_fma_f32 v[188:189], v[188:189], v[178:179], v[180:181] op_sel_hi:[1,0,0]
	v_pk_fma_f32 v[190:191], v[190:191], v[178:179], v[180:181] op_sel_hi:[1,0,0]
	v_pk_fma_f32 v[192:193], v[192:193], v[178:179], v[180:181] op_sel_hi:[1,0,0]
	v_pk_fma_f32 v[194:195], v[194:195], v[178:179], v[180:181] op_sel_hi:[1,0,0]
	v_pk_fma_f32 v[196:197], v[196:197], v[178:179], v[180:181] op_sel_hi:[1,0,0]
	v_pk_fma_f32 v[218:219], v[218:219], v[178:179], v[180:181] op_sel_hi:[1,0,0]
	v_pk_fma_f32 v[220:221], v[220:221], v[178:179], v[180:181] op_sel_hi:[1,0,0]
	v_pk_fma_f32 v[222:223], v[222:223], v[178:179], v[180:181] op_sel_hi:[1,0,0]
	v_pk_mul_f32 v[188:189], v[146:147], v[188:189]
	v_pk_mul_f32 v[190:191], v[148:149], v[190:191]
	v_pk_mul_f32 v[192:193], v[150:151], v[192:193]
	v_pk_mul_f32 v[194:195], v[152:153], v[194:195]
	v_pk_mul_f32 v[196:197], v[154:155], v[196:197]
	v_pk_mul_f32 v[218:219], v[156:157], v[218:219]
	v_pk_mul_f32 v[220:221], v[158:159], v[220:221]
	v_pk_mul_f32 v[222:223], v[160:161], v[222:223]
	v_exp_f32_e32 v188, v188
	v_exp_f32_e32 v189, v189
	v_exp_f32_e32 v190, v190
	v_exp_f32_e32 v191, v191
	v_exp_f32_e32 v192, v192
	v_exp_f32_e32 v193, v193
	v_exp_f32_e32 v194, v194
; DI int crow(int i, int h) { return (i & 3) + 8 * (i >> 2) + 4 * h; }
;   DI void operator()(f32x16 (&acc)[2][4], int wm, int wn, int r, int h) {
;     ...
; #pragma unroll
;     for (int ig = 0; ig < 4; ++ig)
; #pragma unroll
;       for (int qp = 0; qp < 2; ++qp) {
;         const int i0 = ig * 4 + qp * 2;
;         float u[2][4][2];
; #pragma unroll
;         for (int nb = 0; nb < 2; ++nb) {
;           int xp[4];
; #pragma unroll
;           for (int mb = 0; mb < 4; ++mb) xp[mb] = (int)pack2(acc[nb][mb][i0], acc[nb][mb][i0 + 1]);
;           const float eo0 = ob[nb * 32 + crow(i0, h)], eo1 = ob[nb * 32 + crow(i0 + 1, h)];
;           float w0[2], w1[2], w2[2], bz[2];
;           {
;             const int ff = nt * 128 + wn * 32 + crow(i0, h) + nb * DFF;
;             const f32x2n a0 = *(const f32x2n*)(cw + ff), a1 = *(const f32x2n*)(cw + 2 * DFF + ff), a2 = *(const f32x2n*)(cw + 4 * DFF + ff),
;                          a3 = *(const f32x2n*)(cb + ff);
;             w0[0] = a0.x; w0[1] = a0.y; w1[0] = a1.x; w1[1] = a1.y; w2[0] = a2.x; w2[1] = a2.y; bz[0] = a3.x; bz[1] = a3.y;
;           }
;           int spm = 0;
; #pragma unroll
;           for (int mb = 0; mb < 4; ++mb) {
;             const int spc = __builtin_amdgcn_ds_bpermute(sp << 2, xp[mb]);
;             const int snc = __builtin_amdgcn_ds_bpermute(sn << 2, xp[mb]);
;             const int snn = (mb < 3) ? __builtin_amdgcn_ds_bpermute(sn << 2, xp[mb < 3 ? mb + 1 : 3]) : 0;
;             const int pv = (mb > 0) ? ((r == 0) ? spm : spc) : spc;
;             const int nv = (mb < 3) ? ((r == 31) ? snn : snc) : snc;
;             float prev0 = __int_as_float(pv << 16), prev1 = __int_as_float(pv & 0xffff0000);
;             float next0 = __int_as_float(nv << 16), next1 = __int_as_float(nv & 0xffff0000);
;             if (mb == 0 && r == 0) { prev0 = eo0; prev1 = eo1; }
;             if (mb == 3 && r == 31) { next0 = eo0; next1 = eo1; }
;             spm = spc;
;             prev0 *= pm[mb]; prev1 *= pm[mb];
;             next0 *= nm[mb]; next1 *= nm[mb];
;             u[nb][mb][0] = w0[0] * prev0 + w1[0] * acc[nb][mb][i0] + w2[0] * next0 + bz[0];
;             u[nb][mb][1] = w0[1] * prev1 + w1[1] * acc[nb][mb][i0 + 1] + w2[1] * next1 + bz[1];
;           }
;         }
; #pragma unroll
;         for (int mb = 0; mb < 4; ++mb)
;           *(unsigned*)(ost + (mb * 32 + r) * 40 + ig * 8 + h * 4 + qp * 2) =
	v_exp_f32_e32 v195, v195
	v_exp_f32_e32 v196, v196
	v_exp_f32_e32 v197, v197
	v_exp_f32_e32 v218, v218
	v_exp_f32_e32 v219, v219
	v_exp_f32_e32 v220, v220
	v_exp_f32_e32 v221, v221
	v_exp_f32_e32 v222, v222
	v_exp_f32_e32 v223, v223
	v_pk_add_f32 v[188:189], v[188:189], v[182:183] op_sel_hi:[1,0]
	v_pk_add_f32 v[190:191], v[190:191], v[182:183] op_sel_hi:[1,0]
	v_pk_add_f32 v[192:193], v[192:193], v[182:183] op_sel_hi:[1,0]
	v_pk_add_f32 v[194:195], v[194:195], v[182:183] op_sel_hi:[1,0]
	v_pk_add_f32 v[196:197], v[196:197], v[182:183] op_sel_hi:[1,0]
	v_pk_add_f32 v[218:219], v[218:219], v[182:183] op_sel_hi:[1,0]
	v_pk_add_f32 v[220:221], v[220:221], v[182:183] op_sel_hi:[1,0]
	v_pk_add_f32 v[222:223], v[222:223], v[182:183] op_sel_hi:[1,0]
	v_rcp_f32_e32 v188, v188
	v_rcp_f32_e32 v189, v189
	v_rcp_f32_e32 v190, v190
	v_rcp_f32_e32 v191, v191
	v_rcp_f32_e32 v192, v192
	v_rcp_f32_e32 v193, v193
	v_rcp_f32_e32 v194, v194
	v_rcp_f32_e32 v195, v195
	v_rcp_f32_e32 v196, v196
	v_rcp_f32_e32 v197, v197
	v_rcp_f32_e32 v218, v218
	v_rcp_f32_e32 v219, v219
	v_rcp_f32_e32 v220, v220
	v_rcp_f32_e32 v221, v221
	v_rcp_f32_e32 v222, v222
	v_rcp_f32_e32 v223, v223
	v_pk_mul_f32 v[188:189], v[146:147], v[188:189]
	v_pk_mul_f32 v[190:191], v[148:149], v[190:191]
	v_pk_mul_f32 v[192:193], v[150:151], v[192:193]
	v_pk_mul_f32 v[194:195], v[152:153], v[194:195]
	v_pk_mul_f32 v[196:197], v[154:155], v[196:197]
	v_pk_mul_f32 v[218:219], v[156:157], v[218:219]
	v_pk_mul_f32 v[220:221], v[158:159], v[220:221]
	v_pk_mul_f32 v[222:223], v[160:161], v[222:223]
	v_pk_mul_f32 v[188:189], v[188:189], v[130:131]
	v_pk_mul_f32 v[190:191], v[190:191], v[132:133]
	v_pk_mul_f32 v[192:193], v[192:193], v[134:135]
	v_pk_mul_f32 v[194:195], v[194:195], v[136:137]
	v_pk_mul_f32 v[196:197], v[196:197], v[138:139]
	v_pk_mul_f32 v[218:219], v[218:219], v[140:141]
	v_pk_mul_f32 v[220:221], v[220:221], v[142:143]
	v_pk_mul_f32 v[222:223], v[222:223], v[144:145]
	v_cvt_pk_bf16_f32 v188, v188, v189
	v_cvt_pk_bf16_f32 v190, v190, v191
	v_cvt_pk_bf16_f32 v192, v192, v193
	v_cvt_pk_bf16_f32 v194, v194, v195
	v_cvt_pk_bf16_f32 v196, v196, v197
	v_cvt_pk_bf16_f32 v218, v218, v219
	v_cvt_pk_bf16_f32 v220, v220, v221
	v_cvt_pk_bf16_f32 v222, v222, v223
	ds_write_b16 v224, v188 offset:2048
	ds_write_b16_d16_hi v237, v188 offset:2112
	ds_write_b16 v224, v190 offset:2176
	ds_write_b16_d16_hi v237, v190 offset:2240
	ds_write_b16 v224, v192 offset:2560
	ds_write_b16_d16_hi v237, v192 offset:2624
	ds_write_b16 v224, v194 offset:2688
	ds_write_b16_d16_hi v237, v194 offset:2752
	ds_write_b16 v224, v196 offset:3072
	ds_write_b16_d16_hi v237, v196 offset:3136
	ds_write_b16 v224, v218 offset:3200
	ds_write_b16_d16_hi v237, v218 offset:3264
	ds_write_b16 v224, v220 offset:3584
	ds_write_b16_d16_hi v237, v220 offset:3648
	ds_write_b16 v224, v222 offset:3712
	ds_write_b16_d16_hi v237, v222 offset:3776
	v_mov_b32_e32 v184, v2
	v_mov_b32_e32 v185, v34
	v_pk_fma_f32 v[130:131], v[18:19], v[240:241], v[242:243] op_sel_hi:[1,0,0]
	v_pk_fma_f32 v[132:133], v[20:21], v[240:241], v[242:243] op_sel_hi:[1,0,0]
	v_pk_fma_f32 v[134:135], v[22:23], v[240:241], v[242:243] op_sel_hi:[1,0,0]
	v_pk_fma_f32 v[136:137], v[24:25], v[240:241], v[242:243] op_sel_hi:[1,0,0]
	v_pk_fma_f32 v[138:139], v[26:27], v[240:241], v[242:243] op_sel_hi:[1,0,0]
	v_pk_fma_f32 v[140:141], v[28:29], v[240:241], v[242:243] op_sel_hi:[1,0,0]
	v_pk_fma_f32 v[142:143], v[30:31], v[240:241], v[242:243] op_sel_hi:[1,0,0]
	v_pk_fma_f32 v[144:145], v[32:33], v[240:241], v[242:243] op_sel_hi:[1,0,0]
	v_pk_fma_f32 v[146:147], v[66:67], v[244:245], v[246:247] op_sel_hi:[1,0,0]
	v_pk_fma_f32 v[148:149], v[68:69], v[244:245], v[246:247] op_sel_hi:[1,0,0]
	v_pk_fma_f32 v[150:151], v[70:71], v[244:245], v[246:247] op_sel_hi:[1,0,0]
	v_pk_fma_f32 v[152:153], v[72:73], v[244:245], v[246:247] op_sel_hi:[1,0,0]
	v_pk_fma_f32 v[154:155], v[74:75], v[244:245], v[246:247] op_sel_hi:[1,0,0]
	v_pk_fma_f32 v[156:157], v[76:77], v[244:245], v[246:247] op_sel_hi:[1,0,0]
	v_pk_fma_f32 v[158:159], v[78:79], v[244:245], v[246:247] op_sel_hi:[1,0,0]
	v_pk_fma_f32 v[160:161], v[80:81], v[244:245], v[246:247] op_sel_hi:[1,0,0]
	v_fmac_f32_e32 v131, v241, v18
	v_fmac_f32_e32 v130, v243, v19
	v_fmac_f32_e32 v147, v245, v66
	v_fmac_f32_e32 v146, v247, v67
	v_fmac_f32_e32 v133, v241, v20
	v_fmac_f32_e32 v132, v243, v21
	v_fmac_f32_e32 v149, v245, v68
	v_fmac_f32_e32 v148, v247, v69
	v_fmac_f32_e32 v135, v241, v22
	v_fmac_f32_e32 v134, v243, v23
	v_fmac_f32_e32 v151, v245, v70
	v_fmac_f32_e32 v150, v247, v71
	v_fmac_f32_e32 v137, v241, v24
	v_fmac_f32_e32 v136, v243, v25
	v_fmac_f32_e32 v153, v245, v72
	v_fmac_f32_e32 v152, v247, v73
	v_fmac_f32_e32 v139, v241, v26
	v_fmac_f32_e32 v138, v243, v27
	v_fmac_f32_e32 v155, v245, v74
	v_fmac_f32_e32 v154, v247, v75
	v_fmac_f32_e32 v141, v241, v28
	v_fmac_f32_e32 v140, v243, v29
	v_fmac_f32_e32 v157, v245, v76
	v_fmac_f32_e32 v156, v247, v77
	v_fmac_f32_e32 v143, v241, v30
	v_fmac_f32_e32 v142, v243, v31
	v_fmac_f32_e32 v159, v245, v78
	v_fmac_f32_e32 v158, v247, v79
	v_fmac_f32_e32 v145, v241, v32
	v_fmac_f32_e32 v144, v243, v33
	v_fmac_f32_e32 v161, v245, v80
	v_fmac_f32_e32 v160, v247, v81
	v_permlane32_swap_b32_e32 v18, v21
	v_permlane32_swap_b32_e32 v22, v25
	v_permlane32_swap_b32_e32 v26, v29
	v_permlane32_swap_b32_e32 v30, v33
	v_permlane32_swap_b32_e32 v66, v69
	v_permlane32_swap_b32_e32 v70, v73
	v_permlane32_swap_b32_e32 v74, v77
	v_permlane32_swap_b32_e32 v78, v81
	v_permlane32_swap_b32_e32 v21, v22
	v_permlane32_swap_b32_e32 v25, v26
	v_permlane32_swap_b32_e32 v29, v30
	v_permlane32_swap_b32_e32 v69, v70
; DI int crow(int i, int h) { return (i & 3) + 8 * (i >> 2) + 4 * h; }
;   DI void operator()(f32x16 (&acc)[2][4], int wm, int wn, int r, int h) {
;     ...
; #pragma unroll
;     for (int ig = 0; ig < 4; ++ig)
; #pragma unroll
;       for (int qp = 0; qp < 2; ++qp) {
;         const int i0 = ig * 4 + qp * 2;
;         float u[2][4][2];
; #pragma unroll
;         for (int nb = 0; nb < 2; ++nb) {
;           int xp[4];
; #pragma unroll
;           for (int mb = 0; mb < 4; ++mb) xp[mb] = (int)pack2(acc[nb][mb][i0], acc[nb][mb][i0 + 1]);
;           const float eo0 = ob[nb * 32 + crow(i0, h)], eo1 = ob[nb * 32 + crow(i0 + 1, h)];
;           float w0[2], w1[2], w2[2], bz[2];
;           {
;             const int ff = nt * 128 + wn * 32 + crow(i0, h) + nb * DFF;
;             const f32x2n a0 = *(const f32x2n*)(cw + ff), a1 = *(const f32x2n*)(cw + 2 * DFF + ff), a2 = *(const f32x2n*)(cw + 4 * DFF + ff),
;                          a3 = *(const f32x2n*)(cb + ff);
;             w0[0] = a0.x; w0[1] = a0.y; w1[0] = a1.x; w1[1] = a1.y; w2[0] = a2.x; w2[1] = a2.y; bz[0] = a3.x; bz[1] = a3.y;
;           }
;           int spm = 0;
; #pragma unroll
;           for (int mb = 0; mb < 4; ++mb) {
;             const int spc = __builtin_amdgcn_ds_bpermute(sp << 2, xp[mb]);
;             const int snc = __builtin_amdgcn_ds_bpermute(sn << 2, xp[mb]);
;             const int snn = (mb < 3) ? __builtin_amdgcn_ds_bpermute(sn << 2, xp[mb < 3 ? mb + 1 : 3]) : 0;
;             const int pv = (mb > 0) ? ((r == 0) ? spm : spc) : spc;
;             const int nv = (mb < 3) ? ((r == 31) ? snn : snc) : snc;
;             float prev0 = __int_as_float(pv << 16), prev1 = __int_as_float(pv & 0xffff0000);
;             float next0 = __int_as_float(nv << 16), next1 = __int_as_float(nv & 0xffff0000);
;             if (mb == 0 && r == 0) { prev0 = eo0; prev1 = eo1; }
;             if (mb == 3 && r == 31) { next0 = eo0; next1 = eo1; }
;             spm = spc;
;             prev0 *= pm[mb]; prev1 *= pm[mb];
;             next0 *= nm[mb]; next1 *= nm[mb];
;             u[nb][mb][0] = w0[0] * prev0 + w1[0] * acc[nb][mb][i0] + w2[0] * next0 + bz[0];
;             u[nb][mb][1] = w0[1] * prev1 + w1[1] * acc[nb][mb][i0 + 1] + w2[1] * next1 + bz[1];
;           }
;         }
; #pragma unroll
;         for (int mb = 0; mb < 4; ++mb)
;           *(unsigned*)(ost + (mb * 32 + r) * 40 + ig * 8 + h * 4 + qp * 2) =
	v_permlane32_swap_b32_e32 v73, v74
	v_permlane32_swap_b32_e32 v77, v78
	v_permlane32_swap_b32_e32 v33, v184
	v_permlane32_swap_b32_e32 v81, v185
	s_mov_b32 exec_hi, 0
	v_mov_b32_e32 v18, v186
	v_mov_b32_e32 v66, v187
	s_mov_b64 exec, -1
	v_fmac_f32_e32 v131, v243, v20
	v_fmac_f32_e32 v132, v241, v19
	v_fmac_f32_e32 v135, v243, v24
	v_fmac_f32_e32 v136, v241, v23
	v_fmac_f32_e32 v139, v243, v28
	v_fmac_f32_e32 v140, v241, v27
	v_fmac_f32_e32 v143, v243, v32
	v_fmac_f32_e32 v144, v241, v31
	v_fmac_f32_e32 v147, v247, v68
	v_fmac_f32_e32 v148, v245, v67
	v_fmac_f32_e32 v151, v247, v72
	v_fmac_f32_e32 v152, v245, v71
	v_fmac_f32_e32 v155, v247, v76
	v_fmac_f32_e32 v156, v245, v75
	v_fmac_f32_e32 v159, v247, v80
	v_fmac_f32_e32 v160, v245, v79
	v_fmac_f32_e32 v130, v241, v18
	v_fmac_f32_e32 v133, v243, v21
	v_fmac_f32_e32 v134, v241, v22
	v_fmac_f32_e32 v137, v243, v25
	v_fmac_f32_e32 v138, v241, v26
	v_fmac_f32_e32 v141, v243, v29
	v_fmac_f32_e32 v142, v241, v30
	v_fmac_f32_e32 v145, v243, v33
	v_fmac_f32_e32 v146, v245, v66
	v_fmac_f32_e32 v149, v247, v69
	v_fmac_f32_e32 v150, v245, v70
	v_fmac_f32_e32 v153, v247, v73
	v_fmac_f32_e32 v154, v245, v74
	v_fmac_f32_e32 v157, v247, v77
	v_fmac_f32_e32 v158, v245, v78
	v_fmac_f32_e32 v161, v247, v81
	v_pk_mul_f32 v[188:189], v[146:147], v[146:147]
	v_pk_mul_f32 v[190:191], v[148:149], v[148:149]
	v_pk_mul_f32 v[192:193], v[150:151], v[150:151]
	v_pk_mul_f32 v[194:195], v[152:153], v[152:153]
	v_pk_mul_f32 v[196:197], v[154:155], v[154:155]
	v_pk_mul_f32 v[218:219], v[156:157], v[156:157]
	v_pk_mul_f32 v[220:221], v[158:159], v[158:159]
	v_pk_mul_f32 v[222:223], v[160:161], v[160:161]
	v_pk_fma_f32 v[188:189], v[188:189], v[178:179], v[180:181] op_sel_hi:[1,0,0]
	v_pk_fma_f32 v[190:191], v[190:191], v[178:179], v[180:181] op_sel_hi:[1,0,0]
	v_pk_fma_f32 v[192:193], v[192:193], v[178:179], v[180:181] op_sel_hi:[1,0,0]
	v_pk_fma_f32 v[194:195], v[194:195], v[178:179], v[180:181] op_sel_hi:[1,0,0]
	v_pk_fma_f32 v[196:197], v[196:197], v[178:179], v[180:181] op_sel_hi:[1,0,0]
	v_pk_fma_f32 v[218:219], v[218:219], v[178:179], v[180:181] op_sel_hi:[1,0,0]
	v_pk_fma_f32 v[220:221], v[220:221], v[178:179], v[180:181] op_sel_hi:[1,0,0]
	v_pk_fma_f32 v[222:223], v[222:223], v[178:179], v[180:181] op_sel_hi:[1,0,0]
	v_pk_mul_f32 v[188:189], v[146:147], v[188:189]
	v_pk_mul_f32 v[190:191], v[148:149], v[190:191]
	v_pk_mul_f32 v[192:193], v[150:151], v[192:193]
	v_pk_mul_f32 v[194:195], v[152:153], v[194:195]
	v_pk_mul_f32 v[196:197], v[154:155], v[196:197]
	v_pk_mul_f32 v[218:219], v[156:157], v[218:219]
	v_pk_mul_f32 v[220:221], v[158:159], v[220:221]
	v_pk_mul_f32 v[222:223], v[160:161], v[222:223]
	v_exp_f32_e32 v188, v188
	v_exp_f32_e32 v189, v189
	v_exp_f32_e32 v190, v190
	v_exp_f32_e32 v191, v191
	v_exp_f32_e32 v192, v192
	v_exp_f32_e32 v193, v193
	v_exp_f32_e32 v194, v194
	v_exp_f32_e32 v195, v195
	v_exp_f32_e32 v196, v196
	v_exp_f32_e32 v197, v197
	v_exp_f32_e32 v218, v218
	v_exp_f32_e32 v219, v219
	v_exp_f32_e32 v220, v220
	v_exp_f32_e32 v221, v221
	v_exp_f32_e32 v222, v222
	v_exp_f32_e32 v223, v223
	v_pk_add_f32 v[188:189], v[188:189], v[182:183] op_sel_hi:[1,0]
	v_pk_add_f32 v[190:191], v[190:191], v[182:183] op_sel_hi:[1,0]
	v_pk_add_f32 v[192:193], v[192:193], v[182:183] op_sel_hi:[1,0]
	v_pk_add_f32 v[194:195], v[194:195], v[182:183] op_sel_hi:[1,0]
	v_pk_add_f32 v[196:197], v[196:197], v[182:183] op_sel_hi:[1,0]
	v_pk_add_f32 v[218:219], v[218:219], v[182:183] op_sel_hi:[1,0]
	v_pk_add_f32 v[220:221], v[220:221], v[182:183] op_sel_hi:[1,0]
	v_pk_add_f32 v[222:223], v[222:223], v[182:183] op_sel_hi:[1,0]
	v_rcp_f32_e32 v188, v188
	v_rcp_f32_e32 v189, v189
	v_rcp_f32_e32 v190, v190
	v_rcp_f32_e32 v191, v191
	v_rcp_f32_e32 v192, v192
	v_rcp_f32_e32 v193, v193
	v_rcp_f32_e32 v194, v194
	v_rcp_f32_e32 v195, v195
	v_rcp_f32_e32 v196, v196
	v_rcp_f32_e32 v197, v197
	v_rcp_f32_e32 v218, v218
	v_rcp_f32_e32 v219, v219
	v_rcp_f32_e32 v220, v220
	v_rcp_f32_e32 v221, v221
	v_rcp_f32_e32 v222, v222
	v_rcp_f32_e32 v223, v223
	v_pk_mul_f32 v[188:189], v[146:147], v[188:189]
	v_pk_mul_f32 v[190:191], v[148:149], v[190:191]
	v_pk_mul_f32 v[192:193], v[150:151], v[192:193]
	v_pk_mul_f32 v[194:195], v[152:153], v[194:195]
	v_pk_mul_f32 v[196:197], v[154:155], v[196:197]
	v_pk_mul_f32 v[218:219], v[156:157], v[218:219]
	v_pk_mul_f32 v[220:221], v[158:159], v[220:221]
	v_pk_mul_f32 v[222:223], v[160:161], v[222:223]
	v_pk_mul_f32 v[188:189], v[188:189], v[130:131]
	v_pk_mul_f32 v[190:191], v[190:191], v[132:133]
	v_pk_mul_f32 v[192:193], v[192:193], v[134:135]
	v_pk_mul_f32 v[194:195], v[194:195], v[136:137]
	v_pk_mul_f32 v[196:197], v[196:197], v[138:139]
	v_pk_mul_f32 v[218:219], v[218:219], v[140:141]
	v_pk_mul_f32 v[220:221], v[220:221], v[142:143]
	v_pk_mul_f32 v[222:223], v[222:223], v[144:145]
	v_cvt_pk_bf16_f32 v188, v188, v189
	v_cvt_pk_bf16_f32 v190, v190, v191
	v_cvt_pk_bf16_f32 v192, v192, v193
	v_cvt_pk_bf16_f32 v194, v194, v195
	v_cvt_pk_bf16_f32 v196, v196, v197
	v_cvt_pk_bf16_f32 v218, v218, v219
	v_cvt_pk_bf16_f32 v220, v220, v221
	v_cvt_pk_bf16_f32 v222, v222, v223
	ds_write_b16 v224, v188 offset:4096
	ds_write_b16_d16_hi v237, v188 offset:4160
	ds_write_b16 v224, v190 offset:4224
	ds_write_b16_d16_hi v237, v190 offset:4288
	ds_write_b16 v224, v192 offset:4608
	ds_write_b16_d16_hi v237, v192 offset:4672
	ds_write_b16 v224, v194 offset:4736
	ds_write_b16_d16_hi v237, v194 offset:4800
	ds_write_b16 v224, v196 offset:5120
	ds_write_b16_d16_hi v237, v196 offset:5184
	ds_write_b16 v224, v218 offset:5248
	ds_write_b16_d16_hi v237, v218 offset:5312
	ds_write_b16 v224, v220 offset:5632
; DI int crow(int i, int h) { return (i & 3) + 8 * (i >> 2) + 4 * h; }
;   DI void operator()(f32x16 (&acc)[2][4], int wm, int wn, int r, int h) {
;     ...
; #pragma unroll
;     for (int ig = 0; ig < 4; ++ig)
; #pragma unroll
;       for (int qp = 0; qp < 2; ++qp) {
;         const int i0 = ig * 4 + qp * 2;
;         float u[2][4][2];
; #pragma unroll
;         for (int nb = 0; nb < 2; ++nb) {
;           int xp[4];
; #pragma unroll
;           for (int mb = 0; mb < 4; ++mb) xp[mb] = (int)pack2(acc[nb][mb][i0], acc[nb][mb][i0 + 1]);
;           const float eo0 = ob[nb * 32 + crow(i0, h)], eo1 = ob[nb * 32 + crow(i0 + 1, h)];
;           float w0[2], w1[2], w2[2], bz[2];
;           {
;             const int ff = nt * 128 + wn * 32 + crow(i0, h) + nb * DFF;
;             const f32x2n a0 = *(const f32x2n*)(cw + ff), a1 = *(const f32x2n*)(cw + 2 * DFF + ff), a2 = *(const f32x2n*)(cw + 4 * DFF + ff),
;                          a3 = *(const f32x2n*)(cb + ff);
;             w0[0] = a0.x; w0[1] = a0.y; w1[0] = a1.x; w1[1] = a1.y; w2[0] = a2.x; w2[1] = a2.y; bz[0] = a3.x; bz[1] = a3.y;
;           }
;           int spm = 0;
; #pragma unroll
;           for (int mb = 0; mb < 4; ++mb) {
;             const int spc = __builtin_amdgcn_ds_bpermute(sp << 2, xp[mb]);
;             const int snc = __builtin_amdgcn_ds_bpermute(sn << 2, xp[mb]);
;             const int snn = (mb < 3) ? __builtin_amdgcn_ds_bpermute(sn << 2, xp[mb < 3 ? mb + 1 : 3]) : 0;
;             const int pv = (mb > 0) ? ((r == 0) ? spm : spc) : spc;
;             const int nv = (mb < 3) ? ((r == 31) ? snn : snc) : snc;
;             float prev0 = __int_as_float(pv << 16), prev1 = __int_as_float(pv & 0xffff0000);
;             float next0 = __int_as_float(nv << 16), next1 = __int_as_float(nv & 0xffff0000);
;             if (mb == 0 && r == 0) { prev0 = eo0; prev1 = eo1; }
;             if (mb == 3 && r == 31) { next0 = eo0; next1 = eo1; }
;             spm = spc;
;             prev0 *= pm[mb]; prev1 *= pm[mb];
;             next0 *= nm[mb]; next1 *= nm[mb];
;             u[nb][mb][0] = w0[0] * prev0 + w1[0] * acc[nb][mb][i0] + w2[0] * next0 + bz[0];
;             u[nb][mb][1] = w0[1] * prev1 + w1[1] * acc[nb][mb][i0 + 1] + w2[1] * next1 + bz[1];
;           }
;         }
; #pragma unroll
;         for (int mb = 0; mb < 4; ++mb)
;           *(unsigned*)(ost + (mb * 32 + r) * 40 + ig * 8 + h * 4 + qp * 2) =
	ds_write_b16_d16_hi v237, v220 offset:5696
	ds_write_b16 v224, v222 offset:5760
	ds_write_b16_d16_hi v237, v222 offset:5824
	v_pk_fma_f32 v[130:131], v[2:3], v[240:241], v[242:243] op_sel_hi:[1,0,0]
	v_pk_fma_f32 v[132:133], v[4:5], v[240:241], v[242:243] op_sel_hi:[1,0,0]
	v_pk_fma_f32 v[134:135], v[6:7], v[240:241], v[242:243] op_sel_hi:[1,0,0]
	v_pk_fma_f32 v[136:137], v[8:9], v[240:241], v[242:243] op_sel_hi:[1,0,0]
	v_pk_fma_f32 v[138:139], v[10:11], v[240:241], v[242:243] op_sel_hi:[1,0,0]
	v_pk_fma_f32 v[140:141], v[12:13], v[240:241], v[242:243] op_sel_hi:[1,0,0]
	v_pk_fma_f32 v[142:143], v[14:15], v[240:241], v[242:243] op_sel_hi:[1,0,0]
	v_pk_fma_f32 v[144:145], v[16:17], v[240:241], v[242:243] op_sel_hi:[1,0,0]
	v_pk_fma_f32 v[146:147], v[34:35], v[244:245], v[246:247] op_sel_hi:[1,0,0]
	v_pk_fma_f32 v[148:149], v[36:37], v[244:245], v[246:247] op_sel_hi:[1,0,0]
	v_pk_fma_f32 v[150:151], v[38:39], v[244:245], v[246:247] op_sel_hi:[1,0,0]
	v_pk_fma_f32 v[152:153], v[40:41], v[244:245], v[246:247] op_sel_hi:[1,0,0]
	v_pk_fma_f32 v[154:155], v[42:43], v[244:245], v[246:247] op_sel_hi:[1,0,0]
	v_pk_fma_f32 v[156:157], v[44:45], v[244:245], v[246:247] op_sel_hi:[1,0,0]
	v_pk_fma_f32 v[158:159], v[46:47], v[244:245], v[246:247] op_sel_hi:[1,0,0]
	v_pk_fma_f32 v[160:161], v[48:49], v[244:245], v[246:247] op_sel_hi:[1,0,0]
	v_fmac_f32_e32 v131, v241, v2
	v_fmac_f32_e32 v130, v243, v3
	v_fmac_f32_e32 v147, v245, v34
	v_fmac_f32_e32 v146, v247, v35
	v_fmac_f32_e32 v133, v241, v4
	v_fmac_f32_e32 v132, v243, v5
	v_fmac_f32_e32 v149, v245, v36
	v_fmac_f32_e32 v148, v247, v37
	v_fmac_f32_e32 v135, v241, v6
	v_fmac_f32_e32 v134, v243, v7
	v_fmac_f32_e32 v151, v245, v38
	v_fmac_f32_e32 v150, v247, v39
	v_fmac_f32_e32 v137, v241, v8
	v_fmac_f32_e32 v136, v243, v9
	v_fmac_f32_e32 v153, v245, v40
	v_fmac_f32_e32 v152, v247, v41
	v_fmac_f32_e32 v139, v241, v10
	v_fmac_f32_e32 v138, v243, v11
	v_fmac_f32_e32 v155, v245, v42
	v_fmac_f32_e32 v154, v247, v43
	v_fmac_f32_e32 v141, v241, v12
	v_fmac_f32_e32 v140, v243, v13
	v_fmac_f32_e32 v157, v245, v44
	v_fmac_f32_e32 v156, v247, v45
	v_fmac_f32_e32 v143, v241, v14
	v_fmac_f32_e32 v142, v243, v15
	v_fmac_f32_e32 v159, v245, v46
	v_fmac_f32_e32 v158, v247, v47
	v_fmac_f32_e32 v145, v241, v16
	v_fmac_f32_e32 v144, v243, v17
	v_fmac_f32_e32 v161, v245, v48
	v_fmac_f32_e32 v160, v247, v49
	v_permlane32_swap_b32_e32 v2, v5
	v_permlane32_swap_b32_e32 v6, v9
	v_permlane32_swap_b32_e32 v10, v13
	v_permlane32_swap_b32_e32 v14, v17
	v_permlane32_swap_b32_e32 v34, v37
	v_permlane32_swap_b32_e32 v38, v41
	v_permlane32_swap_b32_e32 v42, v45
	v_permlane32_swap_b32_e32 v46, v49
	v_permlane32_swap_b32_e32 v5, v6
	v_permlane32_swap_b32_e32 v9, v10
	v_permlane32_swap_b32_e32 v13, v14
	v_permlane32_swap_b32_e32 v37, v38
	v_permlane32_swap_b32_e32 v41, v42
	v_permlane32_swap_b32_e32 v45, v46
	s_mov_b32 exec_lo, 0
	ds_read_b32 v17, v226 offset:0
	ds_read_b32 v49, v226 offset:128
	s_mov_b64 exec, -1
	s_mov_b32 exec_hi, 0
	v_mov_b32_e32 v2, v184
	v_mov_b32_e32 v34, v185
	s_mov_b64 exec, -1
	v_fmac_f32_e32 v131, v243, v4
	v_fmac_f32_e32 v132, v241, v3
	v_fmac_f32_e32 v135, v243, v8
	v_fmac_f32_e32 v136, v241, v7
	v_fmac_f32_e32 v139, v243, v12
	v_fmac_f32_e32 v140, v241, v11
	v_fmac_f32_e32 v143, v243, v16
	v_fmac_f32_e32 v144, v241, v15
	v_fmac_f32_e32 v147, v247, v36
	v_fmac_f32_e32 v148, v245, v35
	v_fmac_f32_e32 v151, v247, v40
	v_fmac_f32_e32 v152, v245, v39
	v_fmac_f32_e32 v155, v247, v44
	v_fmac_f32_e32 v156, v245, v43
	v_fmac_f32_e32 v159, v247, v48
	v_fmac_f32_e32 v160, v245, v47
	s_waitcnt lgkmcnt(0)
	v_fmac_f32_e32 v130, v241, v2
	v_fmac_f32_e32 v133, v243, v5
	v_fmac_f32_e32 v134, v241, v6
	v_fmac_f32_e32 v137, v243, v9
	v_fmac_f32_e32 v138, v241, v10
	v_fmac_f32_e32 v141, v243, v13
	v_fmac_f32_e32 v142, v241, v14
	v_fmac_f32_e32 v145, v243, v17
	v_fmac_f32_e32 v146, v245, v34
	v_fmac_f32_e32 v149, v247, v37
	v_fmac_f32_e32 v150, v245, v38
	v_fmac_f32_e32 v153, v247, v41
	v_fmac_f32_e32 v154, v245, v42
	v_fmac_f32_e32 v157, v247, v45
	v_fmac_f32_e32 v158, v245, v46
	v_fmac_f32_e32 v161, v247, v49
	v_pk_mul_f32 v[188:189], v[146:147], v[146:147]
	v_pk_mul_f32 v[190:191], v[148:149], v[148:149]
	v_pk_mul_f32 v[192:193], v[150:151], v[150:151]
	v_pk_mul_f32 v[194:195], v[152:153], v[152:153]
	v_pk_mul_f32 v[196:197], v[154:155], v[154:155]
	v_pk_mul_f32 v[218:219], v[156:157], v[156:157]
	v_pk_mul_f32 v[220:221], v[158:159], v[158:159]
	v_pk_mul_f32 v[222:223], v[160:161], v[160:161]
	v_pk_fma_f32 v[188:189], v[188:189], v[178:179], v[180:181] op_sel_hi:[1,0,0]
	v_pk_fma_f32 v[190:191], v[190:191], v[178:179], v[180:181] op_sel_hi:[1,0,0]
	v_pk_fma_f32 v[192:193], v[192:193], v[178:179], v[180:181] op_sel_hi:[1,0,0]
	v_pk_fma_f32 v[194:195], v[194:195], v[178:179], v[180:181] op_sel_hi:[1,0,0]
	v_pk_fma_f32 v[196:197], v[196:197], v[178:179], v[180:181] op_sel_hi:[1,0,0]
	v_pk_fma_f32 v[218:219], v[218:219], v[178:179], v[180:181] op_sel_hi:[1,0,0]
	v_pk_fma_f32 v[220:221], v[220:221], v[178:179], v[180:181] op_sel_hi:[1,0,0]
	v_pk_fma_f32 v[222:223], v[222:223], v[178:179], v[180:181] op_sel_hi:[1,0,0]
	v_pk_mul_f32 v[188:189], v[146:147], v[188:189]
	v_pk_mul_f32 v[190:191], v[148:149], v[190:191]
	v_pk_mul_f32 v[192:193], v[150:151], v[192:193]
	v_pk_mul_f32 v[194:195], v[152:153], v[194:195]
	v_pk_mul_f32 v[196:197], v[154:155], v[196:197]
	v_pk_mul_f32 v[218:219], v[156:157], v[218:219]
	v_pk_mul_f32 v[220:221], v[158:159], v[220:221]
	v_pk_mul_f32 v[222:223], v[160:161], v[222:223]
	v_exp_f32_e32 v188, v188
	v_exp_f32_e32 v189, v189
	v_exp_f32_e32 v190, v190
	v_exp_f32_e32 v191, v191
	v_exp_f32_e32 v192, v192
; DI int crow(int i, int h) { return (i & 3) + 8 * (i >> 2) + 4 * h; }
;   DI void operator()(f32x16 (&acc)[2][4], int wm, int wn, int r, int h) {
;     ...
; #pragma unroll
;     for (int ig = 0; ig < 4; ++ig)
; #pragma unroll
;       for (int qp = 0; qp < 2; ++qp) {
;         const int i0 = ig * 4 + qp * 2;
;         float u[2][4][2];
; #pragma unroll
;         for (int nb = 0; nb < 2; ++nb) {
;           int xp[4];
; #pragma unroll
;           for (int mb = 0; mb < 4; ++mb) xp[mb] = (int)pack2(acc[nb][mb][i0], acc[nb][mb][i0 + 1]);
;           const float eo0 = ob[nb * 32 + crow(i0, h)], eo1 = ob[nb * 32 + crow(i0 + 1, h)];
;           float w0[2], w1[2], w2[2], bz[2];
;           {
;             const int ff = nt * 128 + wn * 32 + crow(i0, h) + nb * DFF;
;             const f32x2n a0 = *(const f32x2n*)(cw + ff), a1 = *(const f32x2n*)(cw + 2 * DFF + ff), a2 = *(const f32x2n*)(cw + 4 * DFF + ff),
;                          a3 = *(const f32x2n*)(cb + ff);
;             w0[0] = a0.x; w0[1] = a0.y; w1[0] = a1.x; w1[1] = a1.y; w2[0] = a2.x; w2[1] = a2.y; bz[0] = a3.x; bz[1] = a3.y;
;           }
;           int spm = 0;
; #pragma unroll
;           for (int mb = 0; mb < 4; ++mb) {
;             const int spc = __builtin_amdgcn_ds_bpermute(sp << 2, xp[mb]);
;             const int snc = __builtin_amdgcn_ds_bpermute(sn << 2, xp[mb]);
;             const int snn = (mb < 3) ? __builtin_amdgcn_ds_bpermute(sn << 2, xp[mb < 3 ? mb + 1 : 3]) : 0;
;             const int pv = (mb > 0) ? ((r == 0) ? spm : spc) : spc;
;             const int nv = (mb < 3) ? ((r == 31) ? snn : snc) : snc;
;             float prev0 = __int_as_float(pv << 16), prev1 = __int_as_float(pv & 0xffff0000);
;             float next0 = __int_as_float(nv << 16), next1 = __int_as_float(nv & 0xffff0000);
;             if (mb == 0 && r == 0) { prev0 = eo0; prev1 = eo1; }
;             if (mb == 3 && r == 31) { next0 = eo0; next1 = eo1; }
;             spm = spc;
;             prev0 *= pm[mb]; prev1 *= pm[mb];
;             next0 *= nm[mb]; next1 *= nm[mb];
;             u[nb][mb][0] = w0[0] * prev0 + w1[0] * acc[nb][mb][i0] + w2[0] * next0 + bz[0];
;             u[nb][mb][1] = w0[1] * prev1 + w1[1] * acc[nb][mb][i0 + 1] + w2[1] * next1 + bz[1];
;           }
;         }
; #pragma unroll
;         for (int mb = 0; mb < 4; ++mb)
;           *(unsigned*)(ost + (mb * 32 + r) * 40 + ig * 8 + h * 4 + qp * 2) =
	v_exp_f32_e32 v193, v193
	v_exp_f32_e32 v194, v194
	v_exp_f32_e32 v195, v195
	v_exp_f32_e32 v196, v196
	v_exp_f32_e32 v197, v197
	v_exp_f32_e32 v218, v218
	v_exp_f32_e32 v219, v219
	v_exp_f32_e32 v220, v220
	v_exp_f32_e32 v221, v221
	v_exp_f32_e32 v222, v222
	v_exp_f32_e32 v223, v223
	v_pk_add_f32 v[188:189], v[188:189], v[182:183] op_sel_hi:[1,0]
	v_pk_add_f32 v[190:191], v[190:191], v[182:183] op_sel_hi:[1,0]
	v_pk_add_f32 v[192:193], v[192:193], v[182:183] op_sel_hi:[1,0]
	v_pk_add_f32 v[194:195], v[194:195], v[182:183] op_sel_hi:[1,0]
	v_pk_add_f32 v[196:197], v[196:197], v[182:183] op_sel_hi:[1,0]
	v_pk_add_f32 v[218:219], v[218:219], v[182:183] op_sel_hi:[1,0]
	v_pk_add_f32 v[220:221], v[220:221], v[182:183] op_sel_hi:[1,0]
	v_pk_add_f32 v[222:223], v[222:223], v[182:183] op_sel_hi:[1,0]
	v_rcp_f32_e32 v188, v188
	v_rcp_f32_e32 v189, v189
	v_rcp_f32_e32 v190, v190
	v_rcp_f32_e32 v191, v191
	v_rcp_f32_e32 v192, v192
	v_rcp_f32_e32 v193, v193
	v_rcp_f32_e32 v194, v194
	v_rcp_f32_e32 v195, v195
	v_rcp_f32_e32 v196, v196
	v_rcp_f32_e32 v197, v197
	v_rcp_f32_e32 v218, v218
	v_rcp_f32_e32 v219, v219
	v_rcp_f32_e32 v220, v220
	v_rcp_f32_e32 v221, v221
	v_rcp_f32_e32 v222, v222
	v_rcp_f32_e32 v223, v223
	v_pk_mul_f32 v[188:189], v[146:147], v[188:189]
	v_pk_mul_f32 v[190:191], v[148:149], v[190:191]
	v_pk_mul_f32 v[192:193], v[150:151], v[192:193]
	v_pk_mul_f32 v[194:195], v[152:153], v[194:195]
	v_pk_mul_f32 v[196:197], v[154:155], v[196:197]
	v_pk_mul_f32 v[218:219], v[156:157], v[218:219]
	v_pk_mul_f32 v[220:221], v[158:159], v[220:221]
	v_pk_mul_f32 v[222:223], v[160:161], v[222:223]
	v_pk_mul_f32 v[188:189], v[188:189], v[130:131]
	v_pk_mul_f32 v[190:191], v[190:191], v[132:133]
	v_pk_mul_f32 v[192:193], v[192:193], v[134:135]
	v_pk_mul_f32 v[194:195], v[194:195], v[136:137]
	v_pk_mul_f32 v[196:197], v[196:197], v[138:139]
	v_pk_mul_f32 v[218:219], v[218:219], v[140:141]
	v_pk_mul_f32 v[220:221], v[220:221], v[142:143]
	v_pk_mul_f32 v[222:223], v[222:223], v[144:145]
	v_cvt_pk_bf16_f32 v188, v188, v189
	v_cvt_pk_bf16_f32 v190, v190, v191
	v_cvt_pk_bf16_f32 v192, v192, v193
	v_cvt_pk_bf16_f32 v194, v194, v195
	v_cvt_pk_bf16_f32 v196, v196, v197
	v_cvt_pk_bf16_f32 v218, v218, v219
	v_cvt_pk_bf16_f32 v220, v220, v221
	v_cvt_pk_bf16_f32 v222, v222, v223
	ds_write_b16 v224, v188 offset:6144
	ds_write_b16_d16_hi v237, v188 offset:6208
	ds_write_b16 v224, v190 offset:6272
	ds_write_b16_d16_hi v237, v190 offset:6336
	ds_write_b16 v224, v192 offset:6656
	ds_write_b16_d16_hi v237, v192 offset:6720
	ds_write_b16 v224, v194 offset:6784
	ds_write_b16_d16_hi v237, v194 offset:6848
	ds_write_b16 v224, v196 offset:7168
	ds_write_b16_d16_hi v237, v196 offset:7232
	ds_write_b16 v224, v218 offset:7296
	ds_write_b16_d16_hi v237, v218 offset:7360
	ds_write_b16 v224, v220 offset:7680
	ds_write_b16_d16_hi v237, v220 offset:7744
	ds_write_b16 v224, v222 offset:7808
	ds_write_b16_d16_hi v237, v222 offset:7872
	s_branch .Lupe_done
.Lupe_slow:
	v_mov_b32_e32 v184, v50
	v_mov_b32_e32 v185, v82
	v_pk_fma_f32 v[130:131], v[98:99], v[240:241], v[242:243] op_sel_hi:[1,0,0]
	v_pk_fma_f32 v[132:133], v[100:101], v[240:241], v[242:243] op_sel_hi:[1,0,0]
	v_pk_fma_f32 v[134:135], v[102:103], v[240:241], v[242:243] op_sel_hi:[1,0,0]
	v_pk_fma_f32 v[136:137], v[104:105], v[240:241], v[242:243] op_sel_hi:[1,0,0]
	v_pk_fma_f32 v[138:139], v[106:107], v[240:241], v[242:243] op_sel_hi:[1,0,0]
	v_pk_fma_f32 v[140:141], v[108:109], v[240:241], v[242:243] op_sel_hi:[1,0,0]
	v_pk_fma_f32 v[142:143], v[110:111], v[240:241], v[242:243] op_sel_hi:[1,0,0]
	v_pk_fma_f32 v[144:145], v[112:113], v[240:241], v[242:243] op_sel_hi:[1,0,0]
	v_pk_fma_f32 v[146:147], v[114:115], v[244:245], v[246:247] op_sel_hi:[1,0,0]
	v_pk_fma_f32 v[148:149], v[116:117], v[244:245], v[246:247] op_sel_hi:[1,0,0]
	v_pk_fma_f32 v[150:151], v[118:119], v[244:245], v[246:247] op_sel_hi:[1,0,0]
	v_pk_fma_f32 v[152:153], v[120:121], v[244:245], v[246:247] op_sel_hi:[1,0,0]
	v_pk_fma_f32 v[154:155], v[122:123], v[244:245], v[246:247] op_sel_hi:[1,0,0]
	v_pk_fma_f32 v[156:157], v[124:125], v[244:245], v[246:247] op_sel_hi:[1,0,0]
	v_pk_fma_f32 v[158:159], v[126:127], v[244:245], v[246:247] op_sel_hi:[1,0,0]
	v_pk_fma_f32 v[160:161], v[128:129], v[244:245], v[246:247] op_sel_hi:[1,0,0]
	s_cmp_eq_u32 s36, 0
	s_cselect_b64 exec, s[38:39], -1
	v_fmac_f32_e32 v131, v241, v98
	v_fmac_f32_e32 v130, v243, v99
	v_fmac_f32_e32 v147, v245, v114
	v_fmac_f32_e32 v146, v247, v115
	s_cmp_eq_u32 s36, 1
	s_cselect_b64 exec, s[38:39], -1
	v_fmac_f32_e32 v133, v241, v100
	v_fmac_f32_e32 v132, v243, v101
	v_fmac_f32_e32 v149, v245, v116
	v_fmac_f32_e32 v148, v247, v117
	s_cmp_eq_u32 s36, 2
	s_cselect_b64 exec, s[38:39], -1
	v_fmac_f32_e32 v135, v241, v102
	v_fmac_f32_e32 v134, v243, v103
	v_fmac_f32_e32 v151, v245, v118
	v_fmac_f32_e32 v150, v247, v119
	s_cmp_eq_u32 s36, 3
	s_cselect_b64 exec, s[38:39], -1
	v_fmac_f32_e32 v137, v241, v104
	v_fmac_f32_e32 v136, v243, v105
	v_fmac_f32_e32 v153, v245, v120
	v_fmac_f32_e32 v152, v247, v121
	s_cmp_eq_u32 s36, 4
	s_cselect_b64 exec, s[38:39], -1
	v_fmac_f32_e32 v139, v241, v106
	v_fmac_f32_e32 v138, v243, v107
	v_fmac_f32_e32 v155, v245, v122
	v_fmac_f32_e32 v154, v247, v123
	s_cmp_eq_u32 s36, 5
	s_cselect_b64 exec, s[38:39], -1
	v_fmac_f32_e32 v141, v241, v108
	v_fmac_f32_e32 v140, v243, v109
	v_fmac_f32_e32 v157, v245, v124
	v_fmac_f32_e32 v156, v247, v125
	s_cmp_eq_u32 s36, 6
	s_cselect_b64 exec, s[38:39], -1
	v_fmac_f32_e32 v143, v241, v110
	v_fmac_f32_e32 v142, v243, v111
	v_fmac_f32_e32 v159, v245, v126
	v_fmac_f32_e32 v158, v247, v127
	s_cmp_eq_u32 s36, 7
	s_cselect_b64 exec, s[38:39], -1
	v_fmac_f32_e32 v145, v241, v112
	v_fmac_f32_e32 v144, v243, v113
	v_fmac_f32_e32 v161, v245, v128
	v_fmac_f32_e32 v160, v247, v129
	s_mov_b64 exec, -1
	s_nop 1
	v_permlane32_swap_b32_e32 v98, v101
	v_permlane32_swap_b32_e32 v102, v105
	v_permlane32_swap_b32_e32 v106, v109
	v_permlane32_swap_b32_e32 v110, v113
	v_permlane32_swap_b32_e32 v114, v117
	v_permlane32_swap_b32_e32 v118, v121
	v_permlane32_swap_b32_e32 v122, v125
	v_permlane32_swap_b32_e32 v126, v129
	v_permlane32_swap_b32_e32 v101, v102
	v_permlane32_swap_b32_e32 v105, v106
	v_permlane32_swap_b32_e32 v109, v110
	v_permlane32_swap_b32_e32 v117, v118
	v_permlane32_swap_b32_e32 v121, v122
	v_permlane32_swap_b32_e32 v125, v126
	v_permlane32_swap_b32_e32 v113, v184
	v_permlane32_swap_b32_e32 v129, v185
	s_waitcnt lgkmcnt(0)
	s_barrier
	s_mov_b32 s101, 0
	s_mov_b32 s2, s9

; DI unsigned pack2(float a, float b) { f2 v = {a, b}; bf2 r = __builtin_convertvector(v, bf2); return __builtin_bit_cast(unsigned, r); }
; DI int crow(int i, int h) { return (i & 3) + 8 * (i >> 2) + 4 * h; }
;   DI void operator()(f32x16 (&acc)[2][4], int wm, int wn, int r, int h) {
;     ...
;           const float eo0 = ob[nb * 32 + crow(i0, h)], eo1 = ob[nb * 32 + crow(i0 + 1, h)];
;           float w0[2], w1[2], w2[2], bz[2];
;           {
;             const int ff = nt * 128 + wn * 32 + crow(i0, h) + nb * DFF;
;             const f32x2n a0 = *(const f32x2n*)(cw + ff), a1 = *(const f32x2n*)(cw + 2 * DFF + ff), a2 = *(const f32x2n*)(cw + 4 * DFF + ff),
;                          a3 = *(const f32x2n*)(cb + ff);
;             w0[0] = a0.x; w0[1] = a0.y; w1[0] = a1.x; w1[1] = a1.y; w2[0] = a2.x; w2[1] = a2.y; bz[0] = a3.x; bz[1] = a3.y;
;           }
;           int spm = 0;
; #pragma unroll
;           for (int mb = 0; mb < 4; ++mb) {
;             const int spc = __builtin_amdgcn_ds_bpermute(sp << 2, xp[mb]);
;             const int snc = __builtin_amdgcn_ds_bpermute(sn << 2, xp[mb]);
;             const int snn = (mb < 3) ? __builtin_amdgcn_ds_bpermute(sn << 2, xp[mb < 3 ? mb + 1 : 3]) : 0;
;             const int pv = (mb > 0) ? ((r == 0) ? spm : spc) : spc;
;             const int nv = (mb < 3) ? ((r == 31) ? snn : snc) : snc;
;             float prev0 = __int_as_float(pv << 16), prev1 = __int_as_float(pv & 0xffff0000);
;             float next0 = __int_as_float(nv << 16), next1 = __int_as_float(nv & 0xffff0000);
;             if (mb == 0 && r == 0) { prev0 = eo0; prev1 = eo1; }
;             if (mb == 3 && r == 31) { next0 = eo0; next1 = eo1; }
;             spm = spc;
;             prev0 *= pm[mb]; prev1 *= pm[mb];
;             next0 *= nm[mb]; next1 *= nm[mb];
;             u[nb][mb][0] = w0[0] * prev0 + w1[0] * acc[nb][mb][i0] + w2[0] * next0 + bz[0];
;             u[nb][mb][1] = w0[1] * prev1 + w1[1] * acc[nb][mb][i0 + 1] + w2[1] * next1 + bz[1];
;           }
;         }
; #pragma unroll
;         for (int mb = 0; mb < 4; ++mb)
;           *(unsigned*)(ost + (mb * 32 + r) * 40 + ig * 8 + h * 4 + qp * 2) =
;               pack2(gelu_tanh(u[1][mb][0]) * u[0][mb][0], gelu_tanh(u[1][mb][1]) * u[0][mb][1]);
.Lupf_nones:
	s_mov_b32 exec_hi, 0
	ds_read_b32 v98, v226 offset:256
	ds_read_b32 v114, v226 offset:384
	s_mov_b64 exec, -1
	v_fmac_f32_e32 v131, v243, v100
	v_fmac_f32_e32 v132, v241, v99
	v_fmac_f32_e32 v135, v243, v104
	v_fmac_f32_e32 v136, v241, v103
	v_fmac_f32_e32 v139, v243, v108
	v_fmac_f32_e32 v140, v241, v107
	v_fmac_f32_e32 v143, v243, v112
	v_fmac_f32_e32 v144, v241, v111
	v_fmac_f32_e32 v147, v247, v116
	v_fmac_f32_e32 v148, v245, v115
	v_fmac_f32_e32 v151, v247, v120
	v_fmac_f32_e32 v152, v245, v119
	v_fmac_f32_e32 v155, v247, v124
	v_fmac_f32_e32 v156, v245, v123
	v_fmac_f32_e32 v159, v247, v128
	v_fmac_f32_e32 v160, v245, v127
	s_waitcnt lgkmcnt(0)
	v_fmac_f32_e32 v130, v241, v98
	v_fmac_f32_e32 v133, v243, v101
	v_fmac_f32_e32 v134, v241, v102
	v_fmac_f32_e32 v137, v243, v105
	v_fmac_f32_e32 v138, v241, v106
	v_fmac_f32_e32 v141, v243, v109
	v_fmac_f32_e32 v142, v241, v110
	v_fmac_f32_e32 v145, v243, v113
	v_fmac_f32_e32 v146, v245, v114
	v_fmac_f32_e32 v149, v247, v117
	v_fmac_f32_e32 v150, v245, v118
	v_fmac_f32_e32 v153, v247, v121
	v_fmac_f32_e32 v154, v245, v122
	v_fmac_f32_e32 v157, v247, v125
	v_fmac_f32_e32 v158, v245, v126
	v_fmac_f32_e32 v161, v247, v129
	v_pk_mul_f32 v[188:189], v[146:147], v[146:147]
	v_pk_mul_f32 v[190:191], v[148:149], v[148:149]
	v_pk_mul_f32 v[192:193], v[150:151], v[150:151]
	v_pk_mul_f32 v[194:195], v[152:153], v[152:153]
	v_pk_mul_f32 v[196:197], v[154:155], v[154:155]
	v_pk_mul_f32 v[218:219], v[156:157], v[156:157]
	v_pk_mul_f32 v[220:221], v[158:159], v[158:159]
	v_pk_mul_f32 v[222:223], v[160:161], v[160:161]
	v_pk_fma_f32 v[188:189], v[188:189], v[178:179], v[180:181] op_sel_hi:[1,0,0]
	v_pk_fma_f32 v[190:191], v[190:191], v[178:179], v[180:181] op_sel_hi:[1,0,0]
	v_pk_fma_f32 v[192:193], v[192:193], v[178:179], v[180:181] op_sel_hi:[1,0,0]
	v_pk_fma_f32 v[194:195], v[194:195], v[178:179], v[180:181] op_sel_hi:[1,0,0]
	v_pk_fma_f32 v[196:197], v[196:197], v[178:179], v[180:181] op_sel_hi:[1,0,0]
	v_pk_fma_f32 v[218:219], v[218:219], v[178:179], v[180:181] op_sel_hi:[1,0,0]
	v_pk_fma_f32 v[220:221], v[220:221], v[178:179], v[180:181] op_sel_hi:[1,0,0]
	v_pk_fma_f32 v[222:223], v[222:223], v[178:179], v[180:181] op_sel_hi:[1,0,0]
	v_pk_mul_f32 v[188:189], v[146:147], v[188:189]
	v_pk_mul_f32 v[190:191], v[148:149], v[190:191]
	v_pk_mul_f32 v[192:193], v[150:151], v[192:193]
	v_pk_mul_f32 v[194:195], v[152:153], v[194:195]
	v_pk_mul_f32 v[196:197], v[154:155], v[196:197]
	v_pk_mul_f32 v[218:219], v[156:157], v[218:219]
	v_pk_mul_f32 v[220:221], v[158:159], v[220:221]
	v_pk_mul_f32 v[222:223], v[160:161], v[222:223]
	v_exp_f32_e32 v188, v188
	v_exp_f32_e32 v189, v189
	v_exp_f32_e32 v190, v190
	v_exp_f32_e32 v191, v191
	v_exp_f32_e32 v192, v192
	v_exp_f32_e32 v193, v193
	v_exp_f32_e32 v194, v194
	v_exp_f32_e32 v195, v195
	v_exp_f32_e32 v196, v196
	v_exp_f32_e32 v197, v197
	v_exp_f32_e32 v218, v218
	v_exp_f32_e32 v219, v219
	v_exp_f32_e32 v220, v220
	v_exp_f32_e32 v221, v221
	v_exp_f32_e32 v222, v222
	v_exp_f32_e32 v223, v223
	v_pk_add_f32 v[188:189], v[188:189], v[182:183] op_sel_hi:[1,0]
	v_pk_add_f32 v[190:191], v[190:191], v[182:183] op_sel_hi:[1,0]
	v_pk_add_f32 v[192:193], v[192:193], v[182:183] op_sel_hi:[1,0]
	v_pk_add_f32 v[194:195], v[194:195], v[182:183] op_sel_hi:[1,0]
	v_pk_add_f32 v[196:197], v[196:197], v[182:183] op_sel_hi:[1,0]
	v_pk_add_f32 v[218:219], v[218:219], v[182:183] op_sel_hi:[1,0]
	v_pk_add_f32 v[220:221], v[220:221], v[182:183] op_sel_hi:[1,0]
	v_pk_add_f32 v[222:223], v[222:223], v[182:183] op_sel_hi:[1,0]
	v_rcp_f32_e32 v188, v188
	v_rcp_f32_e32 v189, v189
	v_rcp_f32_e32 v190, v190
	v_rcp_f32_e32 v191, v191
	v_rcp_f32_e32 v192, v192
	v_rcp_f32_e32 v193, v193
	v_rcp_f32_e32 v194, v194
	v_rcp_f32_e32 v195, v195
	v_rcp_f32_e32 v196, v196
	v_rcp_f32_e32 v197, v197
	v_rcp_f32_e32 v218, v218
	v_rcp_f32_e32 v219, v219
	v_rcp_f32_e32 v220, v220
	v_rcp_f32_e32 v221, v221
	v_rcp_f32_e32 v222, v222
	v_rcp_f32_e32 v223, v223
	v_pk_mul_f32 v[188:189], v[146:147], v[188:189]
	v_pk_mul_f32 v[190:191], v[148:149], v[190:191]
	v_pk_mul_f32 v[192:193], v[150:151], v[192:193]
	v_pk_mul_f32 v[194:195], v[152:153], v[194:195]
	v_pk_mul_f32 v[196:197], v[154:155], v[196:197]
	v_pk_mul_f32 v[218:219], v[156:157], v[218:219]
	v_pk_mul_f32 v[220:221], v[158:159], v[220:221]
	v_pk_mul_f32 v[222:223], v[160:161], v[222:223]
	v_pk_mul_f32 v[188:189], v[188:189], v[130:131]
	v_pk_mul_f32 v[190:191], v[190:191], v[132:133]
	v_pk_mul_f32 v[192:193], v[192:193], v[134:135]
	v_pk_mul_f32 v[194:195], v[194:195], v[136:137]
	v_pk_mul_f32 v[196:197], v[196:197], v[138:139]
	v_pk_mul_f32 v[218:219], v[218:219], v[140:141]
	v_pk_mul_f32 v[220:221], v[220:221], v[142:143]
	v_pk_mul_f32 v[222:223], v[222:223], v[144:145]
	v_cvt_pk_bf16_f32 v188, v188, v189
	v_cvt_pk_bf16_f32 v190, v190, v191
	v_cvt_pk_bf16_f32 v192, v192, v193
	v_cvt_pk_bf16_f32 v194, v194, v195
	v_cvt_pk_bf16_f32 v196, v196, v197
	v_cvt_pk_bf16_f32 v218, v218, v219
	v_cvt_pk_bf16_f32 v220, v220, v221
	v_cvt_pk_bf16_f32 v222, v222, v223
	ds_write_b16 v224, v188 offset:0
	ds_write_b16_d16_hi v237, v188 offset:64
	ds_write_b16 v224, v190 offset:128
	ds_write_b16_d16_hi v237, v190 offset:192
	ds_write_b16 v224, v192 offset:512
	ds_write_b16_d16_hi v237, v192 offset:576
	ds_write_b16 v224, v194 offset:640
	ds_write_b16_d16_hi v237, v194 offset:704
	ds_write_b16 v224, v196 offset:1024
	ds_write_b16_d16_hi v237, v196 offset:1088
	ds_write_b16 v224, v218 offset:1152
	ds_write_b16_d16_hi v237, v218 offset:1216
	ds_write_b16 v224, v220 offset:1536
	ds_write_b16_d16_hi v237, v220 offset:1600
	ds_write_b16 v224, v222 offset:1664
; DI unsigned pack2(float a, float b) { f2 v = {a, b}; bf2 r = __builtin_convertvector(v, bf2); return __builtin_bit_cast(unsigned, r); }
; DI int crow(int i, int h) { return (i & 3) + 8 * (i >> 2) + 4 * h; }
;   DI void operator()(f32x16 (&acc)[2][4], int wm, int wn, int r, int h) {
;     ...
;         for (int nb = 0; nb < 2; ++nb) {
;           int xp[4];
; #pragma unroll
;           for (int mb = 0; mb < 4; ++mb) xp[mb] = (int)pack2(acc[nb][mb][i0], acc[nb][mb][i0 + 1]);
;           const float eo0 = ob[nb * 32 + crow(i0, h)], eo1 = ob[nb * 32 + crow(i0 + 1, h)];
;           float w0[2], w1[2], w2[2], bz[2];
;           {
;             const int ff = nt * 128 + wn * 32 + crow(i0, h) + nb * DFF;
;             const f32x2n a0 = *(const f32x2n*)(cw + ff), a1 = *(const f32x2n*)(cw + 2 * DFF + ff), a2 = *(const f32x2n*)(cw + 4 * DFF + ff),
;                          a3 = *(const f32x2n*)(cb + ff);
;             w0[0] = a0.x; w0[1] = a0.y; w1[0] = a1.x; w1[1] = a1.y; w2[0] = a2.x; w2[1] = a2.y; bz[0] = a3.x; bz[1] = a3.y;
;           }
;           int spm = 0;
; #pragma unroll
;           for (int mb = 0; mb < 4; ++mb) {
;             const int spc = __builtin_amdgcn_ds_bpermute(sp << 2, xp[mb]);
;             const int snc = __builtin_amdgcn_ds_bpermute(sn << 2, xp[mb]);
;             const int snn = (mb < 3) ? __builtin_amdgcn_ds_bpermute(sn << 2, xp[mb < 3 ? mb + 1 : 3]) : 0;
;             const int pv = (mb > 0) ? ((r == 0) ? spm : spc) : spc;
;             const int nv = (mb < 3) ? ((r == 31) ? snn : snc) : snc;
;             float prev0 = __int_as_float(pv << 16), prev1 = __int_as_float(pv & 0xffff0000);
;             float next0 = __int_as_float(nv << 16), next1 = __int_as_float(nv & 0xffff0000);
;             if (mb == 0 && r == 0) { prev0 = eo0; prev1 = eo1; }
;             if (mb == 3 && r == 31) { next0 = eo0; next1 = eo1; }
;             spm = spc;
;             prev0 *= pm[mb]; prev1 *= pm[mb];
;             next0 *= nm[mb]; next1 *= nm[mb];
;             u[nb][mb][0] = w0[0] * prev0 + w1[0] * acc[nb][mb][i0] + w2[0] * next0 + bz[0];
;             u[nb][mb][1] = w0[1] * prev1 + w1[1] * acc[nb][mb][i0 + 1] + w2[1] * next1 + bz[1];
;           }
	ds_write_b16_d16_hi v237, v222 offset:1728
	v_mov_b32_e32 v186, v18
	v_mov_b32_e32 v187, v66
	v_pk_fma_f32 v[130:131], v[50:51], v[240:241], v[242:243] op_sel_hi:[1,0,0]
	v_pk_fma_f32 v[132:133], v[52:53], v[240:241], v[242:243] op_sel_hi:[1,0,0]
	v_pk_fma_f32 v[134:135], v[54:55], v[240:241], v[242:243] op_sel_hi:[1,0,0]
	v_pk_fma_f32 v[136:137], v[56:57], v[240:241], v[242:243] op_sel_hi:[1,0,0]
	v_pk_fma_f32 v[138:139], v[58:59], v[240:241], v[242:243] op_sel_hi:[1,0,0]
	v_pk_fma_f32 v[140:141], v[60:61], v[240:241], v[242:243] op_sel_hi:[1,0,0]
	v_pk_fma_f32 v[142:143], v[62:63], v[240:241], v[242:243] op_sel_hi:[1,0,0]
	v_pk_fma_f32 v[144:145], v[64:65], v[240:241], v[242:243] op_sel_hi:[1,0,0]
	v_pk_fma_f32 v[146:147], v[82:83], v[244:245], v[246:247] op_sel_hi:[1,0,0]
	v_pk_fma_f32 v[148:149], v[84:85], v[244:245], v[246:247] op_sel_hi:[1,0,0]
	v_pk_fma_f32 v[150:151], v[86:87], v[244:245], v[246:247] op_sel_hi:[1,0,0]
	v_pk_fma_f32 v[152:153], v[88:89], v[244:245], v[246:247] op_sel_hi:[1,0,0]
	v_pk_fma_f32 v[154:155], v[90:91], v[244:245], v[246:247] op_sel_hi:[1,0,0]
	v_pk_fma_f32 v[156:157], v[92:93], v[244:245], v[246:247] op_sel_hi:[1,0,0]
	v_pk_fma_f32 v[158:159], v[94:95], v[244:245], v[246:247] op_sel_hi:[1,0,0]
	v_pk_fma_f32 v[160:161], v[96:97], v[244:245], v[246:247] op_sel_hi:[1,0,0]
	s_cmp_eq_u32 s36, 8
	s_cselect_b64 exec, s[38:39], -1
	v_fmac_f32_e32 v131, v241, v50
	v_fmac_f32_e32 v130, v243, v51
	v_fmac_f32_e32 v147, v245, v82
	v_fmac_f32_e32 v146, v247, v83
	s_cmp_eq_u32 s36, 9
	s_cselect_b64 exec, s[38:39], -1
	v_fmac_f32_e32 v133, v241, v52
	v_fmac_f32_e32 v132, v243, v53
	v_fmac_f32_e32 v149, v245, v84
	v_fmac_f32_e32 v148, v247, v85
	s_cmp_eq_u32 s36, 10
	s_cselect_b64 exec, s[38:39], -1
	v_fmac_f32_e32 v135, v241, v54
	v_fmac_f32_e32 v134, v243, v55
	v_fmac_f32_e32 v151, v245, v86
	v_fmac_f32_e32 v150, v247, v87
	s_cmp_eq_u32 s36, 11
	s_cselect_b64 exec, s[38:39], -1
	v_fmac_f32_e32 v137, v241, v56
	v_fmac_f32_e32 v136, v243, v57
	v_fmac_f32_e32 v153, v245, v88
	v_fmac_f32_e32 v152, v247, v89
	s_cmp_eq_u32 s36, 12
	s_cselect_b64 exec, s[38:39], -1
	v_fmac_f32_e32 v139, v241, v58
	v_fmac_f32_e32 v138, v243, v59
	v_fmac_f32_e32 v155, v245, v90
	v_fmac_f32_e32 v154, v247, v91
	s_cmp_eq_u32 s36, 13
	s_cselect_b64 exec, s[38:39], -1
	v_fmac_f32_e32 v141, v241, v60
	v_fmac_f32_e32 v140, v243, v61
	v_fmac_f32_e32 v157, v245, v92
	v_fmac_f32_e32 v156, v247, v93
	s_cmp_eq_u32 s36, 14
	s_cselect_b64 exec, s[38:39], -1
	v_fmac_f32_e32 v143, v241, v62
	v_fmac_f32_e32 v142, v243, v63
	v_fmac_f32_e32 v159, v245, v94
	v_fmac_f32_e32 v158, v247, v95
	s_cmp_eq_u32 s36, 15
	s_cselect_b64 exec, s[38:39], -1
	v_fmac_f32_e32 v145, v241, v64
	v_fmac_f32_e32 v144, v243, v65
	v_fmac_f32_e32 v161, v245, v96
	v_fmac_f32_e32 v160, v247, v97
	s_mov_b64 exec, -1
	s_nop 1
	v_permlane32_swap_b32_e32 v50, v53
	v_permlane32_swap_b32_e32 v54, v57
	v_permlane32_swap_b32_e32 v58, v61
	v_permlane32_swap_b32_e32 v62, v65
	v_permlane32_swap_b32_e32 v82, v85
	v_permlane32_swap_b32_e32 v86, v89
	v_permlane32_swap_b32_e32 v90, v93
	v_permlane32_swap_b32_e32 v94, v97
	v_permlane32_swap_b32_e32 v53, v54
	v_permlane32_swap_b32_e32 v57, v58
	v_permlane32_swap_b32_e32 v61, v62
	v_permlane32_swap_b32_e32 v85, v86
	v_permlane32_swap_b32_e32 v89, v90
	v_permlane32_swap_b32_e32 v93, v94
	v_permlane32_swap_b32_e32 v65, v186
	v_permlane32_swap_b32_e32 v97, v187
	s_mov_b32 exec_hi, 0
	v_mov_b32_e32 v50, v184
	v_mov_b32_e32 v82, v185
	s_mov_b64 exec, -1
	v_fmac_f32_e32 v131, v243, v52
	v_fmac_f32_e32 v132, v241, v51
	v_fmac_f32_e32 v135, v243, v56
	v_fmac_f32_e32 v136, v241, v55
	v_fmac_f32_e32 v139, v243, v60
	v_fmac_f32_e32 v140, v241, v59
	v_fmac_f32_e32 v143, v243, v64
	v_fmac_f32_e32 v144, v241, v63
	v_fmac_f32_e32 v147, v247, v84
	v_fmac_f32_e32 v148, v245, v83
	v_fmac_f32_e32 v151, v247, v88
	v_fmac_f32_e32 v152, v245, v87
	v_fmac_f32_e32 v155, v247, v92
	v_fmac_f32_e32 v156, v245, v91
	v_fmac_f32_e32 v159, v247, v96
	v_fmac_f32_e32 v160, v245, v95
	v_fmac_f32_e32 v130, v241, v50
	v_fmac_f32_e32 v133, v243, v53
	v_fmac_f32_e32 v134, v241, v54
	v_fmac_f32_e32 v137, v243, v57
	v_fmac_f32_e32 v138, v241, v58
	v_fmac_f32_e32 v141, v243, v61
	v_fmac_f32_e32 v142, v241, v62
	v_fmac_f32_e32 v145, v243, v65
	v_fmac_f32_e32 v146, v245, v82
	v_fmac_f32_e32 v149, v247, v85
	v_fmac_f32_e32 v150, v245, v86
	v_fmac_f32_e32 v153, v247, v89
	v_fmac_f32_e32 v154, v245, v90
	v_fmac_f32_e32 v157, v247, v93
	v_fmac_f32_e32 v158, v245, v94
	v_fmac_f32_e32 v161, v247, v97
	v_pk_mul_f32 v[188:189], v[146:147], v[146:147]
	v_pk_mul_f32 v[190:191], v[148:149], v[148:149]
	v_pk_mul_f32 v[192:193], v[150:151], v[150:151]
	v_pk_mul_f32 v[194:195], v[152:153], v[152:153]
	v_pk_mul_f32 v[196:197], v[154:155], v[154:155]
	v_pk_mul_f32 v[218:219], v[156:157], v[156:157]
	v_pk_mul_f32 v[220:221], v[158:159], v[158:159]
	v_pk_mul_f32 v[222:223], v[160:161], v[160:161]
	v_pk_fma_f32 v[188:189], v[188:189], v[178:179], v[180:181] op_sel_hi:[1,0,0]
	v_pk_fma_f32 v[190:191], v[190:191], v[178:179], v[180:181] op_sel_hi:[1,0,0]
	v_pk_fma_f32 v[192:193], v[192:193], v[178:179], v[180:181] op_sel_hi:[1,0,0]
	v_pk_fma_f32 v[194:195], v[194:195], v[178:179], v[180:181] op_sel_hi:[1,0,0]
	v_pk_fma_f32 v[196:197], v[196:197], v[178:179], v[180:181] op_sel_hi:[1,0,0]
	v_pk_fma_f32 v[218:219], v[218:219], v[178:179], v[180:181] op_sel_hi:[1,0,0]
	v_pk_fma_f32 v[220:221], v[220:221], v[178:179], v[180:181] op_sel_hi:[1,0,0]
	v_pk_fma_f32 v[222:223], v[222:223], v[178:179], v[180:181] op_sel_hi:[1,0,0]
	v_pk_mul_f32 v[188:189], v[146:147], v[188:189]
	v_pk_mul_f32 v[190:191], v[148:149], v[190:191]
; DI unsigned pack2(float a, float b) { f2 v = {a, b}; bf2 r = __builtin_convertvector(v, bf2); return __builtin_bit_cast(unsigned, r); }
;   DI void operator()(f32x16 (&acc)[2][4], int wm, int wn, int r, int h) {
;     ...
;         for (int nb = 0; nb < 2; ++nb) {
;           int xp[4];
; #pragma unroll
;           for (int mb = 0; mb < 4; ++mb) xp[mb] = (int)pack2(acc[nb][mb][i0], acc[nb][mb][i0 + 1]);
;           const float eo0 = ob[nb * 32 + crow(i0, h)], eo1 = ob[nb * 32 + crow(i0 + 1, h)];
;           float w0[2], w1[2], w2[2], bz[2];
;           {
;             const int ff = nt * 128 + wn * 32 + crow(i0, h) + nb * DFF;
;             const f32x2n a0 = *(const f32x2n*)(cw + ff), a1 = *(const f32x2n*)(cw + 2 * DFF + ff), a2 = *(const f32x2n*)(cw + 4 * DFF + ff),
;                          a3 = *(const f32x2n*)(cb + ff);
;             w0[0] = a0.x; w0[1] = a0.y; w1[0] = a1.x; w1[1] = a1.y; w2[0] = a2.x; w2[1] = a2.y; bz[0] = a3.x; bz[1] = a3.y;
;           }
;           int spm = 0;
; #pragma unroll
;           for (int mb = 0; mb < 4; ++mb) {
;             const int spc = __builtin_amdgcn_ds_bpermute(sp << 2, xp[mb]);
;             const int snc = __builtin_amdgcn_ds_bpermute(sn << 2, xp[mb]);
;             const int snn = (mb < 3) ? __builtin_amdgcn_ds_bpermute(sn << 2, xp[mb < 3 ? mb + 1 : 3]) : 0;
;             const int pv = (mb > 0) ? ((r == 0) ? spm : spc) : spc;
;             const int nv = (mb < 3) ? ((r == 31) ? snn : snc) : snc;
;             float prev0 = __int_as_float(pv << 16), prev1 = __int_as_float(pv & 0xffff0000);
;             float next0 = __int_as_float(nv << 16), next1 = __int_as_float(nv & 0xffff0000);
;             if (mb == 0 && r == 0) { prev0 = eo0; prev1 = eo1; }
;             if (mb == 3 && r == 31) { next0 = eo0; next1 = eo1; }
;             spm = spc;
;             prev0 *= pm[mb]; prev1 *= pm[mb];
;             next0 *= nm[mb]; next1 *= nm[mb];
;             u[nb][mb][0] = w0[0] * prev0 + w1[0] * acc[nb][mb][i0] + w2[0] * next0 + bz[0];
;             u[nb][mb][1] = w0[1] * prev1 + w1[1] * acc[nb][mb][i0 + 1] + w2[1] * next1 + bz[1];
;           }
;         }
; #pragma unroll
;         for (int mb = 0; mb < 4; ++mb)
;           *(unsigned*)(ost + (mb * 32 + r) * 40 + ig * 8 + h * 4 + qp * 2) =
;               pack2(gelu_tanh(u[1][mb][0]) * u[0][mb][0], gelu_tanh(u[1][mb][1]) * u[0][mb][1]);
	v_pk_mul_f32 v[192:193], v[150:151], v[192:193]
	v_pk_mul_f32 v[194:195], v[152:153], v[194:195]
	v_pk_mul_f32 v[196:197], v[154:155], v[196:197]
	v_pk_mul_f32 v[218:219], v[156:157], v[218:219]
	v_pk_mul_f32 v[220:221], v[158:159], v[220:221]
	v_pk_mul_f32 v[222:223], v[160:161], v[222:223]
	v_exp_f32_e32 v188, v188
	v_exp_f32_e32 v189, v189
	v_exp_f32_e32 v190, v190
	v_exp_f32_e32 v191, v191
	v_exp_f32_e32 v192, v192
	v_exp_f32_e32 v193, v193
	v_exp_f32_e32 v194, v194
	v_exp_f32_e32 v195, v195
	v_exp_f32_e32 v196, v196
	v_exp_f32_e32 v197, v197
	v_exp_f32_e32 v218, v218
	v_exp_f32_e32 v219, v219
	v_exp_f32_e32 v220, v220
	v_exp_f32_e32 v221, v221
	v_exp_f32_e32 v222, v222
	v_exp_f32_e32 v223, v223
	v_pk_add_f32 v[188:189], v[188:189], v[182:183] op_sel_hi:[1,0]
	v_pk_add_f32 v[190:191], v[190:191], v[182:183] op_sel_hi:[1,0]
	v_pk_add_f32 v[192:193], v[192:193], v[182:183] op_sel_hi:[1,0]
	v_pk_add_f32 v[194:195], v[194:195], v[182:183] op_sel_hi:[1,0]
	v_pk_add_f32 v[196:197], v[196:197], v[182:183] op_sel_hi:[1,0]
	v_pk_add_f32 v[218:219], v[218:219], v[182:183] op_sel_hi:[1,0]
	v_pk_add_f32 v[220:221], v[220:221], v[182:183] op_sel_hi:[1,0]
	v_pk_add_f32 v[222:223], v[222:223], v[182:183] op_sel_hi:[1,0]
	v_rcp_f32_e32 v188, v188
	v_rcp_f32_e32 v189, v189
	v_rcp_f32_e32 v190, v190
	v_rcp_f32_e32 v191, v191
	v_rcp_f32_e32 v192, v192
	v_rcp_f32_e32 v193, v193
	v_rcp_f32_e32 v194, v194
	v_rcp_f32_e32 v195, v195
	v_rcp_f32_e32 v196, v196
	v_rcp_f32_e32 v197, v197
	v_rcp_f32_e32 v218, v218
	v_rcp_f32_e32 v219, v219
	v_rcp_f32_e32 v220, v220
	v_rcp_f32_e32 v221, v221
	v_rcp_f32_e32 v222, v222
	v_rcp_f32_e32 v223, v223
	v_pk_mul_f32 v[188:189], v[146:147], v[188:189]
	v_pk_mul_f32 v[190:191], v[148:149], v[190:191]
	v_pk_mul_f32 v[192:193], v[150:151], v[192:193]
	v_pk_mul_f32 v[194:195], v[152:153], v[194:195]
	v_pk_mul_f32 v[196:197], v[154:155], v[196:197]
	v_pk_mul_f32 v[218:219], v[156:157], v[218:219]
	v_pk_mul_f32 v[220:221], v[158:159], v[220:221]
	v_pk_mul_f32 v[222:223], v[160:161], v[222:223]
	v_pk_mul_f32 v[188:189], v[188:189], v[130:131]
	v_pk_mul_f32 v[190:191], v[190:191], v[132:133]
	v_pk_mul_f32 v[192:193], v[192:193], v[134:135]
	v_pk_mul_f32 v[194:195], v[194:195], v[136:137]
	v_pk_mul_f32 v[196:197], v[196:197], v[138:139]
	v_pk_mul_f32 v[218:219], v[218:219], v[140:141]
	v_pk_mul_f32 v[220:221], v[220:221], v[142:143]
	v_pk_mul_f32 v[222:223], v[222:223], v[144:145]
	v_cvt_pk_bf16_f32 v188, v188, v189
	v_cvt_pk_bf16_f32 v190, v190, v191
	v_cvt_pk_bf16_f32 v192, v192, v193
	v_cvt_pk_bf16_f32 v194, v194, v195
	v_cvt_pk_bf16_f32 v196, v196, v197
	v_cvt_pk_bf16_f32 v218, v218, v219
	v_cvt_pk_bf16_f32 v220, v220, v221
	v_cvt_pk_bf16_f32 v222, v222, v223
	ds_write_b16 v224, v188 offset:2048
	ds_write_b16_d16_hi v237, v188 offset:2112
	ds_write_b16 v224, v190 offset:2176
	ds_write_b16_d16_hi v237, v190 offset:2240
	ds_write_b16 v224, v192 offset:2560
	ds_write_b16_d16_hi v237, v192 offset:2624
	ds_write_b16 v224, v194 offset:2688
	ds_write_b16_d16_hi v237, v194 offset:2752
	ds_write_b16 v224, v196 offset:3072
	ds_write_b16_d16_hi v237, v196 offset:3136
	ds_write_b16 v224, v218 offset:3200
	ds_write_b16_d16_hi v237, v218 offset:3264
	ds_write_b16 v224, v220 offset:3584
	ds_write_b16_d16_hi v237, v220 offset:3648
	ds_write_b16 v224, v222 offset:3712
	ds_write_b16_d16_hi v237, v222 offset:3776
	v_mov_b32_e32 v184, v2
	v_mov_b32_e32 v185, v34
	v_pk_fma_f32 v[130:131], v[18:19], v[240:241], v[242:243] op_sel_hi:[1,0,0]
	v_pk_fma_f32 v[132:133], v[20:21], v[240:241], v[242:243] op_sel_hi:[1,0,0]
	v_pk_fma_f32 v[134:135], v[22:23], v[240:241], v[242:243] op_sel_hi:[1,0,0]
	v_pk_fma_f32 v[136:137], v[24:25], v[240:241], v[242:243] op_sel_hi:[1,0,0]
	v_pk_fma_f32 v[138:139], v[26:27], v[240:241], v[242:243] op_sel_hi:[1,0,0]
	v_pk_fma_f32 v[140:141], v[28:29], v[240:241], v[242:243] op_sel_hi:[1,0,0]
	v_pk_fma_f32 v[142:143], v[30:31], v[240:241], v[242:243] op_sel_hi:[1,0,0]
	v_pk_fma_f32 v[144:145], v[32:33], v[240:241], v[242:243] op_sel_hi:[1,0,0]
	v_pk_fma_f32 v[146:147], v[66:67], v[244:245], v[246:247] op_sel_hi:[1,0,0]
	v_pk_fma_f32 v[148:149], v[68:69], v[244:245], v[246:247] op_sel_hi:[1,0,0]
	v_pk_fma_f32 v[150:151], v[70:71], v[244:245], v[246:247] op_sel_hi:[1,0,0]
	v_pk_fma_f32 v[152:153], v[72:73], v[244:245], v[246:247] op_sel_hi:[1,0,0]
	v_pk_fma_f32 v[154:155], v[74:75], v[244:245], v[246:247] op_sel_hi:[1,0,0]
	v_pk_fma_f32 v[156:157], v[76:77], v[244:245], v[246:247] op_sel_hi:[1,0,0]
	v_pk_fma_f32 v[158:159], v[78:79], v[244:245], v[246:247] op_sel_hi:[1,0,0]
	v_pk_fma_f32 v[160:161], v[80:81], v[244:245], v[246:247] op_sel_hi:[1,0,0]
	s_cmp_eq_u32 s36, 16
	s_cselect_b64 exec, s[38:39], -1
	v_fmac_f32_e32 v131, v241, v18
	v_fmac_f32_e32 v130, v243, v19
	v_fmac_f32_e32 v147, v245, v66
	v_fmac_f32_e32 v146, v247, v67
	s_cmp_eq_u32 s36, 17
	s_cselect_b64 exec, s[38:39], -1
	v_fmac_f32_e32 v133, v241, v20
	v_fmac_f32_e32 v132, v243, v21
	v_fmac_f32_e32 v149, v245, v68
	v_fmac_f32_e32 v148, v247, v69
	s_cmp_eq_u32 s36, 18
	s_cselect_b64 exec, s[38:39], -1
	v_fmac_f32_e32 v135, v241, v22
	v_fmac_f32_e32 v134, v243, v23
	v_fmac_f32_e32 v151, v245, v70
	v_fmac_f32_e32 v150, v247, v71
	s_cmp_eq_u32 s36, 19
	s_cselect_b64 exec, s[38:39], -1
	v_fmac_f32_e32 v137, v241, v24
	v_fmac_f32_e32 v136, v243, v25
	v_fmac_f32_e32 v153, v245, v72
	v_fmac_f32_e32 v152, v247, v73
	s_cmp_eq_u32 s36, 20
	s_cselect_b64 exec, s[38:39], -1
	v_fmac_f32_e32 v139, v241, v26
	v_fmac_f32_e32 v138, v243, v27
	v_fmac_f32_e32 v155, v245, v74
	v_fmac_f32_e32 v154, v247, v75
	s_cmp_eq_u32 s36, 21
	s_cselect_b64 exec, s[38:39], -1
	v_fmac_f32_e32 v141, v241, v28
; DI unsigned pack2(float a, float b) { f2 v = {a, b}; bf2 r = __builtin_convertvector(v, bf2); return __builtin_bit_cast(unsigned, r); }
;   DI void operator()(f32x16 (&acc)[2][4], int wm, int wn, int r, int h) {
;     ...
;         for (int nb = 0; nb < 2; ++nb) {
;           int xp[4];
; #pragma unroll
;           for (int mb = 0; mb < 4; ++mb) xp[mb] = (int)pack2(acc[nb][mb][i0], acc[nb][mb][i0 + 1]);
;           const float eo0 = ob[nb * 32 + crow(i0, h)], eo1 = ob[nb * 32 + crow(i0 + 1, h)];
;           float w0[2], w1[2], w2[2], bz[2];
;           {
;             const int ff = nt * 128 + wn * 32 + crow(i0, h) + nb * DFF;
;             const f32x2n a0 = *(const f32x2n*)(cw + ff), a1 = *(const f32x2n*)(cw + 2 * DFF + ff), a2 = *(const f32x2n*)(cw + 4 * DFF + ff),
;                          a3 = *(const f32x2n*)(cb + ff);
;             w0[0] = a0.x; w0[1] = a0.y; w1[0] = a1.x; w1[1] = a1.y; w2[0] = a2.x; w2[1] = a2.y; bz[0] = a3.x; bz[1] = a3.y;
;           }
;           int spm = 0;
; #pragma unroll
;           for (int mb = 0; mb < 4; ++mb) {
;             const int spc = __builtin_amdgcn_ds_bpermute(sp << 2, xp[mb]);
;             const int snc = __builtin_amdgcn_ds_bpermute(sn << 2, xp[mb]);
;             const int snn = (mb < 3) ? __builtin_amdgcn_ds_bpermute(sn << 2, xp[mb < 3 ? mb + 1 : 3]) : 0;
;             const int pv = (mb > 0) ? ((r == 0) ? spm : spc) : spc;
;             const int nv = (mb < 3) ? ((r == 31) ? snn : snc) : snc;
;             float prev0 = __int_as_float(pv << 16), prev1 = __int_as_float(pv & 0xffff0000);
;             float next0 = __int_as_float(nv << 16), next1 = __int_as_float(nv & 0xffff0000);
;             if (mb == 0 && r == 0) { prev0 = eo0; prev1 = eo1; }
;             if (mb == 3 && r == 31) { next0 = eo0; next1 = eo1; }
;             spm = spc;
;             prev0 *= pm[mb]; prev1 *= pm[mb];
;             next0 *= nm[mb]; next1 *= nm[mb];
;             u[nb][mb][0] = w0[0] * prev0 + w1[0] * acc[nb][mb][i0] + w2[0] * next0 + bz[0];
;             u[nb][mb][1] = w0[1] * prev1 + w1[1] * acc[nb][mb][i0 + 1] + w2[1] * next1 + bz[1];
;           }
;         }
; #pragma unroll
;         for (int mb = 0; mb < 4; ++mb)
;           *(unsigned*)(ost + (mb * 32 + r) * 40 + ig * 8 + h * 4 + qp * 2) =
;               pack2(gelu_tanh(u[1][mb][0]) * u[0][mb][0], gelu_tanh(u[1][mb][1]) * u[0][mb][1]);
	v_fmac_f32_e32 v140, v243, v29
	v_fmac_f32_e32 v157, v245, v76
	v_fmac_f32_e32 v156, v247, v77
	s_cmp_eq_u32 s36, 22
	s_cselect_b64 exec, s[38:39], -1
	v_fmac_f32_e32 v143, v241, v30
	v_fmac_f32_e32 v142, v243, v31
	v_fmac_f32_e32 v159, v245, v78
	v_fmac_f32_e32 v158, v247, v79
	s_cmp_eq_u32 s36, 23
	s_cselect_b64 exec, s[38:39], -1
	v_fmac_f32_e32 v145, v241, v32
	v_fmac_f32_e32 v144, v243, v33
	v_fmac_f32_e32 v161, v245, v80
	v_fmac_f32_e32 v160, v247, v81
	s_mov_b64 exec, -1
	s_nop 1
	v_permlane32_swap_b32_e32 v18, v21
	v_permlane32_swap_b32_e32 v22, v25
	v_permlane32_swap_b32_e32 v26, v29
	v_permlane32_swap_b32_e32 v30, v33
	v_permlane32_swap_b32_e32 v66, v69
	v_permlane32_swap_b32_e32 v70, v73
	v_permlane32_swap_b32_e32 v74, v77
	v_permlane32_swap_b32_e32 v78, v81
	v_permlane32_swap_b32_e32 v21, v22
	v_permlane32_swap_b32_e32 v25, v26
	v_permlane32_swap_b32_e32 v29, v30
	v_permlane32_swap_b32_e32 v69, v70
	v_permlane32_swap_b32_e32 v73, v74
	v_permlane32_swap_b32_e32 v77, v78
	v_permlane32_swap_b32_e32 v33, v184
	v_permlane32_swap_b32_e32 v81, v185
	s_mov_b32 exec_hi, 0
	v_mov_b32_e32 v18, v186
	v_mov_b32_e32 v66, v187
	s_mov_b64 exec, -1
	v_fmac_f32_e32 v131, v243, v20
	v_fmac_f32_e32 v132, v241, v19
	v_fmac_f32_e32 v135, v243, v24
	v_fmac_f32_e32 v136, v241, v23
	v_fmac_f32_e32 v139, v243, v28
	v_fmac_f32_e32 v140, v241, v27
	v_fmac_f32_e32 v143, v243, v32
	v_fmac_f32_e32 v144, v241, v31
	v_fmac_f32_e32 v147, v247, v68
	v_fmac_f32_e32 v148, v245, v67
	v_fmac_f32_e32 v151, v247, v72
	v_fmac_f32_e32 v152, v245, v71
	v_fmac_f32_e32 v155, v247, v76
	v_fmac_f32_e32 v156, v245, v75
	v_fmac_f32_e32 v159, v247, v80
	v_fmac_f32_e32 v160, v245, v79
	v_fmac_f32_e32 v130, v241, v18
	v_fmac_f32_e32 v133, v243, v21
	v_fmac_f32_e32 v134, v241, v22
	v_fmac_f32_e32 v137, v243, v25
	v_fmac_f32_e32 v138, v241, v26
	v_fmac_f32_e32 v141, v243, v29
	v_fmac_f32_e32 v142, v241, v30
	v_fmac_f32_e32 v145, v243, v33
	v_fmac_f32_e32 v146, v245, v66
	v_fmac_f32_e32 v149, v247, v69
	v_fmac_f32_e32 v150, v245, v70
	v_fmac_f32_e32 v153, v247, v73
	v_fmac_f32_e32 v154, v245, v74
	v_fmac_f32_e32 v157, v247, v77
	v_fmac_f32_e32 v158, v245, v78
	v_fmac_f32_e32 v161, v247, v81
	v_pk_mul_f32 v[188:189], v[146:147], v[146:147]
	v_pk_mul_f32 v[190:191], v[148:149], v[148:149]
	v_pk_mul_f32 v[192:193], v[150:151], v[150:151]
	v_pk_mul_f32 v[194:195], v[152:153], v[152:153]
	v_pk_mul_f32 v[196:197], v[154:155], v[154:155]
	v_pk_mul_f32 v[218:219], v[156:157], v[156:157]
	v_pk_mul_f32 v[220:221], v[158:159], v[158:159]
	v_pk_mul_f32 v[222:223], v[160:161], v[160:161]
	v_pk_fma_f32 v[188:189], v[188:189], v[178:179], v[180:181] op_sel_hi:[1,0,0]
	v_pk_fma_f32 v[190:191], v[190:191], v[178:179], v[180:181] op_sel_hi:[1,0,0]
	v_pk_fma_f32 v[192:193], v[192:193], v[178:179], v[180:181] op_sel_hi:[1,0,0]
	v_pk_fma_f32 v[194:195], v[194:195], v[178:179], v[180:181] op_sel_hi:[1,0,0]
	v_pk_fma_f32 v[196:197], v[196:197], v[178:179], v[180:181] op_sel_hi:[1,0,0]
	v_pk_fma_f32 v[218:219], v[218:219], v[178:179], v[180:181] op_sel_hi:[1,0,0]
	v_pk_fma_f32 v[220:221], v[220:221], v[178:179], v[180:181] op_sel_hi:[1,0,0]
	v_pk_fma_f32 v[222:223], v[222:223], v[178:179], v[180:181] op_sel_hi:[1,0,0]
	v_pk_mul_f32 v[188:189], v[146:147], v[188:189]
	v_pk_mul_f32 v[190:191], v[148:149], v[190:191]
	v_pk_mul_f32 v[192:193], v[150:151], v[192:193]
	v_pk_mul_f32 v[194:195], v[152:153], v[194:195]
	v_pk_mul_f32 v[196:197], v[154:155], v[196:197]
	v_pk_mul_f32 v[218:219], v[156:157], v[218:219]
	v_pk_mul_f32 v[220:221], v[158:159], v[220:221]
	v_pk_mul_f32 v[222:223], v[160:161], v[222:223]
	v_exp_f32_e32 v188, v188
	v_exp_f32_e32 v189, v189
	v_exp_f32_e32 v190, v190
	v_exp_f32_e32 v191, v191
	v_exp_f32_e32 v192, v192
	v_exp_f32_e32 v193, v193
	v_exp_f32_e32 v194, v194
	v_exp_f32_e32 v195, v195
	v_exp_f32_e32 v196, v196
	v_exp_f32_e32 v197, v197
	v_exp_f32_e32 v218, v218
	v_exp_f32_e32 v219, v219
	v_exp_f32_e32 v220, v220
	v_exp_f32_e32 v221, v221
	v_exp_f32_e32 v222, v222
	v_exp_f32_e32 v223, v223
	v_pk_add_f32 v[188:189], v[188:189], v[182:183] op_sel_hi:[1,0]
	v_pk_add_f32 v[190:191], v[190:191], v[182:183] op_sel_hi:[1,0]
	v_pk_add_f32 v[192:193], v[192:193], v[182:183] op_sel_hi:[1,0]
	v_pk_add_f32 v[194:195], v[194:195], v[182:183] op_sel_hi:[1,0]
	v_pk_add_f32 v[196:197], v[196:197], v[182:183] op_sel_hi:[1,0]
	v_pk_add_f32 v[218:219], v[218:219], v[182:183] op_sel_hi:[1,0]
	v_pk_add_f32 v[220:221], v[220:221], v[182:183] op_sel_hi:[1,0]
	v_pk_add_f32 v[222:223], v[222:223], v[182:183] op_sel_hi:[1,0]
	v_rcp_f32_e32 v188, v188
	v_rcp_f32_e32 v189, v189
	v_rcp_f32_e32 v190, v190
	v_rcp_f32_e32 v191, v191
	v_rcp_f32_e32 v192, v192
	v_rcp_f32_e32 v193, v193
	v_rcp_f32_e32 v194, v194
	v_rcp_f32_e32 v195, v195
	v_rcp_f32_e32 v196, v196
	v_rcp_f32_e32 v197, v197
	v_rcp_f32_e32 v218, v218
	v_rcp_f32_e32 v219, v219
	v_rcp_f32_e32 v220, v220
	v_rcp_f32_e32 v221, v221
	v_rcp_f32_e32 v222, v222
	v_rcp_f32_e32 v223, v223
	v_pk_mul_f32 v[188:189], v[146:147], v[188:189]
	v_pk_mul_f32 v[190:191], v[148:149], v[190:191]
	v_pk_mul_f32 v[192:193], v[150:151], v[192:193]
	v_pk_mul_f32 v[194:195], v[152:153], v[194:195]
	v_pk_mul_f32 v[196:197], v[154:155], v[196:197]
	v_pk_mul_f32 v[218:219], v[156:157], v[218:219]
	v_pk_mul_f32 v[220:221], v[158:159], v[220:221]
	v_pk_mul_f32 v[222:223], v[160:161], v[222:223]
	v_pk_mul_f32 v[188:189], v[188:189], v[130:131]
	v_pk_mul_f32 v[190:191], v[190:191], v[132:133]
	v_pk_mul_f32 v[192:193], v[192:193], v[134:135]
	v_pk_mul_f32 v[194:195], v[194:195], v[136:137]
	v_pk_mul_f32 v[196:197], v[196:197], v[138:139]
	v_pk_mul_f32 v[218:219], v[218:219], v[140:141]
; DI unsigned pack2(float a, float b) { f2 v = {a, b}; bf2 r = __builtin_convertvector(v, bf2); return __builtin_bit_cast(unsigned, r); }
;   DI void operator()(f32x16 (&acc)[2][4], int wm, int wn, int r, int h) {
;     ...
;         for (int nb = 0; nb < 2; ++nb) {
;           int xp[4];
; #pragma unroll
;           for (int mb = 0; mb < 4; ++mb) xp[mb] = (int)pack2(acc[nb][mb][i0], acc[nb][mb][i0 + 1]);
;           const float eo0 = ob[nb * 32 + crow(i0, h)], eo1 = ob[nb * 32 + crow(i0 + 1, h)];
;           float w0[2], w1[2], w2[2], bz[2];
;           {
;             const int ff = nt * 128 + wn * 32 + crow(i0, h) + nb * DFF;
;             const f32x2n a0 = *(const f32x2n*)(cw + ff), a1 = *(const f32x2n*)(cw + 2 * DFF + ff), a2 = *(const f32x2n*)(cw + 4 * DFF + ff),
;                          a3 = *(const f32x2n*)(cb + ff);
;             w0[0] = a0.x; w0[1] = a0.y; w1[0] = a1.x; w1[1] = a1.y; w2[0] = a2.x; w2[1] = a2.y; bz[0] = a3.x; bz[1] = a3.y;
;           }
;           int spm = 0;
; #pragma unroll
;           for (int mb = 0; mb < 4; ++mb) {
;             const int spc = __builtin_amdgcn_ds_bpermute(sp << 2, xp[mb]);
;             const int snc = __builtin_amdgcn_ds_bpermute(sn << 2, xp[mb]);
;             const int snn = (mb < 3) ? __builtin_amdgcn_ds_bpermute(sn << 2, xp[mb < 3 ? mb + 1 : 3]) : 0;
;             const int pv = (mb > 0) ? ((r == 0) ? spm : spc) : spc;
;             const int nv = (mb < 3) ? ((r == 31) ? snn : snc) : snc;
;             float prev0 = __int_as_float(pv << 16), prev1 = __int_as_float(pv & 0xffff0000);
;             float next0 = __int_as_float(nv << 16), next1 = __int_as_float(nv & 0xffff0000);
;             if (mb == 0 && r == 0) { prev0 = eo0; prev1 = eo1; }
;             if (mb == 3 && r == 31) { next0 = eo0; next1 = eo1; }
;             spm = spc;
;             prev0 *= pm[mb]; prev1 *= pm[mb];
;             next0 *= nm[mb]; next1 *= nm[mb];
;             u[nb][mb][0] = w0[0] * prev0 + w1[0] * acc[nb][mb][i0] + w2[0] * next0 + bz[0];
;             u[nb][mb][1] = w0[1] * prev1 + w1[1] * acc[nb][mb][i0 + 1] + w2[1] * next1 + bz[1];
;           }
;         }
; #pragma unroll
;         for (int mb = 0; mb < 4; ++mb)
;           *(unsigned*)(ost + (mb * 32 + r) * 40 + ig * 8 + h * 4 + qp * 2) =
;               pack2(gelu_tanh(u[1][mb][0]) * u[0][mb][0], gelu_tanh(u[1][mb][1]) * u[0][mb][1]);
	v_pk_mul_f32 v[220:221], v[220:221], v[142:143]
	v_pk_mul_f32 v[222:223], v[222:223], v[144:145]
	v_cvt_pk_bf16_f32 v188, v188, v189
	v_cvt_pk_bf16_f32 v190, v190, v191
	v_cvt_pk_bf16_f32 v192, v192, v193
	v_cvt_pk_bf16_f32 v194, v194, v195
	v_cvt_pk_bf16_f32 v196, v196, v197
	v_cvt_pk_bf16_f32 v218, v218, v219
	v_cvt_pk_bf16_f32 v220, v220, v221
	v_cvt_pk_bf16_f32 v222, v222, v223
	ds_write_b16 v224, v188 offset:4096
	ds_write_b16_d16_hi v237, v188 offset:4160
	ds_write_b16 v224, v190 offset:4224
	ds_write_b16_d16_hi v237, v190 offset:4288
	ds_write_b16 v224, v192 offset:4608
	ds_write_b16_d16_hi v237, v192 offset:4672
	ds_write_b16 v224, v194 offset:4736
	ds_write_b16_d16_hi v237, v194 offset:4800
	ds_write_b16 v224, v196 offset:5120
	ds_write_b16_d16_hi v237, v196 offset:5184
	ds_write_b16 v224, v218 offset:5248
	ds_write_b16_d16_hi v237, v218 offset:5312
	ds_write_b16 v224, v220 offset:5632
	ds_write_b16_d16_hi v237, v220 offset:5696
	ds_write_b16 v224, v222 offset:5760
	ds_write_b16_d16_hi v237, v222 offset:5824
	v_pk_fma_f32 v[130:131], v[2:3], v[240:241], v[242:243] op_sel_hi:[1,0,0]
	v_pk_fma_f32 v[132:133], v[4:5], v[240:241], v[242:243] op_sel_hi:[1,0,0]
	v_pk_fma_f32 v[134:135], v[6:7], v[240:241], v[242:243] op_sel_hi:[1,0,0]
	v_pk_fma_f32 v[136:137], v[8:9], v[240:241], v[242:243] op_sel_hi:[1,0,0]
	v_pk_fma_f32 v[138:139], v[10:11], v[240:241], v[242:243] op_sel_hi:[1,0,0]
	v_pk_fma_f32 v[140:141], v[12:13], v[240:241], v[242:243] op_sel_hi:[1,0,0]
	v_pk_fma_f32 v[142:143], v[14:15], v[240:241], v[242:243] op_sel_hi:[1,0,0]
	v_pk_fma_f32 v[144:145], v[16:17], v[240:241], v[242:243] op_sel_hi:[1,0,0]
	v_pk_fma_f32 v[146:147], v[34:35], v[244:245], v[246:247] op_sel_hi:[1,0,0]
	v_pk_fma_f32 v[148:149], v[36:37], v[244:245], v[246:247] op_sel_hi:[1,0,0]
	v_pk_fma_f32 v[150:151], v[38:39], v[244:245], v[246:247] op_sel_hi:[1,0,0]
	v_pk_fma_f32 v[152:153], v[40:41], v[244:245], v[246:247] op_sel_hi:[1,0,0]
	v_pk_fma_f32 v[154:155], v[42:43], v[244:245], v[246:247] op_sel_hi:[1,0,0]
	v_pk_fma_f32 v[156:157], v[44:45], v[244:245], v[246:247] op_sel_hi:[1,0,0]
	v_pk_fma_f32 v[158:159], v[46:47], v[244:245], v[246:247] op_sel_hi:[1,0,0]
	v_pk_fma_f32 v[160:161], v[48:49], v[244:245], v[246:247] op_sel_hi:[1,0,0]
	s_cmp_eq_u32 s36, 24
	s_cselect_b64 exec, s[38:39], -1
	v_fmac_f32_e32 v131, v241, v2
	v_fmac_f32_e32 v130, v243, v3
	v_fmac_f32_e32 v147, v245, v34
	v_fmac_f32_e32 v146, v247, v35
	s_cmp_eq_u32 s36, 25
	s_cselect_b64 exec, s[38:39], -1
	v_fmac_f32_e32 v133, v241, v4
	v_fmac_f32_e32 v132, v243, v5
	v_fmac_f32_e32 v149, v245, v36
	v_fmac_f32_e32 v148, v247, v37
	s_cmp_eq_u32 s36, 26
	s_cselect_b64 exec, s[38:39], -1
	v_fmac_f32_e32 v135, v241, v6
	v_fmac_f32_e32 v134, v243, v7
	v_fmac_f32_e32 v151, v245, v38
	v_fmac_f32_e32 v150, v247, v39
	s_cmp_eq_u32 s36, 27
	s_cselect_b64 exec, s[38:39], -1
	v_fmac_f32_e32 v137, v241, v8
	v_fmac_f32_e32 v136, v243, v9
	v_fmac_f32_e32 v153, v245, v40
	v_fmac_f32_e32 v152, v247, v41
	s_cmp_eq_u32 s36, 28
	s_cselect_b64 exec, s[38:39], -1
	v_fmac_f32_e32 v139, v241, v10
	v_fmac_f32_e32 v138, v243, v11
	v_fmac_f32_e32 v155, v245, v42
	v_fmac_f32_e32 v154, v247, v43
	s_cmp_eq_u32 s36, 29
	s_cselect_b64 exec, s[38:39], -1
	v_fmac_f32_e32 v141, v241, v12
	v_fmac_f32_e32 v140, v243, v13
	v_fmac_f32_e32 v157, v245, v44
	v_fmac_f32_e32 v156, v247, v45
	s_cmp_eq_u32 s36, 30
	s_cselect_b64 exec, s[38:39], -1
	v_fmac_f32_e32 v143, v241, v14
	v_fmac_f32_e32 v142, v243, v15
	v_fmac_f32_e32 v159, v245, v46
	v_fmac_f32_e32 v158, v247, v47
	s_cmp_eq_u32 s36, 31
	s_cselect_b64 exec, s[38:39], -1
	v_fmac_f32_e32 v145, v241, v16
	v_fmac_f32_e32 v144, v243, v17
	v_fmac_f32_e32 v161, v245, v48
	v_fmac_f32_e32 v160, v247, v49
	s_mov_b64 exec, -1
	s_nop 1
	v_permlane32_swap_b32_e32 v2, v5
	v_permlane32_swap_b32_e32 v6, v9
	v_permlane32_swap_b32_e32 v10, v13
	v_permlane32_swap_b32_e32 v14, v17
	v_permlane32_swap_b32_e32 v34, v37
	v_permlane32_swap_b32_e32 v38, v41
	v_permlane32_swap_b32_e32 v42, v45
	v_permlane32_swap_b32_e32 v46, v49
	v_permlane32_swap_b32_e32 v5, v6
	v_permlane32_swap_b32_e32 v9, v10
	v_permlane32_swap_b32_e32 v13, v14
	v_permlane32_swap_b32_e32 v37, v38
	v_permlane32_swap_b32_e32 v41, v42
	v_permlane32_swap_b32_e32 v45, v46
	s_mov_b32 exec_lo, 0
	ds_read_b32 v17, v226 offset:0
	ds_read_b32 v49, v226 offset:128
	s_mov_b64 exec, -1
	s_mov_b32 exec_hi, 0
	v_mov_b32_e32 v2, v184
	v_mov_b32_e32 v34, v185
	s_mov_b64 exec, -1
	v_fmac_f32_e32 v131, v243, v4
	v_fmac_f32_e32 v132, v241, v3
	v_fmac_f32_e32 v135, v243, v8
	v_fmac_f32_e32 v136, v241, v7
	v_fmac_f32_e32 v139, v243, v12
	v_fmac_f32_e32 v140, v241, v11
	v_fmac_f32_e32 v143, v243, v16
	v_fmac_f32_e32 v144, v241, v15
	v_fmac_f32_e32 v147, v247, v36
	v_fmac_f32_e32 v148, v245, v35
	v_fmac_f32_e32 v151, v247, v40
	v_fmac_f32_e32 v152, v245, v39
	v_fmac_f32_e32 v155, v247, v44
	v_fmac_f32_e32 v156, v245, v43
	v_fmac_f32_e32 v159, v247, v48
	v_fmac_f32_e32 v160, v245, v47
	s_waitcnt lgkmcnt(0)
; DI unsigned pack2(float a, float b) { f2 v = {a, b}; bf2 r = __builtin_convertvector(v, bf2); return __builtin_bit_cast(unsigned, r); }
;   DI void operator()(f32x16 (&acc)[2][4], int wm, int wn, int r, int h) {
;     ...
;             prev0 *= pm[mb]; prev1 *= pm[mb];
;             next0 *= nm[mb]; next1 *= nm[mb];
;             u[nb][mb][0] = w0[0] * prev0 + w1[0] * acc[nb][mb][i0] + w2[0] * next0 + bz[0];
;             u[nb][mb][1] = w0[1] * prev1 + w1[1] * acc[nb][mb][i0 + 1] + w2[1] * next1 + bz[1];
;           }
;         }
; #pragma unroll
;         for (int mb = 0; mb < 4; ++mb)
;           *(unsigned*)(ost + (mb * 32 + r) * 40 + ig * 8 + h * 4 + qp * 2) =
;               pack2(gelu_tanh(u[1][mb][0]) * u[0][mb][0], gelu_tanh(u[1][mb][1]) * u[0][mb][1]);
	v_fmac_f32_e32 v130, v241, v2
	v_fmac_f32_e32 v133, v243, v5
	v_fmac_f32_e32 v134, v241, v6
	v_fmac_f32_e32 v137, v243, v9
	v_fmac_f32_e32 v138, v241, v10
	v_fmac_f32_e32 v141, v243, v13
	v_fmac_f32_e32 v142, v241, v14
	v_fmac_f32_e32 v145, v243, v17
	v_fmac_f32_e32 v146, v245, v34
	v_fmac_f32_e32 v149, v247, v37
	v_fmac_f32_e32 v150, v245, v38
	v_fmac_f32_e32 v153, v247, v41
	v_fmac_f32_e32 v154, v245, v42
	v_fmac_f32_e32 v157, v247, v45
	v_fmac_f32_e32 v158, v245, v46
	v_fmac_f32_e32 v161, v247, v49
	v_pk_mul_f32 v[188:189], v[146:147], v[146:147]
	v_pk_mul_f32 v[190:191], v[148:149], v[148:149]
	v_pk_mul_f32 v[192:193], v[150:151], v[150:151]
	v_pk_mul_f32 v[194:195], v[152:153], v[152:153]
	v_pk_mul_f32 v[196:197], v[154:155], v[154:155]
	v_pk_mul_f32 v[218:219], v[156:157], v[156:157]
	v_pk_mul_f32 v[220:221], v[158:159], v[158:159]
	v_pk_mul_f32 v[222:223], v[160:161], v[160:161]
	v_pk_fma_f32 v[188:189], v[188:189], v[178:179], v[180:181] op_sel_hi:[1,0,0]
	v_pk_fma_f32 v[190:191], v[190:191], v[178:179], v[180:181] op_sel_hi:[1,0,0]
	v_pk_fma_f32 v[192:193], v[192:193], v[178:179], v[180:181] op_sel_hi:[1,0,0]
	v_pk_fma_f32 v[194:195], v[194:195], v[178:179], v[180:181] op_sel_hi:[1,0,0]
	v_pk_fma_f32 v[196:197], v[196:197], v[178:179], v[180:181] op_sel_hi:[1,0,0]
	v_pk_fma_f32 v[218:219], v[218:219], v[178:179], v[180:181] op_sel_hi:[1,0,0]
	v_pk_fma_f32 v[220:221], v[220:221], v[178:179], v[180:181] op_sel_hi:[1,0,0]
	v_pk_fma_f32 v[222:223], v[222:223], v[178:179], v[180:181] op_sel_hi:[1,0,0]
	v_pk_mul_f32 v[188:189], v[146:147], v[188:189]
	v_pk_mul_f32 v[190:191], v[148:149], v[190:191]
	v_pk_mul_f32 v[192:193], v[150:151], v[192:193]
	v_pk_mul_f32 v[194:195], v[152:153], v[194:195]
	v_pk_mul_f32 v[196:197], v[154:155], v[196:197]
	v_pk_mul_f32 v[218:219], v[156:157], v[218:219]
	v_pk_mul_f32 v[220:221], v[158:159], v[220:221]
	v_pk_mul_f32 v[222:223], v[160:161], v[222:223]
	v_exp_f32_e32 v188, v188
	v_exp_f32_e32 v189, v189
	v_exp_f32_e32 v190, v190
	v_exp_f32_e32 v191, v191
	v_exp_f32_e32 v192, v192
	v_exp_f32_e32 v193, v193
	v_exp_f32_e32 v194, v194
	v_exp_f32_e32 v195, v195
	v_exp_f32_e32 v196, v196
	v_exp_f32_e32 v197, v197
	v_exp_f32_e32 v218, v218
	v_exp_f32_e32 v219, v219
	v_exp_f32_e32 v220, v220
	v_exp_f32_e32 v221, v221
	v_exp_f32_e32 v222, v222
	v_exp_f32_e32 v223, v223
	v_pk_add_f32 v[188:189], v[188:189], v[182:183] op_sel_hi:[1,0]
	v_pk_add_f32 v[190:191], v[190:191], v[182:183] op_sel_hi:[1,0]
	v_pk_add_f32 v[192:193], v[192:193], v[182:183] op_sel_hi:[1,0]
	v_pk_add_f32 v[194:195], v[194:195], v[182:183] op_sel_hi:[1,0]
	v_pk_add_f32 v[196:197], v[196:197], v[182:183] op_sel_hi:[1,0]
	v_pk_add_f32 v[218:219], v[218:219], v[182:183] op_sel_hi:[1,0]
	v_pk_add_f32 v[220:221], v[220:221], v[182:183] op_sel_hi:[1,0]
	v_pk_add_f32 v[222:223], v[222:223], v[182:183] op_sel_hi:[1,0]
	v_rcp_f32_e32 v188, v188
	v_rcp_f32_e32 v189, v189
	v_rcp_f32_e32 v190, v190
	v_rcp_f32_e32 v191, v191
	v_rcp_f32_e32 v192, v192
	v_rcp_f32_e32 v193, v193
	v_rcp_f32_e32 v194, v194
	v_rcp_f32_e32 v195, v195
	v_rcp_f32_e32 v196, v196
	v_rcp_f32_e32 v197, v197
	v_rcp_f32_e32 v218, v218
	v_rcp_f32_e32 v219, v219
	v_rcp_f32_e32 v220, v220
	v_rcp_f32_e32 v221, v221
	v_rcp_f32_e32 v222, v222
	v_rcp_f32_e32 v223, v223
	v_pk_mul_f32 v[188:189], v[146:147], v[188:189]
	v_pk_mul_f32 v[190:191], v[148:149], v[190:191]
	v_pk_mul_f32 v[192:193], v[150:151], v[192:193]
	v_pk_mul_f32 v[194:195], v[152:153], v[194:195]
	v_pk_mul_f32 v[196:197], v[154:155], v[196:197]
	v_pk_mul_f32 v[218:219], v[156:157], v[218:219]
	v_pk_mul_f32 v[220:221], v[158:159], v[220:221]
	v_pk_mul_f32 v[222:223], v[160:161], v[222:223]
	v_pk_mul_f32 v[188:189], v[188:189], v[130:131]
	v_pk_mul_f32 v[190:191], v[190:191], v[132:133]
	v_pk_mul_f32 v[192:193], v[192:193], v[134:135]
	v_pk_mul_f32 v[194:195], v[194:195], v[136:137]
	v_pk_mul_f32 v[196:197], v[196:197], v[138:139]
	v_pk_mul_f32 v[218:219], v[218:219], v[140:141]
	v_pk_mul_f32 v[220:221], v[220:221], v[142:143]
	v_pk_mul_f32 v[222:223], v[222:223], v[144:145]
	v_cvt_pk_bf16_f32 v188, v188, v189
	v_cvt_pk_bf16_f32 v190, v190, v191
	v_cvt_pk_bf16_f32 v192, v192, v193
	v_cvt_pk_bf16_f32 v194, v194, v195
	v_cvt_pk_bf16_f32 v196, v196, v197
	v_cvt_pk_bf16_f32 v218, v218, v219
	v_cvt_pk_bf16_f32 v220, v220, v221
	v_cvt_pk_bf16_f32 v222, v222, v223
	ds_write_b16 v224, v188 offset:6144
	ds_write_b16_d16_hi v237, v188 offset:6208
	ds_write_b16 v224, v190 offset:6272
	ds_write_b16_d16_hi v237, v190 offset:6336
	ds_write_b16 v224, v192 offset:6656
	ds_write_b16_d16_hi v237, v192 offset:6720
	ds_write_b16 v224, v194 offset:6784
	ds_write_b16_d16_hi v237, v194 offset:6848
	ds_write_b16 v224, v196 offset:7168
	ds_write_b16_d16_hi v237, v196 offset:7232
	ds_write_b16 v224, v218 offset:7296
	ds_write_b16_d16_hi v237, v218 offset:7360
	ds_write_b16 v224, v220 offset:7680
	ds_write_b16_d16_hi v237, v220 offset:7744
	ds_write_b16 v224, v222 offset:7808
	ds_write_b16_d16_hi v237, v222 offset:7872
;   DI void operator()(f32x16 (&acc)[2][4], int wm, int wn, int r, int h) {
;     ...
;     asm volatile("s_waitcnt lgkmcnt(0)" ::: "memory");
;     const int lane = h * 32 + r;
; #pragma unroll
;     for (int j = 0; j < 8; ++j) {
;       const int tk = (lane >> 2) + 16 * j, ch = lane & 3;
;       const int tr = wm * 128 + tk;
;       const int R = row0 + tr;
;       const u32x4 v = *(const u32x4*)(ost + tk * 40 + ch * 8);
;       if ((tr >= 1) && (tr <= 254) && (R >= 0) && (R < Mrows))
;         *(u32x4*)(act + (size_t)R * DFF + nt * 128 + wn * 32 + ch * 8) = v;
;     }
.Lupe_done:
	s_cmp_eq_u32 s101, 1
	s_cselect_b64 s[38:39], 0, -1
	v_bfe_u32 v188, v165, 2, 4
	v_bfe_u32 v189, v188, 2, 1
	v_xor_b32_e32 v189, v189, v188
	v_and_b32_e32 v190, 3, v165
	v_lshlrev_b32_e32 v189, 6, v189
	v_lshl_add_u32 v189, v190, 4, v189
	v_add_u32_e32 v189, s0, v189
	s_waitcnt lgkmcnt(0)
	ds_read_b128 v[130:133], v189 offset:0
	ds_read_b128 v[134:137], v189 offset:1024
	ds_read_b128 v[138:141], v189 offset:2048
	ds_read_b128 v[142:145], v189 offset:3072
	ds_read_b128 v[146:149], v189 offset:4096
	ds_read_b128 v[150:153], v189 offset:5120
	ds_read_b128 v[154:157], v189 offset:6144
	ds_read_b128 v[158:161], v189 offset:7168
	s_lshl_b32 s2, s15, 7
	v_add_u32_e32 v191, s2, v188
	v_add_u32_e32 v192, s14, v191
	s_lshl_b32 s3, s48, 7
	s_lshl_b32 s2, s16, 5
	s_add_i32 s3, s3, s2
	v_lshl_add_u32 v193, v190, 3, s3
	v_lshlrev_b32_e32 v193, 1, v193
	s_movk_i32 s2, 0x1600
	v_mad_u32_u24 v193, v192, s2, v193
	v_cmp_eq_u32_e32 vcc, 0, v191
	s_nop 1
	v_cndmask_b32_e64 v194, v192, -1, vcc
	v_cmp_gt_u32_e32 vcc, s26, v194
	s_and_saveexec_b64 s[2:3], vcc
	s_waitcnt lgkmcnt(7)
	global_store_dwordx4 v193, v[130:133], s[20:21]
	s_mov_b64 exec, -1
	v_add_u32_e32 v194, 16, v192
	v_cmp_gt_u32_e32 vcc, s26, v194
	s_and_saveexec_b64 s[2:3], vcc
	s_waitcnt lgkmcnt(6)
	v_add_u32_e32 v195, 0x16000, v193
	global_store_dwordx4 v195, v[134:137], s[20:21]
	s_mov_b64 exec, -1
	v_add_u32_e32 v194, 32, v192
	v_cmp_gt_u32_e32 vcc, s26, v194
	s_and_saveexec_b64 s[2:3], vcc
	s_waitcnt lgkmcnt(5)
	v_add_u32_e32 v195, 0x2c000, v193
	global_store_dwordx4 v195, v[138:141], s[20:21]
	s_mov_b64 exec, -1
	v_add_u32_e32 v194, 48, v192
	v_cmp_gt_u32_e32 vcc, s26, v194
	s_and_saveexec_b64 s[2:3], vcc
	s_waitcnt lgkmcnt(4)
	v_add_u32_e32 v195, 0x42000, v193
	global_store_dwordx4 v195, v[142:145], s[20:21]
	s_mov_b64 exec, -1
	v_add_u32_e32 v194, 64, v192
	v_cmp_gt_u32_e32 vcc, s26, v194
	s_and_saveexec_b64 s[2:3], vcc
	s_waitcnt lgkmcnt(3)
	v_add_u32_e32 v195, 0x58000, v193
	global_store_dwordx4 v195, v[146:149], s[20:21]
	s_mov_b64 exec, -1
	v_add_u32_e32 v194, 80, v192
	v_cmp_gt_u32_e32 vcc, s26, v194
	s_and_saveexec_b64 s[2:3], vcc
	s_waitcnt lgkmcnt(2)
	v_add_u32_e32 v195, 0x6e000, v193
	global_store_dwordx4 v195, v[150:153], s[20:21]
	s_mov_b64 exec, -1
	v_add_u32_e32 v194, 96, v192
	v_cmp_gt_u32_e32 vcc, s26, v194
	s_and_saveexec_b64 s[2:3], vcc
	s_waitcnt lgkmcnt(1)
	v_add_u32_e32 v195, 0x84000, v193
	global_store_dwordx4 v195, v[154:157], s[20:21]
	s_mov_b64 exec, -1
	v_add_u32_e32 v194, 112, v192
	v_add_u32_e32 v195, 0x70, v191
	v_cmp_eq_u32_e32 vcc, 0xff, v195
	s_nop 1
	v_cndmask_b32_e64 v194, v194, -1, vcc
	v_cmp_gt_u32_e32 vcc, s26, v194
	s_and_saveexec_b64 s[2:3], vcc
	s_waitcnt lgkmcnt(0)
	v_add_u32_e32 v195, 0x9a000, v193
	global_store_dwordx4 v195, v[158:161], s[20:21]
	s_mov_b64 exec, -1
	s_branch .LBB0_771
